# U table: 16-byte units of each 192-byte slice piece interleaved so every gather_u load instruction reads 64 contiguous bytes per pick (one L1 line per pick per instruction instead of two)
# speedup vs baseline: 1.0165x; 1.0108x over previous
.LBB0_35:
	s_or_b64 exec, exec, s[0:1]
	s_and_b32 s0, 0xffff, s20
	s_cmp_lg_u32 s0, 0
	s_cselect_b64 s[6:7], -1, 0
	s_cmp_lg_u64 s[6:7], 0
	s_addc_u32 s92, s96, 0
	s_lshr_b32 s3, s92, 1
	v_cvt_f32_u32_e32 v1, s3
	s_sub_i32 s0, 0, s3
	v_mov_b32_e32 v2, v205
	v_mov_b32_e32 v3, v205
	v_rcp_iflag_f32_e32 v1, v1
	v_mbcnt_lo_u32_b32 v207, -1, 0
	v_mul_f32_e32 v1, 0x4f7ffffe, v1
	v_cvt_u32_f32_e32 v1, v1
	v_ashrrev_i32_e32 v3, 6, v3
	v_readfirstlane_b32 s1, v1
	s_mul_i32 s0, s0, s1
	s_mul_hi_u32 s0, s1, s0
	s_add_i32 s1, s1, s0
	s_mul_hi_u32 s0, s2, s1
	s_mul_i32 s0, s0, s3
	s_sub_i32 s0, s2, s0
	s_sub_i32 s1, s0, s3
	s_cmp_ge_u32 s0, s3
	s_cselect_b32 s0, s1, s0
	s_sub_i32 s1, s0, s3
	s_cmp_ge_u32 s0, s3
	s_cselect_b32 s0, s1, s0
	s_add_u32 s52, s26, 0x1400000
	s_addc_u32 s53, s27, 0
	s_and_b32 s19, s92, -2
	s_lshl_b32 s0, s0, 3
	s_cmp_lt_u32 s2, s3
	s_cselect_b32 s1, 0, 4
	s_or_b32 s21, s0, s1
	v_add_u32_e32 v1, s21, v3
	s_movk_i32 s0, 0x2000
	v_cmp_gt_i32_e32 vcc, s0, v1
	s_and_saveexec_b64 s[14:15], vcc
	s_cbranch_execz .LBB0_40
	v_and_b32_e32 v5, 31, v2
	v_bfe_u32 v4, v2, 5, 1
	v_lshlrev_b32_e32 v2, 4, v5
	v_mov_b32_e32 v3, 0
	v_mbcnt_hi_u32_b32 v6, -1, v207
	v_lshl_add_u64 v[26:27], s[8:9], 0, v[2:3]
	v_and_b32_e32 v2, 64, v6
	v_add_u32_e32 v7, 64, v2
	v_and_b32_e32 v2, 1, v5
	v_cmp_eq_u32_e64 s[100:101], 1, v2
	v_bfe_u32 v2, v5, 1, 2
	v_lshlrev_b32_e32 v2, 4, v2
	v_lshrrev_b32_e32 v3, 3, v5
	v_mul_u32_u24_e32 v3, 0x300000, v3
	v_add_u32_e32 v2, v2, v3
	v_mov_b32_e32 v3, 0
	v_lshl_add_u64 v[2:3], s[26:27], 0, v[2:3]
	s_mov_b64 s[0:1], 0x1800000
	v_lshl_add_u64 v[28:29], v[2:3], 0, s[0:1]
	v_xor_b32_e32 v2, 16, v6
	v_cmp_lt_i32_e32 vcc, v2, v7
	v_cmp_eq_u32_e64 s[0:1], 0, v5
	s_lshl_b32 s28, s19, 2
	v_cndmask_b32_e32 v2, v6, v2, vcc
	v_lshlrev_b32_e32 v38, 2, v2
	v_xor_b32_e32 v2, 8, v6
	v_cmp_lt_i32_e32 vcc, v2, v7
	v_lshl_or_b32 v30, v1, 1, v4
	s_lshl_b32 s29, s3, 4
	v_cndmask_b32_e32 v2, v6, v2, vcc
	v_lshlrev_b32_e32 v39, 2, v2
	v_xor_b32_e32 v2, 4, v6
	v_cmp_lt_i32_e32 vcc, v2, v7
	s_mov_b64 s[16:17], 0
	s_movk_i32 s30, 0xc0
	v_cndmask_b32_e32 v2, v6, v2, vcc
	v_lshlrev_b32_e32 v40, 2, v2
	v_xor_b32_e32 v2, 2, v6
	v_cmp_lt_i32_e32 vcc, v2, v7
	s_mov_b32 s31, 0x40f00000
	s_mov_b32 s18, 0x41000000
	v_cndmask_b32_e32 v2, v6, v2, vcc
	v_lshlrev_b32_e32 v41, 2, v2
	v_xor_b32_e32 v2, 1, v6
	v_cmp_lt_i32_e32 vcc, v2, v7
	s_mov_b32 s20, 0x41800000
	s_movk_i32 s34, 0x1fff
	v_cndmask_b32_e32 v2, v6, v2, vcc
	v_lshlrev_b32_e32 v42, 2, v2
	s_branch .LBB0_38

.LBB0_38:
	v_ashrrev_i32_e32 v31, 31, v30
	v_lshlrev_b64 v[2:3], 12, v[30:31]
	v_lshl_add_u64 v[10:11], v[26:27], 0, v[2:3]
	global_load_dwordx4 v[2:5], v[10:11], off offset:1024
	global_load_dwordx4 v[22:25], v[10:11], off offset:1536
	global_load_dwordx4 v[6:9], v[10:11], off offset:2048
	global_load_dwordx4 v[44:47], v[10:11], off
	global_load_dwordx4 v[48:51], v[10:11], off offset:512
	global_load_dwordx4 v[18:21], v[10:11], off offset:2560
	global_load_dwordx4 v[14:17], v[10:11], off offset:3072
	s_nop 0
	global_load_dwordx4 v[10:13], v[10:11], off offset:3584
	s_waitcnt vmcnt(7)
	v_max_f32_e64 v32, |v5|, |v5|
	v_max_f32_e64 v33, |v4|, |v4|
	s_waitcnt vmcnt(6)
	v_max_f32_e64 v34, |v25|, |v25|
	v_max_f32_e64 v35, |v24|, |v24|
	s_waitcnt vmcnt(5)
	v_max_f32_e64 v36, |v7|, |v7|
	v_max_f32_e64 v37, |v6|, |v6|
	s_waitcnt vmcnt(4)
	v_max_f32_e64 v43, |v45|, |v45|
	v_max_f32_e64 v52, |v44|, |v44|
	v_max_f32_e64 v53, |v47|, |v47|
	v_max_f32_e64 v54, |v46|, |v46|
	s_waitcnt vmcnt(3)
	v_max_f32_e64 v55, |v49|, |v49|
	v_max_f32_e64 v56, |v48|, |v48|
	v_max_f32_e64 v57, |v51|, |v51|
	v_max_f32_e64 v58, |v50|, |v50|
	v_max_f32_e32 v32, v33, v32
	v_max_f32_e32 v33, v35, v34
	v_max_f32_e32 v34, v37, v36
	v_max_f32_e32 v35, v52, v43
	v_max_f32_e32 v36, v54, v53
	v_max_f32_e64 v59, |v3|, |v3|
	v_max_f32_e64 v60, |v2|, |v2|
	v_max_f32_e32 v37, v56, v55
	v_max_f32_e32 v43, v58, v57
	v_max3_f32 v35, v35, 0, v36
	v_max_f32_e64 v61, |v23|, |v23|
	v_max_f32_e64 v62, |v22|, |v22|
	v_max_f32_e32 v52, v60, v59
	v_max3_f32 v35, v35, v37, v43
	v_max_f32_e64 v63, |v9|, |v9|
	v_max_f32_e64 v64, |v8|, |v8|
	v_max_f32_e32 v53, v62, v61
	v_max3_f32 v32, v35, v52, v32
	s_waitcnt vmcnt(2)
	v_max_f32_e64 v65, |v19|, |v19|
	v_max_f32_e64 v66, |v18|, |v18|
	v_max_f32_e64 v67, |v21|, |v21|
	v_max_f32_e64 v68, |v20|, |v20|
	v_max_f32_e32 v54, v64, v63
	v_max3_f32 v32, v32, v53, v33
	s_waitcnt vmcnt(1)
	v_max_f32_e64 v69, |v15|, |v15|
	v_max_f32_e64 v70, |v14|, |v14|
	v_max_f32_e64 v71, |v17|, |v17|
	v_max_f32_e64 v72, |v16|, |v16|
	v_max_f32_e32 v55, v66, v65
	v_max_f32_e32 v56, v68, v67
	v_max3_f32 v32, v32, v34, v54
	s_waitcnt vmcnt(0)
	v_max_f32_e64 v73, |v11|, |v11|
	v_max_f32_e64 v74, |v10|, |v10|
	v_max_f32_e64 v75, |v13|, |v13|
	v_max_f32_e64 v76, |v12|, |v12|
	v_max_f32_e32 v57, v70, v69
	v_max_f32_e32 v58, v72, v71
	v_max3_f32 v32, v32, v55, v56
	v_max_f32_e32 v59, v74, v73
	v_max_f32_e32 v60, v76, v75
	v_max3_f32 v32, v32, v57, v58
	v_max3_f32 v32, v32, v59, v60
	ds_bpermute_b32 v33, v38, v32
	v_mov_b32_e32 v36, v22
	v_mov_b32_e32 v37, v8
	v_mov_b32_e32 v8, v23
	v_mov_b32_e32 v52, v45
	s_waitcnt lgkmcnt(0)
	v_max_f32_e32 v33, v33, v33
	v_max_f32_e32 v32, v32, v33
	ds_bpermute_b32 v33, v39, v32
	v_mov_b32_e32 v53, v50
	v_mov_b32_e32 v50, v46
	v_mov_b32_e32 v46, v47
	v_mov_b32_e32 v47, v2
	s_waitcnt lgkmcnt(0)
	v_max_f32_e32 v33, v33, v33
	v_max_f32_e32 v34, v32, v33
	ds_bpermute_b32 v35, v40, v34
	v_mov_b32_e32 v2, v48
	v_mad_i64_i32 v[32:33], s[4:5], v30, s30, v[28:29]
	s_waitcnt lgkmcnt(0)
	v_max_f32_e32 v35, v35, v35
	v_max_f32_e32 v34, v34, v35
	ds_bpermute_b32 v35, v41, v34
	s_waitcnt lgkmcnt(0)
	v_max_f32_e32 v35, v35, v35
	v_max_f32_e32 v35, v34, v35
	ds_bpermute_b32 v43, v42, v35
	v_mov_b32_e32 v34, v24
	s_waitcnt lgkmcnt(0)
	v_max_f32_e32 v22, v43, v43
	v_max_f32_e32 v24, v35, v22
	v_div_scale_f32 v22, s[4:5], v24, v24, s31
	v_rcp_f32_e32 v23, v22
	v_mov_b32_e32 v35, v18
	v_div_scale_f32 v18, vcc, s31, v24, s31
	v_fma_f32 v43, -v22, v23, 1.0
	v_fmac_f32_e32 v23, v43, v23
	v_mul_f32_e32 v43, v18, v23
	v_fma_f32 v45, -v22, v43, v18
	v_fmac_f32_e32 v43, v45, v23
	v_fma_f32 v18, -v22, v43, v18
	v_div_fmas_f32 v18, v18, v23, v43
	v_div_fixup_f32 v18, v18, v24, s31
	v_cmp_lt_f32_e32 vcc, 0, v24
	s_nop 1
	v_cndmask_b32_e32 v18, 1.0, v18, vcc
	v_mul_f32_e32 v22, v44, v18
	v_pk_mul_f32 v[56:57], v[2:3], v[18:19] op_sel_hi:[1,0]
	v_min_f32_e64 v2, |v22|, s31
	v_mul_f32_e32 v43, 4.0, v2
	v_mul_f32_e32 v23, 0x41000000, v2
	v_add_f32_e32 v44, v2, v2
	v_rndne_f32_e32 v43, v43
	v_rndne_f32_e32 v23, v23
	v_rndne_f32_e32 v44, v44
	v_add_f32_e32 v43, 0x41000000, v43
	v_cmp_nle_f32_e64 s[4:5], 2.0, v2
	v_add_f32_e32 v44, 0x41800000, v44
	v_pk_mul_f32 v[54:55], v[46:47], v[18:19] op_sel_hi:[1,0]
	v_cndmask_b32_e64 v23, v43, v23, s[4:5]
	v_cmp_nle_f32_e64 s[4:5], 4.0, v2
	v_pk_mul_f32 v[52:53], v[52:53], v[18:19] op_sel_hi:[1,0]
	v_min_f32_e64 v67, |v54|, s31
	v_cndmask_b32_e64 v2, v44, v23, s[4:5]
	v_cvt_u32_f32_e32 v2, v2
	v_lshrrev_b32_e32 v3, 26, v22
	v_min_f32_e64 v22, |v52|, s31
	v_mul_f32_e32 v61, 0x41000000, v67
	v_add_f32_e32 v47, v22, v22
	v_rndne_f32_e32 v69, v61
	v_min_f32_e64 v61, |v53|, s31
	v_rndne_f32_e32 v48, v47
	v_min_u32_e32 v2, 31, v2
	v_mul_f32_e32 v47, 0x41000000, v61
	v_mul_f32_e32 v46, 4.0, v22
	v_and_or_b32 v43, v3, 32, v2
	v_mul_f32_e32 v3, v49, v18
	v_rndne_f32_e32 v49, v47
	v_mul_f32_e32 v47, 4.0, v61
	v_mul_f32_e32 v45, 0x41000000, v22
	v_rndne_f32_e32 v46, v46
	v_rndne_f32_e32 v47, v47
	v_rndne_f32_e32 v45, v45
	v_pk_add_f32 v[46:47], v[46:47], s[18:19] op_sel_hi:[1,0]
	v_cmp_nle_f32_e64 s[4:5], 2.0, v22
	v_pk_mul_f32 v[50:51], v[50:51], v[18:19] op_sel_hi:[1,0]
	v_min_f32_e64 v44, |v3|, s31
	v_cndmask_b32_e64 v45, v46, v45, s[4:5]
	v_cmp_nle_f32_e64 s[4:5], 2.0, v61
	v_add_f32_e32 v46, v61, v61
	v_min_f32_e64 v63, |v50|, s31
	v_cndmask_b32_e64 v72, v47, v49, s[4:5]
	v_rndne_f32_e32 v49, v46
	v_pk_add_f32 v[46:47], v[48:49], s[20:21] op_sel_hi:[1,0]
	v_cmp_nle_f32_e64 s[4:5], 4.0, v61
	v_mul_f32_e32 v58, 0x41000000, v63
	v_mul_f32_e32 v59, 4.0, v63
	v_cndmask_b32_e64 v47, v47, v72, s[4:5]
	v_cmp_nle_f32_e64 s[4:5], 4.0, v22
	v_rndne_f32_e32 v65, v58
	v_rndne_f32_e32 v58, v59
	v_cndmask_b32_e64 v22, v46, v45, s[4:5]
	v_cvt_u32_f32_e32 v46, v47
	v_cvt_u32_f32_e32 v47, v22
	v_lshrrev_b32_e32 v45, 26, v3
	v_add_f32_e32 v59, v44, v44
	v_min_u32_e32 v3, 31, v46
	v_lshrrev_b32_e32 v46, 26, v53
	v_min_f32_e64 v53, |v51|, s31
	v_and_b32_e32 v49, 32, v46
	v_mul_f32_e32 v46, 0x41000000, v53
	v_rndne_f32_e32 v61, v46
	v_mul_f32_e32 v46, 4.0, v53
	v_rndne_f32_e32 v22, v59
	v_min_u32_e32 v48, 31, v47
	v_lshrrev_b32_e32 v47, 26, v52
	v_rndne_f32_e32 v59, v46
	v_and_b32_e32 v52, 32, v47
	v_pk_add_f32 v[46:47], v[58:59], s[18:19] op_sel_hi:[1,0]
	v_cmp_nle_f32_e64 s[4:5], 2.0, v63
	v_add_f32_e32 v60, v63, v63
	v_rndne_f32_e32 v60, v60
	v_cndmask_b32_e64 v58, v46, v65, s[4:5]
	v_cmp_nle_f32_e64 s[4:5], 2.0, v53
	v_add_f32_e32 v46, v53, v53
	v_or_b32_e32 v3, v3, v49
	v_cndmask_b32_e64 v59, v47, v61, s[4:5]
	v_rndne_f32_e32 v61, v46
	v_pk_add_f32 v[46:47], v[60:61], s[20:21] op_sel_hi:[1,0]
	v_cmp_nle_f32_e64 s[4:5], 4.0, v53
	v_lshrrev_b32_e32 v49, 26, v50
	v_mul_f32_e32 v62, 4.0, v67
	v_cndmask_b32_e64 v47, v47, v59, s[4:5]
	v_cmp_nle_f32_e64 s[4:5], 4.0, v63
	v_rndne_f32_e32 v62, v62
	v_cvt_u32_f32_e32 v47, v47
	v_cndmask_b32_e64 v46, v46, v58, s[4:5]
	v_cvt_u32_f32_e32 v53, v46
	v_or_b32_e32 v46, v48, v52
	v_lshrrev_b32_e32 v48, 26, v51
	v_and_b32_e32 v50, 32, v48
	v_min_u32_e32 v52, 31, v53
	v_min_f32_e64 v53, |v55|, s31
	v_mul_f32_e32 v48, 0x41000000, v53
	v_rndne_f32_e32 v58, v48
	v_mul_f32_e32 v48, 4.0, v53
	v_rndne_f32_e32 v63, v48
	v_and_b32_e32 v51, 32, v49
	v_pk_add_f32 v[48:49], v[62:63], s[18:19] op_sel_hi:[1,0]
	v_cmp_nle_f32_e64 s[4:5], 2.0, v67
	v_add_f32_e32 v64, v67, v67
	v_rndne_f32_e32 v64, v64
	v_cndmask_b32_e64 v59, v48, v69, s[4:5]
	v_add_f32_e32 v48, v53, v53
	v_cmp_nle_f32_e64 s[4:5], 2.0, v53
	v_rndne_f32_e32 v65, v48
	v_min_u32_e32 v47, 31, v47
	v_cndmask_b32_e64 v58, v49, v58, s[4:5]
	v_pk_add_f32 v[48:49], v[64:65], s[20:21] op_sel_hi:[1,0]
	v_cmp_nle_f32_e64 s[4:5], 4.0, v53
	v_min_f32_e64 v70, |v56|, s31
	v_mul_f32_e32 v2, 0x41000000, v70
	v_cndmask_b32_e64 v49, v49, v58, s[4:5]
	v_cvt_u32_f32_e32 v53, v49
	v_or_b32_e32 v49, v47, v50
	v_or_b32_e32 v50, v52, v51
	v_lshrrev_b32_e32 v51, 26, v55
	v_lshrrev_b32_e32 v52, 26, v54
	v_min_f32_e64 v55, |v57|, s31
	v_and_b32_e32 v54, 32, v52
	v_mul_f32_e32 v52, 0x41000000, v55
	v_rndne_f32_e32 v71, v2
	v_mul_f32_e32 v2, 4.0, v70
	v_rndne_f32_e32 v58, v52
	v_mul_f32_e32 v52, 4.0, v55
	v_rndne_f32_e32 v66, v2
	v_cmp_nle_f32_e64 s[4:5], 4.0, v67
	v_rndne_f32_e32 v67, v52
	v_min_u32_e32 v47, 31, v53
	v_cndmask_b32_e64 v48, v48, v59, s[4:5]
	v_pk_add_f32 v[52:53], v[66:67], s[18:19] op_sel_hi:[1,0]
	v_cmp_nle_f32_e64 s[4:5], 2.0, v70
	v_add_f32_e32 v2, v70, v70
	v_rndne_f32_e32 v68, v2
	v_cndmask_b32_e64 v59, v52, v71, s[4:5]
	v_add_f32_e32 v52, v55, v55
	v_cmp_nle_f32_e64 s[4:5], 2.0, v55
	v_rndne_f32_e32 v69, v52
	v_cvt_u32_f32_e32 v48, v48
	v_cndmask_b32_e64 v58, v53, v58, s[4:5]
	v_pk_add_f32 v[52:53], v[68:69], s[20:21] op_sel_hi:[1,0]
	v_cmp_nle_f32_e64 s[4:5], 4.0, v55
	v_mul_f32_e32 v5, v5, v18
	v_min_u32_e32 v48, 31, v48
	v_cndmask_b32_e64 v53, v53, v58, s[4:5]
	v_cvt_u32_f32_e32 v53, v53
	v_and_b32_e32 v51, 32, v51
	v_min_f32_e64 v55, |v5|, s31
	v_or_b32_sdwa v47, v47, v51 dst_sel:WORD_1 dst_unused:UNUSED_PAD src0_sel:DWORD src1_sel:DWORD
	v_or_b32_e32 v51, v48, v54
	v_min_u32_e32 v48, 31, v53
	v_lshrrev_b32_e32 v53, 26, v57
	v_mul_f32_e32 v57, 4.0, v55
	v_cmp_nle_f32_e64 s[4:5], 4.0, v70
	v_lshrrev_b32_e32 v54, 26, v56
	v_mul_f32_e32 v56, 0x41000000, v55
	v_rndne_f32_e32 v57, v57
	v_cndmask_b32_e64 v52, v52, v59, s[4:5]
	v_rndne_f32_e32 v56, v56
	v_add_f32_e32 v57, 0x41000000, v57
	v_cmp_nle_f32_e64 s[4:5], 2.0, v55
	v_cvt_u32_f32_e32 v52, v52
	v_and_b32_e32 v53, 32, v53
	v_cndmask_b32_e64 v56, v57, v56, s[4:5]
	v_add_f32_e32 v57, v55, v55
	v_rndne_f32_e32 v57, v57
	v_add_f32_e32 v57, 0x41800000, v57
	v_cmp_nle_f32_e64 s[4:5], 4.0, v55
	v_min_u32_e32 v52, 31, v52
	v_and_b32_e32 v54, 32, v54
	v_cndmask_b32_e64 v55, v57, v56, s[4:5]
	v_cvt_u32_f32_e32 v55, v55
	v_or_b32_e32 v66, v48, v53
	v_or_b32_sdwa v48, v52, v54 dst_sel:BYTE_3 dst_unused:UNUSED_PAD src0_sel:DWORD src1_sel:DWORD
	v_lshrrev_b32_e32 v5, 26, v5
	v_min_u32_e32 v52, 31, v55
	v_pk_mul_f32 v[36:37], v[36:37], v[18:19] op_sel_hi:[1,0]
	v_and_or_b32 v67, v5, 32, v52
	v_min_f32_e64 v5, |v36|, s31
	v_pk_mul_f32 v[8:9], v[8:9], v[18:19] op_sel_hi:[1,0]
	v_add_f32_e32 v53, v5, v5
	v_min_f32_e64 v61, |v8|, s31
	v_rndne_f32_e32 v54, v53
	v_mul_f32_e32 v53, 0x41000000, v61
	v_rndne_f32_e32 v59, v53
	v_mul_f32_e32 v53, 4.0, v61
	v_pk_mul_f32 v[34:35], v[34:35], v[18:19] op_sel_hi:[1,0]
	v_rndne_f32_e32 v56, v53
	v_add_f32_e32 v53, v61, v61
	v_min_f32_e64 v64, |v34|, s31
	v_rndne_f32_e32 v58, v53
	v_mul_f32_e32 v53, 0x41000000, v64
	v_rndne_f32_e32 v63, v53
	v_mul_f32_e32 v53, 4.0, v64
	v_mul_f32_e32 v25, v25, v18
	v_rndne_f32_e32 v60, v53
	v_min_f32_e64 v53, |v25|, s31
	v_mul_f32_e32 v62, 4.0, v53
	v_mul_f32_e32 v57, 0x41000000, v53
	v_rndne_f32_e32 v62, v62
	v_rndne_f32_e32 v57, v57
	v_add_f32_e32 v62, 0x41000000, v62
	v_cmp_nle_f32_e64 s[4:5], 2.0, v53
	v_mul_f32_e32 v6, v6, v18
	v_mul_f32_e32 v52, 0x41000000, v5
	v_cndmask_b32_e64 v57, v62, v57, s[4:5]
	v_add_f32_e32 v62, v53, v53
	v_rndne_f32_e32 v62, v62
	v_add_f32_e32 v62, 0x41800000, v62
	v_cmp_nle_f32_e64 s[4:5], 4.0, v53
	v_rndne_f32_e32 v55, v52
	v_mul_f32_e32 v52, 4.0, v5
	v_cndmask_b32_e64 v53, v62, v57, s[4:5]
	v_min_f32_e64 v57, |v6|, s31
	v_mul_f32_e32 v65, 4.0, v57
	v_mul_f32_e32 v62, 0x41000000, v57
	v_rndne_f32_e32 v65, v65
	v_rndne_f32_e32 v62, v62
	v_add_f32_e32 v65, 0x41000000, v65
	v_cmp_nle_f32_e64 s[4:5], 2.0, v57
	v_cvt_u32_f32_e32 v53, v53
	v_rndne_f32_e32 v52, v52
	v_cndmask_b32_e64 v62, v65, v62, s[4:5]
	v_add_f32_e32 v65, v57, v57
	v_rndne_f32_e32 v65, v65
	v_add_f32_e32 v65, 0x41800000, v65
	v_cmp_nle_f32_e64 s[4:5], 4.0, v57
	v_min_u32_e32 v68, 31, v53
	v_lshrrev_b32_e32 v36, 26, v36
	v_cndmask_b32_e64 v57, v65, v62, s[4:5]
	v_min_f32_e64 v65, |v37|, s31
	v_mul_f32_e32 v53, 0x41000000, v65
	v_rndne_f32_e32 v69, v53
	v_mul_f32_e32 v53, 4.0, v65
	v_rndne_f32_e32 v53, v53
	v_pk_add_f32 v[52:53], v[52:53], s[18:19] op_sel_hi:[1,0]
	v_cmp_nle_f32_e64 s[4:5], 2.0, v5
	v_cvt_u32_f32_e32 v57, v57
	v_lshrrev_b32_e32 v6, 26, v6
	v_cndmask_b32_e64 v70, v52, v55, s[4:5]
	v_add_f32_e32 v52, v65, v65
	v_cmp_nle_f32_e64 s[4:5], 2.0, v65
	v_rndne_f32_e32 v55, v52
	v_min_u32_e32 v57, 31, v57
	v_cndmask_b32_e64 v69, v53, v69, s[4:5]
	v_pk_add_f32 v[52:53], v[54:55], s[20:21] op_sel_hi:[1,0]
	v_min_f32_e64 v55, |v9|, s31
	v_and_b32_e32 v54, 32, v36
	v_mul_f32_e32 v36, 0x41000000, v55
	v_cmp_nle_f32_e64 s[4:5], 4.0, v65
	v_rndne_f32_e32 v65, v36
	v_mul_f32_e32 v36, 4.0, v55
	v_cndmask_b32_e64 v53, v53, v69, s[4:5]
	v_cmp_nle_f32_e64 s[4:5], 4.0, v5
	v_and_or_b32 v6, v6, 32, v57
	v_lshrrev_b32_e32 v37, 26, v37
	v_rndne_f32_e32 v57, v36
	v_cndmask_b32_e64 v5, v52, v70, s[4:5]
	v_cvt_u32_f32_e32 v52, v53
	v_and_b32_e32 v53, 32, v37
	v_pk_add_f32 v[36:37], v[56:57], s[18:19] op_sel_hi:[1,0]
	v_cmp_nle_f32_e64 s[4:5], 2.0, v61
	v_cvt_u32_f32_e32 v5, v5
	v_min_u32_e32 v52, 31, v52
	v_cndmask_b32_e64 v56, v36, v59, s[4:5]
	v_add_f32_e32 v36, v55, v55
	v_cmp_nle_f32_e64 s[4:5], 2.0, v55
	v_rndne_f32_e32 v59, v36
	v_or_b32_e32 v69, v52, v53
	v_cndmask_b32_e64 v57, v37, v65, s[4:5]
	v_pk_add_f32 v[36:37], v[58:59], s[20:21] op_sel_hi:[1,0]
	v_cmp_nle_f32_e64 s[4:5], 4.0, v55
	v_lshrrev_b32_e32 v8, 26, v8
	v_min_f32_e64 v53, |v35|, s31
	v_cndmask_b32_e64 v37, v37, v57, s[4:5]
	v_cvt_u32_f32_e32 v37, v37
	v_min_u32_e32 v5, 31, v5
	v_and_b32_e32 v52, 32, v8
	v_mul_f32_e32 v8, 0x41000000, v53
	v_or_b32_e32 v70, v5, v54
	v_rndne_f32_e32 v54, v8
	v_mul_f32_e32 v8, 4.0, v53
	v_cmp_nle_f32_e64 s[4:5], 4.0, v61
	v_lshrrev_b32_e32 v9, 26, v9
	v_rndne_f32_e32 v61, v8
	v_cndmask_b32_e64 v36, v36, v56, s[4:5]
	v_min_u32_e32 v5, 31, v37
	v_and_b32_e32 v37, 32, v9
	v_pk_add_f32 v[8:9], v[60:61], s[18:19] op_sel_hi:[1,0]
	v_cmp_nle_f32_e64 s[4:5], 2.0, v64
	v_add_f32_e32 v62, v64, v64
	v_rndne_f32_e32 v62, v62
	v_cndmask_b32_e64 v55, v8, v63, s[4:5]
	v_add_f32_e32 v8, v53, v53
	v_cmp_nle_f32_e64 s[4:5], 2.0, v53
	v_rndne_f32_e32 v63, v8
	v_or_b32_e32 v71, v5, v37
	v_cndmask_b32_e64 v54, v9, v54, s[4:5]
	v_pk_add_f32 v[8:9], v[62:63], s[20:21] op_sel_hi:[1,0]
	v_cmp_nle_f32_e64 s[4:5], 4.0, v53
	v_lshrrev_b32_e32 v34, 26, v34
	v_and_b32_e32 v34, 32, v34
	v_cndmask_b32_e64 v9, v9, v54, s[4:5]
	v_cmp_nle_f32_e64 s[4:5], 4.0, v64
	v_cvt_u32_f32_e32 v9, v9
	v_cvt_u32_f32_e32 v36, v36
	v_cndmask_b32_e64 v8, v8, v55, s[4:5]
	v_cvt_u32_f32_e32 v8, v8
	v_min_u32_e32 v5, 31, v9
	v_lshrrev_b32_e32 v9, 26, v35
	v_and_b32_e32 v9, 32, v9
	v_min_u32_e32 v8, 31, v8
	v_or_b32_sdwa v73, v5, v9 dst_sel:BYTE_3 dst_unused:UNUSED_PAD src0_sel:DWORD src1_sel:DWORD
	v_or_b32_e32 v74, v8, v34
	v_mov_b32_e32 v8, v19
	v_mov_b32_e32 v9, v16
	v_pk_mul_f32 v[8:9], v[8:9], v[18:19] op_sel_hi:[1,0]
	v_mov_b32_e32 v16, v20
	v_min_f32_e64 v19, |v8|, s31
	v_mul_f32_e32 v5, 0x41000000, v19
	v_rndne_f32_e32 v37, v5
	v_mul_f32_e32 v5, 4.0, v19
	v_pk_mul_f32 v[16:17], v[16:17], v[18:19] op_sel_hi:[1,0]
	v_min_u32_e32 v36, 31, v36
	v_rndne_f32_e32 v34, v5
	v_add_f32_e32 v5, v19, v19
	v_min_f32_e64 v57, |v16|, s31
	v_or_b32_e32 v72, v36, v52
	v_rndne_f32_e32 v36, v5
	v_mul_f32_e32 v5, 0x41000000, v57
	v_mov_b32_e32 v54, v21
	v_mov_b32_e32 v55, v10
	v_rndne_f32_e32 v53, v5
	v_mul_f32_e32 v5, 4.0, v57
	v_pk_mul_f32 v[54:55], v[54:55], v[18:19] op_sel_hi:[1,0]
	v_rndne_f32_e32 v20, v5
	v_add_f32_e32 v5, v57, v57
	v_min_f32_e64 v61, |v54|, s31
	v_rndne_f32_e32 v52, v5
	v_mul_f32_e32 v5, 0x41000000, v61
	v_rndne_f32_e32 v65, v5
	v_mul_f32_e32 v5, 4.0, v61
	v_rndne_f32_e32 v10, v5
	v_add_f32_e32 v5, v61, v61
	v_rndne_f32_e32 v56, v5
	v_mov_b32_e32 v58, v11
	v_mov_b32_e32 v59, v12
	v_mov_b32_e32 v5, v14
	v_pk_mov_b32 v[58:59], v[4:5], v[58:59] op_sel:[1,0]
	v_mov_b32_e32 v62, v15
	v_pk_mul_f32 v[58:59], v[58:59], v[18:19] op_sel_hi:[1,0]
	v_mov_b32_e32 v63, v12
	v_min_f32_e64 v5, |v58|, s31
	v_mul_f32_e32 v11, 0x41000000, v5
	v_rndne_f32_e32 v75, v11
	v_mul_f32_e32 v11, 4.0, v5
	v_pk_mul_f32 v[62:63], v[62:63], v[18:19] op_sel_hi:[1,0]
	v_rndne_f32_e32 v14, v11
	v_add_f32_e32 v11, v5, v5
	v_min_f32_e64 v12, |v62|, s31
	v_rndne_f32_e32 v60, v11
	v_mul_f32_e32 v11, 0x41000000, v12
	v_rndne_f32_e32 v76, v11
	v_mul_f32_e32 v11, 4.0, v12
	v_rndne_f32_e32 v64, v11
	v_min_f32_e64 v11, |v9|, s31
	v_mul_f32_e32 v21, 4.0, v11
	v_rndne_f32_e32 v35, v21
	v_pk_add_f32 v[34:35], v[34:35], s[18:19] op_sel_hi:[1,0]
	v_cmp_nle_f32_e64 s[4:5], 2.0, v19
	v_mul_f32_e32 v15, 0x41000000, v11
	v_rndne_f32_e32 v15, v15
	v_cndmask_b32_e64 v21, v34, v37, s[4:5]
	v_add_f32_e32 v34, v11, v11
	v_cmp_nle_f32_e64 s[4:5], 2.0, v11
	v_rndne_f32_e32 v37, v34
	v_lshrrev_b32_e32 v8, 26, v8
	v_cndmask_b32_e64 v15, v35, v15, s[4:5]
	v_pk_add_f32 v[34:35], v[36:37], s[20:21] op_sel_hi:[1,0]
	v_cmp_nle_f32_e64 s[4:5], 4.0, v11
	v_lshrrev_b32_e32 v9, 26, v9
	v_mul_f32_e32 v13, v13, v18
	v_cndmask_b32_e64 v11, v35, v15, s[4:5]
	v_cmp_nle_f32_e64 s[4:5], 4.0, v19
	v_cvt_u32_f32_e32 v11, v11
	v_min_f32_e64 v35, |v17|, s31
	v_cndmask_b32_e64 v15, v34, v21, s[4:5]
	v_cvt_u32_f32_e32 v15, v15
	v_add_f32_e32 v19, v12, v12
	v_rndne_f32_e32 v34, v19
	v_min_u32_e32 v19, 31, v11
	v_min_u32_e32 v36, 31, v15
	v_and_b32_e32 v15, 32, v8
	v_mul_f32_e32 v8, 0x41000000, v35
	v_rndne_f32_e32 v37, v8
	v_mul_f32_e32 v8, 4.0, v35
	v_rndne_f32_e32 v21, v8
	v_and_b32_e32 v11, 32, v9
	v_pk_add_f32 v[8:9], v[20:21], s[18:19] op_sel_hi:[1,0]
	v_cmp_nle_f32_e64 s[4:5], 2.0, v57
	v_mul_f32_e32 v2, 0x41000000, v44
	v_rndne_f32_e32 v23, v2
	v_cndmask_b32_e64 v20, v8, v53, s[4:5]
	v_add_f32_e32 v8, v35, v35
	v_cmp_nle_f32_e64 s[4:5], 2.0, v35
	v_rndne_f32_e32 v53, v8
	v_mul_f32_e32 v2, 4.0, v44
	v_cndmask_b32_e64 v21, v9, v37, s[4:5]
	v_pk_add_f32 v[8:9], v[52:53], s[20:21] op_sel_hi:[1,0]
	v_cmp_nle_f32_e64 s[4:5], 4.0, v35
	v_min_f32_e64 v37, |v55|, s31
	v_rndne_f32_e32 v2, v2
	v_cndmask_b32_e64 v9, v9, v21, s[4:5]
	v_cmp_nle_f32_e64 s[4:5], 4.0, v57
	v_cvt_u32_f32_e32 v9, v9
	v_or_b32_e32 v21, v36, v15
	v_cndmask_b32_e64 v8, v8, v20, s[4:5]
	v_cvt_u32_f32_e32 v8, v8
	v_min_u32_e32 v15, 31, v9
	v_lshrrev_b32_e32 v9, 26, v16
	v_or_b32_e32 v20, v19, v11
	v_min_u32_e32 v35, 31, v8
	v_lshrrev_b32_e32 v8, 26, v17
	v_and_b32_e32 v16, 32, v8
	v_mul_f32_e32 v8, 0x41000000, v37
	v_rndne_f32_e32 v52, v8
	v_mul_f32_e32 v8, 4.0, v37
	v_rndne_f32_e32 v11, v8
	v_and_b32_e32 v17, 32, v9
	v_pk_add_f32 v[8:9], v[10:11], s[18:19] op_sel_hi:[1,0]
	v_cmp_nle_f32_e64 s[4:5], 2.0, v61
	s_nop 1
	v_cndmask_b32_e64 v10, v8, v65, s[4:5]
	v_add_f32_e32 v8, v37, v37
	v_cmp_nle_f32_e64 s[4:5], 2.0, v37
	v_rndne_f32_e32 v57, v8
	s_nop 0
	v_cndmask_b32_e64 v11, v9, v52, s[4:5]
	v_pk_add_f32 v[8:9], v[56:57], s[20:21] op_sel_hi:[1,0]
	v_cmp_nle_f32_e64 s[4:5], 4.0, v37
	v_min_f32_e64 v52, |v59|, s31
	s_nop 0
	v_cndmask_b32_e64 v9, v9, v11, s[4:5]
	v_cmp_nle_f32_e64 s[4:5], 4.0, v61
	v_cvt_u32_f32_e32 v9, v9
	v_or_b32_e32 v11, v35, v17
	v_cndmask_b32_e64 v8, v8, v10, s[4:5]
	v_cvt_u32_f32_e32 v8, v8
	v_or_b32_e32 v10, v15, v16
	v_min_u32_e32 v16, 31, v9
	v_lshrrev_b32_e32 v9, 26, v54
	v_min_u32_e32 v17, 31, v8
	v_lshrrev_b32_e32 v8, 26, v55
	v_and_b32_e32 v35, 32, v8
	v_mul_f32_e32 v8, 0x41000000, v52
	v_rndne_f32_e32 v53, v8
	v_mul_f32_e32 v8, 4.0, v52
	v_rndne_f32_e32 v15, v8
	v_and_b32_e32 v37, 32, v9
	v_pk_add_f32 v[8:9], v[14:15], s[18:19] op_sel_hi:[1,0]
	v_cmp_nle_f32_e64 s[4:5], 2.0, v5
	v_lshlrev_b32_e32 v10, 2, v10
	v_lshlrev_b32_e32 v11, 4, v11
	v_cndmask_b32_e64 v14, v8, v75, s[4:5]
	v_add_f32_e32 v8, v52, v52
	v_cmp_nle_f32_e64 s[4:5], 2.0, v52
	v_rndne_f32_e32 v61, v8
	s_nop 0
	v_cndmask_b32_e64 v15, v9, v53, s[4:5]
	v_pk_add_f32 v[8:9], v[60:61], s[20:21] op_sel_hi:[1,0]
	v_cmp_nle_f32_e64 s[4:5], 4.0, v52
	v_min_f32_e64 v52, |v63|, s31
	s_nop 0
	v_cndmask_b32_e64 v9, v9, v15, s[4:5]
	v_cmp_nle_f32_e64 s[4:5], 4.0, v5
	v_or_b32_e32 v15, v17, v37
	s_nop 0
	v_cndmask_b32_e64 v5, v8, v14, s[4:5]
	v_cvt_u32_f32_e32 v8, v9
	v_or_b32_e32 v14, v16, v35
	v_cvt_u32_f32_e32 v5, v5
	v_lshrrev_b32_e32 v9, 26, v58
	v_min_u32_e32 v16, 31, v8
	v_lshrrev_b32_e32 v8, 26, v59
	v_and_b32_e32 v17, 32, v8
	v_mul_f32_e32 v8, 0x41000000, v52
	v_rndne_f32_e32 v35, v8
	v_mul_f32_e32 v8, 4.0, v52
	v_rndne_f32_e32 v65, v8
	v_and_b32_e32 v37, 32, v9
	v_pk_add_f32 v[8:9], v[64:65], s[18:19] op_sel_hi:[1,0]
	v_cmp_nle_f32_e64 s[4:5], 2.0, v12
	v_min_u32_e32 v5, 31, v5
	s_nop 0
	v_cndmask_b32_e64 v53, v8, v76, s[4:5]
	v_cmp_nle_f32_e64 s[4:5], 2.0, v52
	v_add_f32_e32 v8, v52, v52
	s_nop 0
	v_cndmask_b32_e64 v54, v9, v35, s[4:5]
	v_rndne_f32_e32 v35, v8
	v_pk_add_f32 v[8:9], v[34:35], s[20:21] op_sel_hi:[1,0]
	v_cmp_nle_f32_e64 s[4:5], 4.0, v52
	v_min_f32_e64 v34, |v13|, s31
	v_mul_f32_e32 v35, 0x41000000, v34
	v_cndmask_b32_e64 v9, v9, v54, s[4:5]
	v_cmp_nle_f32_e64 s[4:5], 4.0, v12
	v_or_b32_e32 v12, v16, v17
	v_or_b32_sdwa v16, v5, v37 dst_sel:WORD_1 dst_unused:UNUSED_PAD src0_sel:DWORD src1_sel:DWORD
	v_mul_f32_e32 v37, 4.0, v34
	v_rndne_f32_e32 v37, v37
	v_cndmask_b32_e64 v8, v8, v53, s[4:5]
	v_rndne_f32_e32 v35, v35
	v_add_f32_e32 v37, 0x41000000, v37
	v_cmp_nle_f32_e64 s[4:5], 2.0, v34
	v_cvt_u32_f32_e32 v9, v9
	v_cvt_u32_f32_e32 v8, v8
	v_cndmask_b32_e64 v35, v37, v35, s[4:5]
	v_add_f32_e32 v37, v34, v34
	v_rndne_f32_e32 v37, v37
	v_add_f32_e32 v37, 0x41800000, v37
	v_cmp_nle_f32_e64 s[4:5], 4.0, v34
	v_min_u32_e32 v5, 31, v9
	v_lshrrev_b32_e32 v9, 26, v63
	v_cndmask_b32_e64 v34, v37, v35, s[4:5]
	v_cvt_u32_f32_e32 v34, v34
	v_and_b32_e32 v9, 32, v9
	v_lshrrev_b32_e32 v17, 26, v62
	v_or_b32_e32 v9, v5, v9
	v_mov_b32_e32 v5, v7
	v_min_u32_e32 v8, 31, v8
	v_and_b32_e32 v17, 32, v17
	v_pk_mul_f32 v[4:5], v[4:5], v[18:19] op_sel_hi:[1,0]
	v_or_b32_e32 v8, v8, v17
	v_min_u32_e32 v17, 31, v34
	v_lshlrev_b32_e32 v34, 4, v3
	v_and_b32_e32 v3, 0x80000000, v25
	v_min_f32_e64 v7, |v4|, s31
	v_lshl_or_b32 v25, v68, 26, v3
	v_mul_f32_e32 v3, 0x41000000, v7
	v_rndne_f32_e32 v18, v3
	v_mul_f32_e32 v3, 4.0, v7
	v_rndne_f32_e32 v3, v3
	v_pk_add_f32 v[2:3], v[2:3], s[18:19] op_sel_hi:[1,0]
	v_cmp_nle_f32_e64 s[4:5], 2.0, v44
	v_lshlrev_b32_e32 v37, 10, v49
	v_lshrrev_b32_e32 v4, 26, v4
	v_cndmask_b32_e64 v52, v2, v23, s[4:5]
	v_cmp_nle_f32_e64 s[4:5], 2.0, v7
	v_add_f32_e32 v2, v7, v7
	v_rndne_f32_e32 v23, v2
	v_cndmask_b32_e64 v18, v3, v18, s[4:5]
	v_cmp_nle_f32_e64 s[4:5], 4.0, v7
	v_min_f32_e64 v7, |v5|, s31
	v_pk_add_f32 v[2:3], v[22:23], s[20:21] op_sel_hi:[1,0]
	v_mul_f32_e32 v22, 4.0, v7
	v_cndmask_b32_e64 v3, v3, v18, s[4:5]
	v_cmp_nle_f32_e64 s[4:5], 4.0, v44
	v_mul_f32_e32 v18, 0x41000000, v7
	v_rndne_f32_e32 v22, v22
	v_cndmask_b32_e64 v2, v2, v52, s[4:5]
	v_rndne_f32_e32 v18, v18
	v_add_f32_e32 v22, 0x41000000, v22
	v_cmp_nle_f32_e64 s[4:5], 2.0, v7
	v_cvt_u32_f32_e32 v2, v2
	v_cvt_u32_f32_e32 v3, v3
	v_cndmask_b32_e64 v18, v22, v18, s[4:5]
	v_add_f32_e32 v22, v7, v7
	v_rndne_f32_e32 v22, v22
	v_add_f32_e32 v22, 0x41800000, v22
	v_cmp_nle_f32_e64 s[4:5], 4.0, v7
	v_min_u32_e32 v2, 31, v2
	v_lshrrev_b32_e32 v5, 26, v5
	v_cndmask_b32_e64 v7, v22, v18, s[4:5]
	v_cvt_u32_f32_e32 v7, v7
	v_and_or_b32 v18, v45, 32, v2
	v_and_b32_e32 v5, 32, v5
	v_lshlrev_b32_e32 v35, 6, v46
	v_min_u32_e32 v7, 31, v7
	v_or_b32_e32 v5, v7, v5
	v_lshrrev_b32_e32 v7, 2, v18
	v_or_b32_e32 v7, v34, v7
	v_min_u32_e32 v3, 31, v3
	v_and_b32_e32 v4, 32, v4
	v_or_b32_e32 v7, v7, v37
	v_lshlrev_b32_e32 v46, 12, v50
	v_lshlrev_b32_e32 v50, 22, v66
	v_or_b32_e32 v4, v3, v4
	v_or_b32_e32 v18, v35, v43
	v_or_b32_e32 v7, v7, v47
	v_lshlrev_b32_e32 v49, 18, v51
	v_lshlrev_b32_e32 v51, 2, v67
	v_or_b32_e32 v18, v18, v46
	v_or_b32_e32 v7, v7, v50
	v_lshlrev_b32_e32 v3, 28, v3
	v_lshrrev_b32_e32 v4, 4, v4
	v_or_b32_e32 v18, v18, v49
	v_or_b32_e32 v3, v7, v3
	v_or_b32_e32 v4, v4, v51
	v_lshlrev_b32_e32 v7, 8, v70
	v_or_b32_e32 v18, v18, v48
	v_lshlrev_b32_e32 v2, 30, v2
	v_or_b32_e32 v4, v4, v7
	v_lshlrev_b32_e32 v7, 14, v72
	v_or_b32_e32 v2, v18, v2
	v_lshlrev_b32_e32 v5, 6, v5
	v_or_b32_e32 v4, v4, v7
	v_lshrrev_b32_e32 v7, 4, v20
	v_lshrrev_b32_e32 v18, 2, v21
	v_or_b32_e32 v5, v5, v6
	v_lshlrev_b32_e32 v6, 12, v69
	v_or_b32_e32 v7, v7, v10
	v_or_b32_e32 v10, v18, v11
	v_lshlrev_b32_e32 v11, 8, v14
	v_or_b32_e32 v5, v5, v6
	v_lshlrev_b32_e32 v6, 18, v71
	v_lshlrev_b32_e32 v14, 10, v15
	v_or_b32_e32 v7, v7, v11
	v_lshlrev_b32_e32 v11, 14, v12
	v_or_b32_e32 v5, v5, v6
	v_lshlrev_b32_e32 v6, 20, v74
	v_or_b32_e32 v10, v10, v14
	v_or_b32_e32 v7, v7, v11
	v_lshlrev_b32_e32 v9, 20, v9
	v_or_b32_e32 v5, v5, v73
	v_or_b32_e32 v4, v4, v6
	v_lshlrev_b32_e32 v6, 30, v36
	v_or_b32_e32 v10, v10, v16
	v_lshlrev_b32_e32 v8, 22, v8
	v_or_b32_e32 v7, v7, v9
	v_and_b32_e32 v9, 0x80000000, v13
	v_or_b32_e32 v5, v5, v6
	v_or_b32_e32 v4, v4, v25
	v_lshlrev_b32_e32 v6, 28, v19
	v_or_b32_e32 v8, v10, v8
	v_lshl_or_b32 v9, v17, 26, v9
	v_or_b32_e32 v7, v7, v9
	v_or_b32_e32 v6, v8, v6
	s_mov_b64 s[98:99], exec
	s_andn2_b64 exec, s[98:99], s[100:101]
	global_store_dwordx4 v[32:33], v[2:5], off
	global_store_dwordx2 v[32:33], v[6:7], off offset:64
	s_and_b64 exec, s[98:99], s[100:101]
	global_store_dwordx2 v[32:33], v[2:3], off offset:72
	global_store_dwordx4 v[32:33], v[4:7], off offset:128
	s_mov_b64 exec, s[98:99]
	s_and_saveexec_b64 s[4:5], s[0:1]
	s_cbranch_execz .LBB0_37
	v_mul_f32_e32 v4, 0x3e088889, v24
	v_lshl_add_u64 v[2:3], v[30:31], 2, s[52:53]
	v_cndmask_b32_e32 v4, 1.0, v4, vcc
	global_store_dword v[2:3], v4, off
	s_branch .LBB0_37

.LBB0_45:
	s_or_b64 exec, exec, s[14:15]
	v_mov_b32_e32 v2, v205
	v_mov_b32_e32 v1, v205
	s_add_u32 s28, s26, 0x1420000
	v_ashrrev_i32_e32 v1, 6, v1
	v_add_u32_e32 v1, s21, v1
	s_movk_i32 s0, 0x2000
	s_addc_u32 s29, s27, 0
	v_cmp_gt_i32_e32 vcc, s0, v1
	s_and_saveexec_b64 s[14:15], vcc
	s_cbranch_execz .LBB0_50
	v_and_b32_e32 v7, 31, v2
	v_bfe_u32 v6, v2, 5, 1
	v_lshlrev_b32_e32 v2, 4, v7
	v_mov_b32_e32 v3, 0
	v_lshl_add_u64 v[4:5], s[8:9], 0, v[2:3]
	s_mov_b64 s[0:1], 0x4000000
	v_lshl_add_u64 v[26:27], v[4:5], 0, s[0:1]
	v_mbcnt_hi_u32_b32 v4, -1, v207
	v_and_b32_e32 v2, 64, v4
	v_add_u32_e32 v5, 64, v2
	v_and_b32_e32 v2, 1, v7
	v_cmp_eq_u32_e64 s[100:101], 1, v2
	v_bfe_u32 v2, v7, 1, 2
	v_lshlrev_b32_e32 v2, 4, v2
	v_lshrrev_b32_e32 v3, 3, v7
	v_mul_u32_u24_e32 v3, 0x300000, v3
	v_add_u32_e32 v2, v2, v3
	v_mov_b32_e32 v3, 0
	v_lshl_add_u64 v[2:3], s[26:27], 0, v[2:3]
	s_mov_b64 s[0:1], 0x2800000
	v_lshl_add_u64 v[28:29], v[2:3], 0, s[0:1]
	v_xor_b32_e32 v2, 16, v4
	v_cmp_lt_i32_e32 vcc, v2, v5
	v_cmp_eq_u32_e64 s[0:1], 0, v7
	s_lshl_b32 s17, s19, 2
	v_cndmask_b32_e32 v2, v4, v2, vcc
	v_lshlrev_b32_e32 v38, 2, v2
	v_xor_b32_e32 v2, 8, v4
	v_cmp_lt_i32_e32 vcc, v2, v5
	v_lshl_or_b32 v30, v1, 1, v6
	s_lshl_b32 s20, s3, 4
	v_cndmask_b32_e32 v2, v4, v2, vcc
	v_lshlrev_b32_e32 v39, 2, v2
	v_xor_b32_e32 v2, 4, v4
	v_cmp_lt_i32_e32 vcc, v2, v5
	s_mov_b64 s[8:9], 0
	s_movk_i32 s30, 0xc0
	v_cndmask_b32_e32 v2, v4, v2, vcc
	v_lshlrev_b32_e32 v40, 2, v2
	v_xor_b32_e32 v2, 2, v4
	v_cmp_lt_i32_e32 vcc, v2, v5
	s_mov_b32 s31, 0x40f00000
	s_mov_b32 s16, 0x41000000
	v_cndmask_b32_e32 v2, v4, v2, vcc
	v_lshlrev_b32_e32 v41, 2, v2
	v_xor_b32_e32 v2, 1, v4
	v_cmp_lt_i32_e32 vcc, v2, v5
	s_mov_b32 s18, 0x41800000
	s_movk_i32 s34, 0x1fff
	v_cndmask_b32_e32 v2, v4, v2, vcc
	v_lshlrev_b32_e32 v42, 2, v2
	s_branch .LBB0_48

.LBB0_48:
	v_ashrrev_i32_e32 v31, 31, v30
	v_lshlrev_b64 v[2:3], 12, v[30:31]
	v_lshl_add_u64 v[10:11], v[26:27], 0, v[2:3]
	global_load_dwordx4 v[2:5], v[10:11], off offset:1024
	global_load_dwordx4 v[22:25], v[10:11], off offset:1536
	global_load_dwordx4 v[6:9], v[10:11], off offset:2048
	global_load_dwordx4 v[44:47], v[10:11], off
	global_load_dwordx4 v[48:51], v[10:11], off offset:512
	global_load_dwordx4 v[18:21], v[10:11], off offset:2560
	global_load_dwordx4 v[14:17], v[10:11], off offset:3072
	s_nop 0
	global_load_dwordx4 v[10:13], v[10:11], off offset:3584
	s_waitcnt vmcnt(7)
	v_max_f32_e64 v32, |v5|, |v5|
	v_max_f32_e64 v33, |v4|, |v4|
	s_waitcnt vmcnt(6)
	v_max_f32_e64 v34, |v25|, |v25|
	v_max_f32_e64 v35, |v24|, |v24|
	s_waitcnt vmcnt(5)
	v_max_f32_e64 v36, |v7|, |v7|
	v_max_f32_e64 v37, |v6|, |v6|
	s_waitcnt vmcnt(4)
	v_max_f32_e64 v43, |v45|, |v45|
	v_max_f32_e64 v52, |v44|, |v44|
	v_max_f32_e64 v53, |v47|, |v47|
	v_max_f32_e64 v54, |v46|, |v46|
	s_waitcnt vmcnt(3)
	v_max_f32_e64 v55, |v49|, |v49|
	v_max_f32_e64 v56, |v48|, |v48|
	v_max_f32_e64 v57, |v51|, |v51|
	v_max_f32_e64 v58, |v50|, |v50|
	v_max_f32_e32 v32, v33, v32
	v_max_f32_e32 v33, v35, v34
	v_max_f32_e32 v34, v37, v36
	v_max_f32_e32 v35, v52, v43
	v_max_f32_e32 v36, v54, v53
	v_max_f32_e64 v59, |v3|, |v3|
	v_max_f32_e64 v60, |v2|, |v2|
	v_max_f32_e32 v37, v56, v55
	v_max_f32_e32 v43, v58, v57
	v_max3_f32 v35, v35, 0, v36
	v_max_f32_e64 v61, |v23|, |v23|
	v_max_f32_e64 v62, |v22|, |v22|
	v_max_f32_e32 v52, v60, v59
	v_max3_f32 v35, v35, v37, v43
	v_max_f32_e64 v63, |v9|, |v9|
	v_max_f32_e64 v64, |v8|, |v8|
	v_max_f32_e32 v53, v62, v61
	v_max3_f32 v32, v35, v52, v32
	s_waitcnt vmcnt(2)
	v_max_f32_e64 v65, |v19|, |v19|
	v_max_f32_e64 v66, |v18|, |v18|
	v_max_f32_e64 v67, |v21|, |v21|
	v_max_f32_e64 v68, |v20|, |v20|
	v_max_f32_e32 v54, v64, v63
	v_max3_f32 v32, v32, v53, v33
	s_waitcnt vmcnt(1)
	v_max_f32_e64 v69, |v15|, |v15|
	v_max_f32_e64 v70, |v14|, |v14|
	v_max_f32_e64 v71, |v17|, |v17|
	v_max_f32_e64 v72, |v16|, |v16|
	v_max_f32_e32 v55, v66, v65
	v_max_f32_e32 v56, v68, v67
	v_max3_f32 v32, v32, v34, v54
	s_waitcnt vmcnt(0)
	v_max_f32_e64 v73, |v11|, |v11|
	v_max_f32_e64 v74, |v10|, |v10|
	v_max_f32_e64 v75, |v13|, |v13|
	v_max_f32_e64 v76, |v12|, |v12|
	v_max_f32_e32 v57, v70, v69
	v_max_f32_e32 v58, v72, v71
	v_max3_f32 v32, v32, v55, v56
	v_max_f32_e32 v59, v74, v73
	v_max_f32_e32 v60, v76, v75
	v_max3_f32 v32, v32, v57, v58
	v_max3_f32 v32, v32, v59, v60
	ds_bpermute_b32 v33, v38, v32
	v_mov_b32_e32 v36, v22
	v_mov_b32_e32 v37, v8
	v_mov_b32_e32 v8, v23
	v_mov_b32_e32 v52, v45
	s_waitcnt lgkmcnt(0)
	v_max_f32_e32 v33, v33, v33
	v_max_f32_e32 v32, v32, v33
	ds_bpermute_b32 v33, v39, v32
	v_mov_b32_e32 v53, v50
	v_mov_b32_e32 v50, v46
	v_mov_b32_e32 v46, v47
	v_mov_b32_e32 v47, v2
	s_waitcnt lgkmcnt(0)
	v_max_f32_e32 v33, v33, v33
	v_max_f32_e32 v34, v32, v33
	ds_bpermute_b32 v35, v40, v34
	v_mov_b32_e32 v2, v48
	v_mad_i64_i32 v[32:33], s[4:5], v30, s30, v[28:29]
	s_waitcnt lgkmcnt(0)
	v_max_f32_e32 v35, v35, v35
	v_max_f32_e32 v34, v34, v35
	ds_bpermute_b32 v35, v41, v34
	s_waitcnt lgkmcnt(0)
	v_max_f32_e32 v35, v35, v35
	v_max_f32_e32 v35, v34, v35
	ds_bpermute_b32 v43, v42, v35
	v_mov_b32_e32 v34, v24
	s_waitcnt lgkmcnt(0)
	v_max_f32_e32 v22, v43, v43
	v_max_f32_e32 v24, v35, v22
	v_div_scale_f32 v22, s[4:5], v24, v24, s31
	v_rcp_f32_e32 v23, v22
	v_mov_b32_e32 v35, v18
	v_div_scale_f32 v18, vcc, s31, v24, s31
	v_fma_f32 v43, -v22, v23, 1.0
	v_fmac_f32_e32 v23, v43, v23
	v_mul_f32_e32 v43, v18, v23
	v_fma_f32 v45, -v22, v43, v18
	v_fmac_f32_e32 v43, v45, v23
	v_fma_f32 v18, -v22, v43, v18
	v_div_fmas_f32 v18, v18, v23, v43
	v_div_fixup_f32 v18, v18, v24, s31
	v_cmp_lt_f32_e32 vcc, 0, v24
	s_nop 1
	v_cndmask_b32_e32 v18, 1.0, v18, vcc
	v_mul_f32_e32 v22, v44, v18
	v_pk_mul_f32 v[56:57], v[2:3], v[18:19] op_sel_hi:[1,0]
	v_min_f32_e64 v2, |v22|, s31
	v_mul_f32_e32 v43, 4.0, v2
	v_mul_f32_e32 v23, 0x41000000, v2
	v_add_f32_e32 v44, v2, v2
	v_rndne_f32_e32 v43, v43
	v_rndne_f32_e32 v23, v23
	v_rndne_f32_e32 v44, v44
	v_add_f32_e32 v43, 0x41000000, v43
	v_cmp_nle_f32_e64 s[4:5], 2.0, v2
	v_add_f32_e32 v44, 0x41800000, v44
	v_pk_mul_f32 v[54:55], v[46:47], v[18:19] op_sel_hi:[1,0]
	v_cndmask_b32_e64 v23, v43, v23, s[4:5]
	v_cmp_nle_f32_e64 s[4:5], 4.0, v2
	v_pk_mul_f32 v[52:53], v[52:53], v[18:19] op_sel_hi:[1,0]
	v_min_f32_e64 v67, |v54|, s31
	v_cndmask_b32_e64 v2, v44, v23, s[4:5]
	v_cvt_u32_f32_e32 v2, v2
	v_lshrrev_b32_e32 v3, 26, v22
	v_min_f32_e64 v22, |v52|, s31
	v_mul_f32_e32 v61, 0x41000000, v67
	v_add_f32_e32 v47, v22, v22
	v_rndne_f32_e32 v69, v61
	v_min_f32_e64 v61, |v53|, s31
	v_rndne_f32_e32 v48, v47
	v_min_u32_e32 v2, 31, v2
	v_mul_f32_e32 v47, 0x41000000, v61
	v_mul_f32_e32 v46, 4.0, v22
	v_and_or_b32 v43, v3, 32, v2
	v_mul_f32_e32 v3, v49, v18
	v_rndne_f32_e32 v49, v47
	v_mul_f32_e32 v47, 4.0, v61
	v_mul_f32_e32 v45, 0x41000000, v22
	v_rndne_f32_e32 v46, v46
	v_rndne_f32_e32 v47, v47
	v_rndne_f32_e32 v45, v45
	v_pk_add_f32 v[46:47], v[46:47], s[16:17] op_sel_hi:[1,0]
	v_cmp_nle_f32_e64 s[4:5], 2.0, v22
	v_pk_mul_f32 v[50:51], v[50:51], v[18:19] op_sel_hi:[1,0]
	v_min_f32_e64 v44, |v3|, s31
	v_cndmask_b32_e64 v45, v46, v45, s[4:5]
	v_cmp_nle_f32_e64 s[4:5], 2.0, v61
	v_add_f32_e32 v46, v61, v61
	v_min_f32_e64 v63, |v50|, s31
	v_cndmask_b32_e64 v72, v47, v49, s[4:5]
	v_rndne_f32_e32 v49, v46
	v_pk_add_f32 v[46:47], v[48:49], s[18:19] op_sel_hi:[1,0]
	v_cmp_nle_f32_e64 s[4:5], 4.0, v61
	v_mul_f32_e32 v58, 0x41000000, v63
	v_mul_f32_e32 v59, 4.0, v63
	v_cndmask_b32_e64 v47, v47, v72, s[4:5]
	v_cmp_nle_f32_e64 s[4:5], 4.0, v22
	v_rndne_f32_e32 v65, v58
	v_rndne_f32_e32 v58, v59
	v_cndmask_b32_e64 v22, v46, v45, s[4:5]
	v_cvt_u32_f32_e32 v46, v47
	v_cvt_u32_f32_e32 v47, v22
	v_lshrrev_b32_e32 v45, 26, v3
	v_add_f32_e32 v59, v44, v44
	v_min_u32_e32 v3, 31, v46
	v_lshrrev_b32_e32 v46, 26, v53
	v_min_f32_e64 v53, |v51|, s31
	v_and_b32_e32 v49, 32, v46
	v_mul_f32_e32 v46, 0x41000000, v53
	v_rndne_f32_e32 v61, v46
	v_mul_f32_e32 v46, 4.0, v53
	v_rndne_f32_e32 v22, v59
	v_min_u32_e32 v48, 31, v47
	v_lshrrev_b32_e32 v47, 26, v52
	v_rndne_f32_e32 v59, v46
	v_and_b32_e32 v52, 32, v47
	v_pk_add_f32 v[46:47], v[58:59], s[16:17] op_sel_hi:[1,0]
	v_cmp_nle_f32_e64 s[4:5], 2.0, v63
	v_add_f32_e32 v60, v63, v63
	v_rndne_f32_e32 v60, v60
	v_cndmask_b32_e64 v58, v46, v65, s[4:5]
	v_cmp_nle_f32_e64 s[4:5], 2.0, v53
	v_add_f32_e32 v46, v53, v53
	v_or_b32_e32 v3, v3, v49
	v_cndmask_b32_e64 v59, v47, v61, s[4:5]
	v_rndne_f32_e32 v61, v46
	v_pk_add_f32 v[46:47], v[60:61], s[18:19] op_sel_hi:[1,0]
	v_cmp_nle_f32_e64 s[4:5], 4.0, v53
	v_lshrrev_b32_e32 v49, 26, v50
	v_mul_f32_e32 v62, 4.0, v67
	v_cndmask_b32_e64 v47, v47, v59, s[4:5]
	v_cmp_nle_f32_e64 s[4:5], 4.0, v63
	v_rndne_f32_e32 v62, v62
	v_cvt_u32_f32_e32 v47, v47
	v_cndmask_b32_e64 v46, v46, v58, s[4:5]
	v_cvt_u32_f32_e32 v53, v46
	v_or_b32_e32 v46, v48, v52
	v_lshrrev_b32_e32 v48, 26, v51
	v_and_b32_e32 v50, 32, v48
	v_min_u32_e32 v52, 31, v53
	v_min_f32_e64 v53, |v55|, s31
	v_mul_f32_e32 v48, 0x41000000, v53
	v_rndne_f32_e32 v58, v48
	v_mul_f32_e32 v48, 4.0, v53
	v_rndne_f32_e32 v63, v48
	v_and_b32_e32 v51, 32, v49
	v_pk_add_f32 v[48:49], v[62:63], s[16:17] op_sel_hi:[1,0]
	v_cmp_nle_f32_e64 s[4:5], 2.0, v67
	v_add_f32_e32 v64, v67, v67
	v_rndne_f32_e32 v64, v64
	v_cndmask_b32_e64 v59, v48, v69, s[4:5]
	v_add_f32_e32 v48, v53, v53
	v_cmp_nle_f32_e64 s[4:5], 2.0, v53
	v_rndne_f32_e32 v65, v48
	v_min_u32_e32 v47, 31, v47
	v_cndmask_b32_e64 v58, v49, v58, s[4:5]
	v_pk_add_f32 v[48:49], v[64:65], s[18:19] op_sel_hi:[1,0]
	v_cmp_nle_f32_e64 s[4:5], 4.0, v53
	v_min_f32_e64 v70, |v56|, s31
	v_mul_f32_e32 v2, 0x41000000, v70
	v_cndmask_b32_e64 v49, v49, v58, s[4:5]
	v_cvt_u32_f32_e32 v53, v49
	v_or_b32_e32 v49, v47, v50
	v_or_b32_e32 v50, v52, v51
	v_lshrrev_b32_e32 v51, 26, v55
	v_lshrrev_b32_e32 v52, 26, v54
	v_min_f32_e64 v55, |v57|, s31
	v_and_b32_e32 v54, 32, v52
	v_mul_f32_e32 v52, 0x41000000, v55
	v_rndne_f32_e32 v71, v2
	v_mul_f32_e32 v2, 4.0, v70
	v_rndne_f32_e32 v58, v52
	v_mul_f32_e32 v52, 4.0, v55
	v_rndne_f32_e32 v66, v2
	v_cmp_nle_f32_e64 s[4:5], 4.0, v67
	v_rndne_f32_e32 v67, v52
	v_min_u32_e32 v47, 31, v53
	v_cndmask_b32_e64 v48, v48, v59, s[4:5]
	v_pk_add_f32 v[52:53], v[66:67], s[16:17] op_sel_hi:[1,0]
	v_cmp_nle_f32_e64 s[4:5], 2.0, v70
	v_add_f32_e32 v2, v70, v70
	v_rndne_f32_e32 v68, v2
	v_cndmask_b32_e64 v59, v52, v71, s[4:5]
	v_add_f32_e32 v52, v55, v55
	v_cmp_nle_f32_e64 s[4:5], 2.0, v55
	v_rndne_f32_e32 v69, v52
	v_cvt_u32_f32_e32 v48, v48
	v_cndmask_b32_e64 v58, v53, v58, s[4:5]
	v_pk_add_f32 v[52:53], v[68:69], s[18:19] op_sel_hi:[1,0]
	v_cmp_nle_f32_e64 s[4:5], 4.0, v55
	v_mul_f32_e32 v5, v5, v18
	v_min_u32_e32 v48, 31, v48
	v_cndmask_b32_e64 v53, v53, v58, s[4:5]
	v_cvt_u32_f32_e32 v53, v53
	v_and_b32_e32 v51, 32, v51
	v_min_f32_e64 v55, |v5|, s31
	v_or_b32_sdwa v47, v47, v51 dst_sel:WORD_1 dst_unused:UNUSED_PAD src0_sel:DWORD src1_sel:DWORD
	v_or_b32_e32 v51, v48, v54
	v_min_u32_e32 v48, 31, v53
	v_lshrrev_b32_e32 v53, 26, v57
	v_mul_f32_e32 v57, 4.0, v55
	v_cmp_nle_f32_e64 s[4:5], 4.0, v70
	v_lshrrev_b32_e32 v54, 26, v56
	v_mul_f32_e32 v56, 0x41000000, v55
	v_rndne_f32_e32 v57, v57
	v_cndmask_b32_e64 v52, v52, v59, s[4:5]
	v_rndne_f32_e32 v56, v56
	v_add_f32_e32 v57, 0x41000000, v57
	v_cmp_nle_f32_e64 s[4:5], 2.0, v55
	v_cvt_u32_f32_e32 v52, v52
	v_and_b32_e32 v53, 32, v53
	v_cndmask_b32_e64 v56, v57, v56, s[4:5]
	v_add_f32_e32 v57, v55, v55
	v_rndne_f32_e32 v57, v57
	v_add_f32_e32 v57, 0x41800000, v57
	v_cmp_nle_f32_e64 s[4:5], 4.0, v55
	v_min_u32_e32 v52, 31, v52
	v_and_b32_e32 v54, 32, v54
	v_cndmask_b32_e64 v55, v57, v56, s[4:5]
	v_cvt_u32_f32_e32 v55, v55
	v_or_b32_e32 v66, v48, v53
	v_or_b32_sdwa v48, v52, v54 dst_sel:BYTE_3 dst_unused:UNUSED_PAD src0_sel:DWORD src1_sel:DWORD
	v_lshrrev_b32_e32 v5, 26, v5
	v_min_u32_e32 v52, 31, v55
	v_pk_mul_f32 v[36:37], v[36:37], v[18:19] op_sel_hi:[1,0]
	v_and_or_b32 v67, v5, 32, v52
	v_min_f32_e64 v5, |v36|, s31
	v_pk_mul_f32 v[8:9], v[8:9], v[18:19] op_sel_hi:[1,0]
	v_add_f32_e32 v53, v5, v5
	v_min_f32_e64 v61, |v8|, s31
	v_rndne_f32_e32 v54, v53
	v_mul_f32_e32 v53, 0x41000000, v61
	v_rndne_f32_e32 v59, v53
	v_mul_f32_e32 v53, 4.0, v61
	v_pk_mul_f32 v[34:35], v[34:35], v[18:19] op_sel_hi:[1,0]
	v_rndne_f32_e32 v56, v53
	v_add_f32_e32 v53, v61, v61
	v_min_f32_e64 v64, |v34|, s31
	v_rndne_f32_e32 v58, v53
	v_mul_f32_e32 v53, 0x41000000, v64
	v_rndne_f32_e32 v63, v53
	v_mul_f32_e32 v53, 4.0, v64
	v_mul_f32_e32 v25, v25, v18
	v_rndne_f32_e32 v60, v53
	v_min_f32_e64 v53, |v25|, s31
	v_mul_f32_e32 v62, 4.0, v53
	v_mul_f32_e32 v57, 0x41000000, v53
	v_rndne_f32_e32 v62, v62
	v_rndne_f32_e32 v57, v57
	v_add_f32_e32 v62, 0x41000000, v62
	v_cmp_nle_f32_e64 s[4:5], 2.0, v53
	v_mul_f32_e32 v6, v6, v18
	v_mul_f32_e32 v52, 0x41000000, v5
	v_cndmask_b32_e64 v57, v62, v57, s[4:5]
	v_add_f32_e32 v62, v53, v53
	v_rndne_f32_e32 v62, v62
	v_add_f32_e32 v62, 0x41800000, v62
	v_cmp_nle_f32_e64 s[4:5], 4.0, v53
	v_rndne_f32_e32 v55, v52
	v_mul_f32_e32 v52, 4.0, v5
	v_cndmask_b32_e64 v53, v62, v57, s[4:5]
	v_min_f32_e64 v57, |v6|, s31
	v_mul_f32_e32 v65, 4.0, v57
	v_mul_f32_e32 v62, 0x41000000, v57
	v_rndne_f32_e32 v65, v65
	v_rndne_f32_e32 v62, v62
	v_add_f32_e32 v65, 0x41000000, v65
	v_cmp_nle_f32_e64 s[4:5], 2.0, v57
	v_cvt_u32_f32_e32 v53, v53
	v_rndne_f32_e32 v52, v52
	v_cndmask_b32_e64 v62, v65, v62, s[4:5]
	v_add_f32_e32 v65, v57, v57
	v_rndne_f32_e32 v65, v65
	v_add_f32_e32 v65, 0x41800000, v65
	v_cmp_nle_f32_e64 s[4:5], 4.0, v57
	v_min_u32_e32 v68, 31, v53
	v_lshrrev_b32_e32 v36, 26, v36
	v_cndmask_b32_e64 v57, v65, v62, s[4:5]
	v_min_f32_e64 v65, |v37|, s31
	v_mul_f32_e32 v53, 0x41000000, v65
	v_rndne_f32_e32 v69, v53
	v_mul_f32_e32 v53, 4.0, v65
	v_rndne_f32_e32 v53, v53
	v_pk_add_f32 v[52:53], v[52:53], s[16:17] op_sel_hi:[1,0]
	v_cmp_nle_f32_e64 s[4:5], 2.0, v5
	v_cvt_u32_f32_e32 v57, v57
	v_lshrrev_b32_e32 v6, 26, v6
	v_cndmask_b32_e64 v70, v52, v55, s[4:5]
	v_add_f32_e32 v52, v65, v65
	v_cmp_nle_f32_e64 s[4:5], 2.0, v65
	v_rndne_f32_e32 v55, v52
	v_min_u32_e32 v57, 31, v57
	v_cndmask_b32_e64 v69, v53, v69, s[4:5]
	v_pk_add_f32 v[52:53], v[54:55], s[18:19] op_sel_hi:[1,0]
	v_min_f32_e64 v55, |v9|, s31
	v_and_b32_e32 v54, 32, v36
	v_mul_f32_e32 v36, 0x41000000, v55
	v_cmp_nle_f32_e64 s[4:5], 4.0, v65
	v_rndne_f32_e32 v65, v36
	v_mul_f32_e32 v36, 4.0, v55
	v_cndmask_b32_e64 v53, v53, v69, s[4:5]
	v_cmp_nle_f32_e64 s[4:5], 4.0, v5
	v_and_or_b32 v6, v6, 32, v57
	v_lshrrev_b32_e32 v37, 26, v37
	v_rndne_f32_e32 v57, v36
	v_cndmask_b32_e64 v5, v52, v70, s[4:5]
	v_cvt_u32_f32_e32 v52, v53
	v_and_b32_e32 v53, 32, v37
	v_pk_add_f32 v[36:37], v[56:57], s[16:17] op_sel_hi:[1,0]
	v_cmp_nle_f32_e64 s[4:5], 2.0, v61
	v_cvt_u32_f32_e32 v5, v5
	v_min_u32_e32 v52, 31, v52
	v_cndmask_b32_e64 v56, v36, v59, s[4:5]
	v_add_f32_e32 v36, v55, v55
	v_cmp_nle_f32_e64 s[4:5], 2.0, v55
	v_rndne_f32_e32 v59, v36
	v_or_b32_e32 v69, v52, v53
	v_cndmask_b32_e64 v57, v37, v65, s[4:5]
	v_pk_add_f32 v[36:37], v[58:59], s[18:19] op_sel_hi:[1,0]
	v_cmp_nle_f32_e64 s[4:5], 4.0, v55
	v_lshrrev_b32_e32 v8, 26, v8
	v_min_f32_e64 v53, |v35|, s31
	v_cndmask_b32_e64 v37, v37, v57, s[4:5]
	v_cvt_u32_f32_e32 v37, v37
	v_min_u32_e32 v5, 31, v5
	v_and_b32_e32 v52, 32, v8
	v_mul_f32_e32 v8, 0x41000000, v53
	v_or_b32_e32 v70, v5, v54
	v_rndne_f32_e32 v54, v8
	v_mul_f32_e32 v8, 4.0, v53
	v_cmp_nle_f32_e64 s[4:5], 4.0, v61
	v_lshrrev_b32_e32 v9, 26, v9
	v_rndne_f32_e32 v61, v8
	v_cndmask_b32_e64 v36, v36, v56, s[4:5]
	v_min_u32_e32 v5, 31, v37
	v_and_b32_e32 v37, 32, v9
	v_pk_add_f32 v[8:9], v[60:61], s[16:17] op_sel_hi:[1,0]
	v_cmp_nle_f32_e64 s[4:5], 2.0, v64
	v_add_f32_e32 v62, v64, v64
	v_rndne_f32_e32 v62, v62
	v_cndmask_b32_e64 v55, v8, v63, s[4:5]
	v_add_f32_e32 v8, v53, v53
	v_cmp_nle_f32_e64 s[4:5], 2.0, v53
	v_rndne_f32_e32 v63, v8
	v_or_b32_e32 v71, v5, v37
	v_cndmask_b32_e64 v54, v9, v54, s[4:5]
	v_pk_add_f32 v[8:9], v[62:63], s[18:19] op_sel_hi:[1,0]
	v_cmp_nle_f32_e64 s[4:5], 4.0, v53
	v_lshrrev_b32_e32 v34, 26, v34
	v_and_b32_e32 v34, 32, v34
	v_cndmask_b32_e64 v9, v9, v54, s[4:5]
	v_cmp_nle_f32_e64 s[4:5], 4.0, v64
	v_cvt_u32_f32_e32 v9, v9
	v_cvt_u32_f32_e32 v36, v36
	v_cndmask_b32_e64 v8, v8, v55, s[4:5]
	v_cvt_u32_f32_e32 v8, v8
	v_min_u32_e32 v5, 31, v9
	v_lshrrev_b32_e32 v9, 26, v35
	v_and_b32_e32 v9, 32, v9
	v_min_u32_e32 v8, 31, v8
	v_or_b32_sdwa v73, v5, v9 dst_sel:BYTE_3 dst_unused:UNUSED_PAD src0_sel:DWORD src1_sel:DWORD
	v_or_b32_e32 v74, v8, v34
	v_mov_b32_e32 v8, v19
	v_mov_b32_e32 v9, v16
	v_pk_mul_f32 v[8:9], v[8:9], v[18:19] op_sel_hi:[1,0]
	v_mov_b32_e32 v16, v20
	v_min_f32_e64 v19, |v8|, s31
	v_mul_f32_e32 v5, 0x41000000, v19
	v_rndne_f32_e32 v37, v5
	v_mul_f32_e32 v5, 4.0, v19
	v_pk_mul_f32 v[16:17], v[16:17], v[18:19] op_sel_hi:[1,0]
	v_min_u32_e32 v36, 31, v36
	v_rndne_f32_e32 v34, v5
	v_add_f32_e32 v5, v19, v19
	v_min_f32_e64 v57, |v16|, s31
	v_or_b32_e32 v72, v36, v52
	v_rndne_f32_e32 v36, v5
	v_mul_f32_e32 v5, 0x41000000, v57
	v_mov_b32_e32 v54, v21
	v_mov_b32_e32 v55, v10
	v_rndne_f32_e32 v53, v5
	v_mul_f32_e32 v5, 4.0, v57
	v_pk_mul_f32 v[54:55], v[54:55], v[18:19] op_sel_hi:[1,0]
	v_rndne_f32_e32 v20, v5
	v_add_f32_e32 v5, v57, v57
	v_min_f32_e64 v61, |v54|, s31
	v_rndne_f32_e32 v52, v5
	v_mul_f32_e32 v5, 0x41000000, v61
	v_rndne_f32_e32 v65, v5
	v_mul_f32_e32 v5, 4.0, v61
	v_rndne_f32_e32 v10, v5
	v_add_f32_e32 v5, v61, v61
	v_rndne_f32_e32 v56, v5
	v_mov_b32_e32 v58, v11
	v_mov_b32_e32 v59, v12
	v_mov_b32_e32 v5, v14
	v_pk_mov_b32 v[58:59], v[4:5], v[58:59] op_sel:[1,0]
	v_mov_b32_e32 v62, v15
	v_pk_mul_f32 v[58:59], v[58:59], v[18:19] op_sel_hi:[1,0]
	v_mov_b32_e32 v63, v12
	v_min_f32_e64 v5, |v58|, s31
	v_mul_f32_e32 v11, 0x41000000, v5
	v_rndne_f32_e32 v75, v11
	v_mul_f32_e32 v11, 4.0, v5
	v_pk_mul_f32 v[62:63], v[62:63], v[18:19] op_sel_hi:[1,0]
	v_rndne_f32_e32 v14, v11
	v_add_f32_e32 v11, v5, v5
	v_min_f32_e64 v12, |v62|, s31
	v_rndne_f32_e32 v60, v11
	v_mul_f32_e32 v11, 0x41000000, v12
	v_rndne_f32_e32 v76, v11
	v_mul_f32_e32 v11, 4.0, v12
	v_rndne_f32_e32 v64, v11
	v_min_f32_e64 v11, |v9|, s31
	v_mul_f32_e32 v21, 4.0, v11
	v_rndne_f32_e32 v35, v21
	v_pk_add_f32 v[34:35], v[34:35], s[16:17] op_sel_hi:[1,0]
	v_cmp_nle_f32_e64 s[4:5], 2.0, v19
	v_mul_f32_e32 v15, 0x41000000, v11
	v_rndne_f32_e32 v15, v15
	v_cndmask_b32_e64 v21, v34, v37, s[4:5]
	v_add_f32_e32 v34, v11, v11
	v_cmp_nle_f32_e64 s[4:5], 2.0, v11
	v_rndne_f32_e32 v37, v34
	v_lshrrev_b32_e32 v8, 26, v8
	v_cndmask_b32_e64 v15, v35, v15, s[4:5]
	v_pk_add_f32 v[34:35], v[36:37], s[18:19] op_sel_hi:[1,0]
	v_cmp_nle_f32_e64 s[4:5], 4.0, v11
	v_lshrrev_b32_e32 v9, 26, v9
	v_mul_f32_e32 v13, v13, v18
	v_cndmask_b32_e64 v11, v35, v15, s[4:5]
	v_cmp_nle_f32_e64 s[4:5], 4.0, v19
	v_cvt_u32_f32_e32 v11, v11
	v_min_f32_e64 v35, |v17|, s31
	v_cndmask_b32_e64 v15, v34, v21, s[4:5]
	v_cvt_u32_f32_e32 v15, v15
	v_add_f32_e32 v19, v12, v12
	v_rndne_f32_e32 v34, v19
	v_min_u32_e32 v19, 31, v11
	v_min_u32_e32 v36, 31, v15
	v_and_b32_e32 v15, 32, v8
	v_mul_f32_e32 v8, 0x41000000, v35
	v_rndne_f32_e32 v37, v8
	v_mul_f32_e32 v8, 4.0, v35
	v_rndne_f32_e32 v21, v8
	v_and_b32_e32 v11, 32, v9
	v_pk_add_f32 v[8:9], v[20:21], s[16:17] op_sel_hi:[1,0]
	v_cmp_nle_f32_e64 s[4:5], 2.0, v57
	v_mul_f32_e32 v2, 0x41000000, v44
	v_rndne_f32_e32 v23, v2
	v_cndmask_b32_e64 v20, v8, v53, s[4:5]
	v_add_f32_e32 v8, v35, v35
	v_cmp_nle_f32_e64 s[4:5], 2.0, v35
	v_rndne_f32_e32 v53, v8
	v_mul_f32_e32 v2, 4.0, v44
	v_cndmask_b32_e64 v21, v9, v37, s[4:5]
	v_pk_add_f32 v[8:9], v[52:53], s[18:19] op_sel_hi:[1,0]
	v_cmp_nle_f32_e64 s[4:5], 4.0, v35
	v_min_f32_e64 v37, |v55|, s31
	v_rndne_f32_e32 v2, v2
	v_cndmask_b32_e64 v9, v9, v21, s[4:5]
	v_cmp_nle_f32_e64 s[4:5], 4.0, v57
	v_cvt_u32_f32_e32 v9, v9
	v_or_b32_e32 v21, v36, v15
	v_cndmask_b32_e64 v8, v8, v20, s[4:5]
	v_cvt_u32_f32_e32 v8, v8
	v_min_u32_e32 v15, 31, v9
	v_lshrrev_b32_e32 v9, 26, v16
	v_or_b32_e32 v20, v19, v11
	v_min_u32_e32 v35, 31, v8
	v_lshrrev_b32_e32 v8, 26, v17
	v_and_b32_e32 v16, 32, v8
	v_mul_f32_e32 v8, 0x41000000, v37
	v_rndne_f32_e32 v52, v8
	v_mul_f32_e32 v8, 4.0, v37
	v_rndne_f32_e32 v11, v8
	v_and_b32_e32 v17, 32, v9
	v_pk_add_f32 v[8:9], v[10:11], s[16:17] op_sel_hi:[1,0]
	v_cmp_nle_f32_e64 s[4:5], 2.0, v61
	s_nop 1
	v_cndmask_b32_e64 v10, v8, v65, s[4:5]
	v_add_f32_e32 v8, v37, v37
	v_cmp_nle_f32_e64 s[4:5], 2.0, v37
	v_rndne_f32_e32 v57, v8
	s_nop 0
	v_cndmask_b32_e64 v11, v9, v52, s[4:5]
	v_pk_add_f32 v[8:9], v[56:57], s[18:19] op_sel_hi:[1,0]
	v_cmp_nle_f32_e64 s[4:5], 4.0, v37
	v_min_f32_e64 v52, |v59|, s31
	s_nop 0
	v_cndmask_b32_e64 v9, v9, v11, s[4:5]
	v_cmp_nle_f32_e64 s[4:5], 4.0, v61
	v_cvt_u32_f32_e32 v9, v9
	v_or_b32_e32 v11, v35, v17
	v_cndmask_b32_e64 v8, v8, v10, s[4:5]
	v_cvt_u32_f32_e32 v8, v8
	v_or_b32_e32 v10, v15, v16
	v_min_u32_e32 v16, 31, v9
	v_lshrrev_b32_e32 v9, 26, v54
	v_min_u32_e32 v17, 31, v8
	v_lshrrev_b32_e32 v8, 26, v55
	v_and_b32_e32 v35, 32, v8
	v_mul_f32_e32 v8, 0x41000000, v52
	v_rndne_f32_e32 v53, v8
	v_mul_f32_e32 v8, 4.0, v52
	v_rndne_f32_e32 v15, v8
	v_and_b32_e32 v37, 32, v9
	v_pk_add_f32 v[8:9], v[14:15], s[16:17] op_sel_hi:[1,0]
	v_cmp_nle_f32_e64 s[4:5], 2.0, v5
	v_lshlrev_b32_e32 v10, 2, v10
	v_lshlrev_b32_e32 v11, 4, v11
	v_cndmask_b32_e64 v14, v8, v75, s[4:5]
	v_add_f32_e32 v8, v52, v52
	v_cmp_nle_f32_e64 s[4:5], 2.0, v52
	v_rndne_f32_e32 v61, v8
	s_nop 0
	v_cndmask_b32_e64 v15, v9, v53, s[4:5]
	v_pk_add_f32 v[8:9], v[60:61], s[18:19] op_sel_hi:[1,0]
	v_cmp_nle_f32_e64 s[4:5], 4.0, v52
	v_min_f32_e64 v52, |v63|, s31
	s_nop 0
	v_cndmask_b32_e64 v9, v9, v15, s[4:5]
	v_cmp_nle_f32_e64 s[4:5], 4.0, v5
	v_or_b32_e32 v15, v17, v37
	s_nop 0
	v_cndmask_b32_e64 v5, v8, v14, s[4:5]
	v_cvt_u32_f32_e32 v8, v9
	v_or_b32_e32 v14, v16, v35
	v_cvt_u32_f32_e32 v5, v5
	v_lshrrev_b32_e32 v9, 26, v58
	v_min_u32_e32 v16, 31, v8
	v_lshrrev_b32_e32 v8, 26, v59
	v_and_b32_e32 v17, 32, v8
	v_mul_f32_e32 v8, 0x41000000, v52
	v_rndne_f32_e32 v35, v8
	v_mul_f32_e32 v8, 4.0, v52
	v_rndne_f32_e32 v65, v8
	v_and_b32_e32 v37, 32, v9
	v_pk_add_f32 v[8:9], v[64:65], s[16:17] op_sel_hi:[1,0]
	v_cmp_nle_f32_e64 s[4:5], 2.0, v12
	v_min_u32_e32 v5, 31, v5
	s_nop 0
	v_cndmask_b32_e64 v53, v8, v76, s[4:5]
	v_cmp_nle_f32_e64 s[4:5], 2.0, v52
	v_add_f32_e32 v8, v52, v52
	s_nop 0
	v_cndmask_b32_e64 v54, v9, v35, s[4:5]
	v_rndne_f32_e32 v35, v8
	v_pk_add_f32 v[8:9], v[34:35], s[18:19] op_sel_hi:[1,0]
	v_cmp_nle_f32_e64 s[4:5], 4.0, v52
	v_min_f32_e64 v34, |v13|, s31
	v_mul_f32_e32 v35, 0x41000000, v34
	v_cndmask_b32_e64 v9, v9, v54, s[4:5]
	v_cmp_nle_f32_e64 s[4:5], 4.0, v12
	v_or_b32_e32 v12, v16, v17
	v_or_b32_sdwa v16, v5, v37 dst_sel:WORD_1 dst_unused:UNUSED_PAD src0_sel:DWORD src1_sel:DWORD
	v_mul_f32_e32 v37, 4.0, v34
	v_rndne_f32_e32 v37, v37
	v_cndmask_b32_e64 v8, v8, v53, s[4:5]
	v_rndne_f32_e32 v35, v35
	v_add_f32_e32 v37, 0x41000000, v37
	v_cmp_nle_f32_e64 s[4:5], 2.0, v34
	v_cvt_u32_f32_e32 v9, v9
	v_cvt_u32_f32_e32 v8, v8
	v_cndmask_b32_e64 v35, v37, v35, s[4:5]
	v_add_f32_e32 v37, v34, v34
	v_rndne_f32_e32 v37, v37
	v_add_f32_e32 v37, 0x41800000, v37
	v_cmp_nle_f32_e64 s[4:5], 4.0, v34
	v_min_u32_e32 v5, 31, v9
	v_lshrrev_b32_e32 v9, 26, v63
	v_cndmask_b32_e64 v34, v37, v35, s[4:5]
	v_cvt_u32_f32_e32 v34, v34
	v_and_b32_e32 v9, 32, v9
	v_lshrrev_b32_e32 v17, 26, v62
	v_or_b32_e32 v9, v5, v9
	v_mov_b32_e32 v5, v7
	v_min_u32_e32 v8, 31, v8
	v_and_b32_e32 v17, 32, v17
	v_pk_mul_f32 v[4:5], v[4:5], v[18:19] op_sel_hi:[1,0]
	v_or_b32_e32 v8, v8, v17
	v_min_u32_e32 v17, 31, v34
	v_lshlrev_b32_e32 v34, 4, v3
	v_and_b32_e32 v3, 0x80000000, v25
	v_min_f32_e64 v7, |v4|, s31
	v_lshl_or_b32 v25, v68, 26, v3
	v_mul_f32_e32 v3, 0x41000000, v7
	v_rndne_f32_e32 v18, v3
	v_mul_f32_e32 v3, 4.0, v7
	v_rndne_f32_e32 v3, v3
	v_pk_add_f32 v[2:3], v[2:3], s[16:17] op_sel_hi:[1,0]
	v_cmp_nle_f32_e64 s[4:5], 2.0, v44
	v_lshlrev_b32_e32 v37, 10, v49
	v_lshrrev_b32_e32 v4, 26, v4
	v_cndmask_b32_e64 v52, v2, v23, s[4:5]
	v_cmp_nle_f32_e64 s[4:5], 2.0, v7
	v_add_f32_e32 v2, v7, v7
	v_rndne_f32_e32 v23, v2
	v_cndmask_b32_e64 v18, v3, v18, s[4:5]
	v_cmp_nle_f32_e64 s[4:5], 4.0, v7
	v_min_f32_e64 v7, |v5|, s31
	v_pk_add_f32 v[2:3], v[22:23], s[18:19] op_sel_hi:[1,0]
	v_mul_f32_e32 v22, 4.0, v7
	v_cndmask_b32_e64 v3, v3, v18, s[4:5]
	v_cmp_nle_f32_e64 s[4:5], 4.0, v44
	v_mul_f32_e32 v18, 0x41000000, v7
	v_rndne_f32_e32 v22, v22
	v_cndmask_b32_e64 v2, v2, v52, s[4:5]
	v_rndne_f32_e32 v18, v18
	v_add_f32_e32 v22, 0x41000000, v22
	v_cmp_nle_f32_e64 s[4:5], 2.0, v7
	v_cvt_u32_f32_e32 v2, v2
	v_cvt_u32_f32_e32 v3, v3
	v_cndmask_b32_e64 v18, v22, v18, s[4:5]
	v_add_f32_e32 v22, v7, v7
	v_rndne_f32_e32 v22, v22
	v_add_f32_e32 v22, 0x41800000, v22
	v_cmp_nle_f32_e64 s[4:5], 4.0, v7
	v_min_u32_e32 v2, 31, v2
	v_lshrrev_b32_e32 v5, 26, v5
	v_cndmask_b32_e64 v7, v22, v18, s[4:5]
	v_cvt_u32_f32_e32 v7, v7
	v_and_or_b32 v18, v45, 32, v2
	v_and_b32_e32 v5, 32, v5
	v_lshlrev_b32_e32 v35, 6, v46
	v_min_u32_e32 v7, 31, v7
	v_or_b32_e32 v5, v7, v5
	v_lshrrev_b32_e32 v7, 2, v18
	v_or_b32_e32 v7, v34, v7
	v_min_u32_e32 v3, 31, v3
	v_and_b32_e32 v4, 32, v4
	v_or_b32_e32 v7, v7, v37
	v_lshlrev_b32_e32 v46, 12, v50
	v_lshlrev_b32_e32 v50, 22, v66
	v_or_b32_e32 v4, v3, v4
	v_or_b32_e32 v18, v35, v43
	v_or_b32_e32 v7, v7, v47
	v_lshlrev_b32_e32 v49, 18, v51
	v_lshlrev_b32_e32 v51, 2, v67
	v_or_b32_e32 v18, v18, v46
	v_or_b32_e32 v7, v7, v50
	v_lshlrev_b32_e32 v3, 28, v3
	v_lshrrev_b32_e32 v4, 4, v4
	v_or_b32_e32 v18, v18, v49
	v_or_b32_e32 v3, v7, v3
	v_or_b32_e32 v4, v4, v51
	v_lshlrev_b32_e32 v7, 8, v70
	v_or_b32_e32 v18, v18, v48
	v_lshlrev_b32_e32 v2, 30, v2
	v_or_b32_e32 v4, v4, v7
	v_lshlrev_b32_e32 v7, 14, v72
	v_or_b32_e32 v2, v18, v2
	v_lshlrev_b32_e32 v5, 6, v5
	v_or_b32_e32 v4, v4, v7
	v_lshrrev_b32_e32 v7, 4, v20
	v_lshrrev_b32_e32 v18, 2, v21
	v_or_b32_e32 v5, v5, v6
	v_lshlrev_b32_e32 v6, 12, v69
	v_or_b32_e32 v7, v7, v10
	v_or_b32_e32 v10, v18, v11
	v_lshlrev_b32_e32 v11, 8, v14
	v_or_b32_e32 v5, v5, v6
	v_lshlrev_b32_e32 v6, 18, v71
	v_lshlrev_b32_e32 v14, 10, v15
	v_or_b32_e32 v7, v7, v11
	v_lshlrev_b32_e32 v11, 14, v12
	v_or_b32_e32 v5, v5, v6
	v_lshlrev_b32_e32 v6, 20, v74
	v_or_b32_e32 v10, v10, v14
	v_or_b32_e32 v7, v7, v11
	v_lshlrev_b32_e32 v9, 20, v9
	v_or_b32_e32 v5, v5, v73
	v_or_b32_e32 v4, v4, v6
	v_lshlrev_b32_e32 v6, 30, v36
	v_or_b32_e32 v10, v10, v16
	v_lshlrev_b32_e32 v8, 22, v8
	v_or_b32_e32 v7, v7, v9
	v_and_b32_e32 v9, 0x80000000, v13
	v_or_b32_e32 v5, v5, v6
	v_or_b32_e32 v4, v4, v25
	v_lshlrev_b32_e32 v6, 28, v19
	v_or_b32_e32 v8, v10, v8
	v_lshl_or_b32 v9, v17, 26, v9
	v_or_b32_e32 v7, v7, v9
	v_or_b32_e32 v6, v8, v6
	s_mov_b64 s[98:99], exec
	s_andn2_b64 exec, s[98:99], s[100:101]
	global_store_dwordx4 v[32:33], v[2:5], off
	global_store_dwordx2 v[32:33], v[6:7], off offset:64
	s_and_b64 exec, s[98:99], s[100:101]
	global_store_dwordx2 v[32:33], v[2:3], off offset:72
	global_store_dwordx4 v[32:33], v[4:7], off offset:128
	s_mov_b64 exec, s[98:99]
	s_and_saveexec_b64 s[4:5], s[0:1]
	s_cbranch_execz .LBB0_47
	v_mul_f32_e32 v4, 0x3e088889, v24
	v_lshl_add_u64 v[2:3], v[30:31], 2, s[28:29]
	v_cndmask_b32_e32 v4, 1.0, v4, vcc
	global_store_dword v[2:3], v4, off
	s_branch .LBB0_47

.Lgu0_start:
	s_mov_b64 exec, -1
	v_and_b32_e32 v0, 63, v205
	v_lshrrev_b32_e32 v1, 6, v205
	v_lshlrev_b32_e32 v193, 2, v0
	v_readfirstlane_b32 s68, v1
	v_and_b32_e32 v1, 3, v0
	v_lshlrev_b32_e32 v196, 4, v1
	v_lshlrev_b32_e32 v197, 4, v1
	s_nop 3
	s_lshl_b32 s17, s68, 14
	s_add_i32 s69, s93, s68
	v_and_b32_e32 v1, 3, v0
	v_lshlrev_b32_e32 v195, 4, v1
	v_lshrrev_b32_e32 v1, 2, v0
	v_add_u32_e32 v195, v195, v1
	v_lshl_add_u32 v195, v195, 2, s17
	v_lshrrev_b32_e32 v1, 2, v0
	v_lshl_add_u32 v194, v1, 2, s17
	v_add_u32_e32 v194, 0x2000, v194
	v_lshl_add_u32 v198, v0, 4, s17
	v_add_u32_e32 v200, s17, v193
	v_add_u32_e32 v199, 0x2000, v200
	v_lshrrev_b32_e32 v114, 3, v0
	v_lshlrev_b32_e32 v114, 8, v114
	v_and_b32_e32 v1, 7, v0
	v_lshl_add_u32 v114, v1, 3, v114
	s_lshl_b32 s18, s68, 9
	s_add_u32 s18, s18, 0x10000
	v_lshl_add_u32 v115, v0, 3, s18
	v_and_b32_e32 v1, 3, v0
	v_lshl_add_u32 v116, v1, 4, s18
.Lgu0_chunk:
	s_movk_i32 s64, 0xc0
	s_lshl_b32 s65, s92, 13
	s_mov_b32 s70, 0x11111111
	s_mov_b32 s71, 0x11111111
	s_mov_b32 s14, 0x22222222
	s_mov_b32 s15, 0x22222222
	s_mov_b32 s100, 0x44444444
	s_mov_b32 s101, 0x44444444
	s_mov_b32 s98, 0x88888888
	s_mov_b32 s99, 0x88888888
	s_add_u32 s10, s26, 0xd800000
	s_addc_u32 s11, s27, 0
	s_lshl_b32 s17, s69, 9
	s_add_u32 s10, s10, s17
	s_addc_u32 s11, s11, 0
	s_lshl_b32 s18, s92, 11
	global_load_dword v16, v193, s[10:11]
	global_load_dword v17, v193, s[10:11] offset:256
	s_add_u32 s10, s10, s18
	s_addc_u32 s11, s11, 0
	global_load_dword v18, v193, s[10:11]
	global_load_dword v19, v193, s[10:11] offset:256
	s_add_u32 s10, s10, s18
	s_addc_u32 s11, s11, 0
	global_load_dword v20, v193, s[10:11]
	global_load_dword v21, v193, s[10:11] offset:256
	s_add_u32 s10, s10, s18
	s_addc_u32 s11, s11, 0
	global_load_dword v22, v193, s[10:11]
	global_load_dword v23, v193, s[10:11] offset:256
	s_add_u32 s10, s10, s18
	s_addc_u32 s11, s11, 0
	global_load_dword v24, v193, s[10:11]
	global_load_dword v25, v193, s[10:11] offset:256
	s_add_u32 s10, s10, s18
	s_addc_u32 s11, s11, 0
	global_load_dword v26, v193, s[10:11]
	global_load_dword v27, v193, s[10:11] offset:256
	s_add_u32 s10, s10, s18
	s_addc_u32 s11, s11, 0
	global_load_dword v28, v193, s[10:11]
	global_load_dword v29, v193, s[10:11] offset:256
	s_add_u32 s10, s10, s18
	s_addc_u32 s11, s11, 0
	global_load_dword v30, v193, s[10:11]
	global_load_dword v31, v193, s[10:11] offset:256
	s_add_u32 s10, s10, s18
	s_addc_u32 s11, s11, 0
	global_load_dword v32, v193, s[10:11]
	global_load_dword v33, v193, s[10:11] offset:256
	s_add_u32 s10, s10, s18
	s_addc_u32 s11, s11, 0
	global_load_dword v34, v193, s[10:11]
	global_load_dword v35, v193, s[10:11] offset:256
	s_add_u32 s10, s10, s18
	s_addc_u32 s11, s11, 0
	global_load_dword v36, v193, s[10:11]
	global_load_dword v37, v193, s[10:11] offset:256
	s_add_u32 s10, s10, s18
	s_addc_u32 s11, s11, 0
	global_load_dword v38, v193, s[10:11]
	global_load_dword v39, v193, s[10:11] offset:256
	s_add_u32 s10, s10, s18
	s_addc_u32 s11, s11, 0
	global_load_dword v40, v193, s[10:11]
	global_load_dword v41, v193, s[10:11] offset:256
	s_add_u32 s10, s10, s18
	s_addc_u32 s11, s11, 0
	global_load_dword v42, v193, s[10:11]
	global_load_dword v43, v193, s[10:11] offset:256
	s_add_u32 s10, s10, s18
	s_addc_u32 s11, s11, 0
	global_load_dword v44, v193, s[10:11]
	global_load_dword v45, v193, s[10:11] offset:256
	s_add_u32 s10, s10, s18
	s_addc_u32 s11, s11, 0
	global_load_dword v46, v193, s[10:11]
	global_load_dword v47, v193, s[10:11] offset:256
	s_add_u32 s10, s10, s18
	s_addc_u32 s11, s11, 0
	v_mov_b32_e32 v0, 0
	v_mov_b32_e32 v1, 0
	v_mov_b32_e32 v2, 0
	v_mov_b32_e32 v3, 0
	ds_write_b128 v198, v[0:3] offset:0
	ds_write_b128 v198, v[0:3] offset:1024
	ds_write_b128 v198, v[0:3] offset:2048
	ds_write_b128 v198, v[0:3] offset:3072
	ds_write_b128 v198, v[0:3] offset:4096
	ds_write_b128 v198, v[0:3] offset:5120
	ds_write_b128 v198, v[0:3] offset:6144
	ds_write_b128 v198, v[0:3] offset:7168
	s_waitcnt vmcnt(0)
	ds_write2st64_b32 v199, v16, v17 offset0:0 offset1:1
	ds_write2st64_b32 v199, v18, v19 offset0:2 offset1:3
	ds_write2st64_b32 v199, v20, v21 offset0:4 offset1:5
	ds_write2st64_b32 v199, v22, v23 offset0:6 offset1:7
	ds_write2st64_b32 v199, v24, v25 offset0:8 offset1:9
	ds_write2st64_b32 v199, v26, v27 offset0:10 offset1:11
	ds_write2st64_b32 v199, v28, v29 offset0:12 offset1:13
	ds_write2st64_b32 v199, v30, v31 offset0:14 offset1:15
	ds_write2st64_b32 v199, v32, v33 offset0:16 offset1:17
	ds_write2st64_b32 v199, v34, v35 offset0:18 offset1:19
	ds_write2st64_b32 v199, v36, v37 offset0:20 offset1:21
	ds_write2st64_b32 v199, v38, v39 offset0:22 offset1:23
	ds_write2st64_b32 v199, v40, v41 offset0:24 offset1:25
	ds_write2st64_b32 v199, v42, v43 offset0:26 offset1:27
	ds_write2st64_b32 v199, v44, v45 offset0:28 offset1:29
	ds_write2st64_b32 v199, v46, v47 offset0:30 offset1:31
	s_waitcnt lgkmcnt(0)
	s_add_u32 s4, s26, 0x1800000
	s_addc_u32 s5, s27, 0
	s_add_u32 s8, s26, 0x5800000
	s_addc_u32 s9, s27, 0
	s_lshl_b32 s17, s69, 11
	s_add_u32 s8, s8, s17
	s_addc_u32 s9, s9, 0
	s_mov_b32 s16, 0
	s_and_b32 s19, s16, 15
	s_lshr_b32 s50, s16, 4
	s_lshl_b32 s51, s19, 9
	s_mul_i32 s17, s19, s65
	s_lshl_b32 s18, s50, 6
	s_add_u32 s17, s17, s18
	s_add_u32 s10, s8, s17
	s_addc_u32 s11, s9, 0
	s_mul_i32 s17, s50, 0x300000
	s_add_u32 s4, s26, 0x1800000
	s_addc_u32 s5, s27, 0
	s_add_u32 s4, s4, s17
	s_addc_u32 s5, s5, 0
	v_add_u32_e32 v201, s51, v194
	ds_read2_b32 v[184:185], v201 offset0:0 offset1:16
	ds_read2_b32 v[186:187], v201 offset0:32 offset1:48
	ds_read2_b32 v[188:189], v201 offset0:64 offset1:80
	ds_read2_b32 v[190:191], v201 offset0:96 offset1:112
	global_load_dwordx2 v[112:113], v114, s[10:11]
	s_waitcnt lgkmcnt(0)
	v_mad_u32_u24 v184, v184, s64, v197
	v_mad_u32_u24 v185, v185, s64, v197
	global_load_dwordx4 v[16:19], v184, s[4:5]
	global_load_dwordx4 v[20:23], v184, s[4:5] offset:64
	global_load_dwordx4 v[24:27], v184, s[4:5] offset:128
	global_load_dwordx4 v[28:31], v185, s[4:5]
	global_load_dwordx4 v[32:35], v185, s[4:5] offset:64
	global_load_dwordx4 v[36:39], v185, s[4:5] offset:128
	v_mad_u32_u24 v186, v186, s64, v197
	v_mad_u32_u24 v187, v187, s64, v197
	global_load_dwordx4 v[40:43], v186, s[4:5]
	global_load_dwordx4 v[44:47], v186, s[4:5] offset:64
	global_load_dwordx4 v[48:51], v186, s[4:5] offset:128
	global_load_dwordx4 v[52:55], v187, s[4:5]
	global_load_dwordx4 v[56:59], v187, s[4:5] offset:64
	global_load_dwordx4 v[60:63], v187, s[4:5] offset:128
	v_mad_u32_u24 v188, v188, s64, v197
	v_mad_u32_u24 v189, v189, s64, v197
	global_load_dwordx4 v[64:67], v188, s[4:5]
	global_load_dwordx4 v[68:71], v188, s[4:5] offset:64
	global_load_dwordx4 v[72:75], v188, s[4:5] offset:128
	global_load_dwordx4 v[76:79], v189, s[4:5]
	global_load_dwordx4 v[80:83], v189, s[4:5] offset:64
	global_load_dwordx4 v[84:87], v189, s[4:5] offset:128
	v_mad_u32_u24 v190, v190, s64, v197
	v_mad_u32_u24 v191, v191, s64, v197
	global_load_dwordx4 v[88:91], v190, s[4:5]
	global_load_dwordx4 v[92:95], v190, s[4:5] offset:64
	global_load_dwordx4 v[96:99], v190, s[4:5] offset:128
	global_load_dwordx4 v[100:103], v191, s[4:5]
	global_load_dwordx4 v[104:107], v191, s[4:5] offset:64
	global_load_dwordx4 v[108:111], v191, s[4:5] offset:128
	s_mov_b32 s18, 1
	s_and_b32 s19, s18, 15
	s_lshr_b32 s50, s18, 4
	s_lshl_b32 s51, s19, 9
	s_mul_i32 s17, s19, s65
	s_lshl_b32 s18, s50, 6
	s_add_u32 s17, s17, s18
	s_add_u32 s12, s8, s17
	s_addc_u32 s13, s9, 0
	s_mul_i32 s17, s50, 0x300000
	s_add_u32 s4, s26, 0x1800000
	s_addc_u32 s5, s27, 0
	s_add_u32 s4, s4, s17
	s_addc_u32 s5, s5, 0
	v_add_u32_e32 v202, s51, v194
	ds_read2_b32 v[184:185], v202 offset0:0 offset1:16
	ds_read2_b32 v[186:187], v202 offset0:32 offset1:48
	ds_read2_b32 v[188:189], v202 offset0:64 offset1:80
	ds_read2_b32 v[190:191], v202 offset0:96 offset1:112
.Lgu0_loop:
	s_and_b32 s19, s16, 15
	s_lshl_b32 s51, s19, 9
	v_add_u32_e32 v203, s51, v195
	s_waitcnt vmcnt(24)
	ds_write_b64 v115, v[112:113]
	ds_read_b128 v[144:147], v116 offset:0
	ds_read_b128 v[148:151], v116 offset:64
	ds_read_b128 v[152:155], v116 offset:128
	ds_read_b128 v[156:159], v116 offset:192
	ds_read_b128 v[160:163], v116 offset:256
	ds_read_b128 v[164:167], v116 offset:320
	ds_read_b128 v[168:171], v116 offset:384
	ds_read_b128 v[172:175], v116 offset:448
	s_waitcnt lgkmcnt(0)
	s_waitcnt vmcnt(21)
	v_cvt_scalef32_pk32_bf16_fp6 v[0:15], v[16:21], 1.0
	v_cvt_scalef32_pk32_bf16_fp6 v[128:143], v[22:27], 1.0
	v_dot2_f32_bf16 v176, v0, v144, 0
	v_dot2_f32_bf16 v177, v1, v145, 0
	v_dot2_f32_bf16 v178, v2, v148, 0
	v_dot2_f32_bf16 v179, v3, v149, 0
	v_dot2c_f32_bf16_e32 v176, v4, v152
	v_dot2c_f32_bf16_e32 v177, v5, v153
	v_dot2c_f32_bf16_e32 v178, v6, v156
	v_dot2c_f32_bf16_e32 v179, v7, v157
	v_dot2c_f32_bf16_e32 v176, v8, v160
	v_dot2c_f32_bf16_e32 v177, v9, v161
	v_dot2c_f32_bf16_e32 v178, v10, v164
	v_dot2c_f32_bf16_e32 v179, v11, v165
	v_dot2c_f32_bf16_e32 v176, v12, v168
	v_dot2c_f32_bf16_e32 v177, v13, v169
	v_dot2c_f32_bf16_e32 v178, v14, v172
	v_dot2c_f32_bf16_e32 v179, v15, v173
	v_dot2c_f32_bf16_e32 v176, v128, v146
	v_dot2c_f32_bf16_e32 v177, v129, v147
	v_dot2c_f32_bf16_e32 v178, v130, v150
	v_dot2c_f32_bf16_e32 v179, v131, v151
	v_dot2c_f32_bf16_e32 v176, v132, v154
	v_dot2c_f32_bf16_e32 v177, v133, v155
	v_dot2c_f32_bf16_e32 v178, v134, v158
	v_dot2c_f32_bf16_e32 v179, v135, v159
	v_dot2c_f32_bf16_e32 v176, v136, v162
	v_dot2c_f32_bf16_e32 v177, v137, v163
	v_dot2c_f32_bf16_e32 v178, v138, v166
	v_dot2c_f32_bf16_e32 v179, v139, v167
	v_dot2c_f32_bf16_e32 v176, v140, v170
	v_dot2c_f32_bf16_e32 v177, v141, v171
	v_dot2c_f32_bf16_e32 v178, v142, v174
	v_dot2c_f32_bf16_e32 v179, v143, v175
	s_waitcnt vmcnt(18)
	v_cvt_scalef32_pk32_bf16_fp6 v[0:15], v[28:33], 1.0
	v_cvt_scalef32_pk32_bf16_fp6 v[128:143], v[34:39], 1.0
	v_dot2_f32_bf16 v180, v0, v144, 0
	v_dot2_f32_bf16 v181, v1, v145, 0
	v_dot2_f32_bf16 v182, v2, v148, 0
	v_dot2_f32_bf16 v183, v3, v149, 0
	v_dot2c_f32_bf16_e32 v180, v4, v152
	v_dot2c_f32_bf16_e32 v181, v5, v153
	v_dot2c_f32_bf16_e32 v182, v6, v156
	v_dot2c_f32_bf16_e32 v183, v7, v157
	v_add_f32_e32 v192, v176, v177
	v_add_f32_e32 v206, v178, v179
	v_add_f32_e32 v192, v192, v206
	s_nop 1
	v_add_f32_dpp v192, v192, v192 quad_perm:[1,0,3,2] row_mask:0xf bank_mask:0xf
	s_nop 1
	v_add_f32_dpp v192, v192, v192 quad_perm:[2,3,0,1] row_mask:0xf bank_mask:0xf
	v_cndmask_b32_e64 v118, v118, v192, s[70:71]
	v_dot2c_f32_bf16_e32 v180, v8, v160
	v_dot2c_f32_bf16_e32 v181, v9, v161
	v_dot2c_f32_bf16_e32 v182, v10, v164
	v_dot2c_f32_bf16_e32 v183, v11, v165
	v_dot2c_f32_bf16_e32 v180, v12, v168
	v_dot2c_f32_bf16_e32 v181, v13, v169
	v_dot2c_f32_bf16_e32 v182, v14, v172
	v_dot2c_f32_bf16_e32 v183, v15, v173
	v_dot2c_f32_bf16_e32 v180, v128, v146
	v_dot2c_f32_bf16_e32 v181, v129, v147
	v_dot2c_f32_bf16_e32 v182, v130, v150
	v_dot2c_f32_bf16_e32 v183, v131, v151
	v_dot2c_f32_bf16_e32 v180, v132, v154
	v_dot2c_f32_bf16_e32 v181, v133, v155
	v_dot2c_f32_bf16_e32 v182, v134, v158
	v_dot2c_f32_bf16_e32 v183, v135, v159
	v_dot2c_f32_bf16_e32 v180, v136, v162
	v_dot2c_f32_bf16_e32 v181, v137, v163
	v_dot2c_f32_bf16_e32 v182, v138, v166
	v_dot2c_f32_bf16_e32 v183, v139, v167
	v_dot2c_f32_bf16_e32 v180, v140, v170
	v_dot2c_f32_bf16_e32 v181, v141, v171
	v_dot2c_f32_bf16_e32 v182, v142, v174
	v_dot2c_f32_bf16_e32 v183, v143, v175
	global_load_dwordx2 v[112:113], v114, s[12:13]
	s_waitcnt lgkmcnt(0)
	v_mad_u32_u24 v184, v184, s64, v197
	v_mad_u32_u24 v185, v185, s64, v197
	global_load_dwordx4 v[16:19], v184, s[4:5]
	global_load_dwordx4 v[20:23], v184, s[4:5] offset:64
	global_load_dwordx4 v[24:27], v184, s[4:5] offset:128
	global_load_dwordx4 v[28:31], v185, s[4:5]
	global_load_dwordx4 v[32:35], v185, s[4:5] offset:64
	global_load_dwordx4 v[36:39], v185, s[4:5] offset:128
	s_waitcnt vmcnt(22)
	v_cvt_scalef32_pk32_bf16_fp6 v[0:15], v[40:45], 1.0
	v_cvt_scalef32_pk32_bf16_fp6 v[128:143], v[46:51], 1.0
	v_dot2_f32_bf16 v176, v0, v144, 0
	v_dot2_f32_bf16 v177, v1, v145, 0
	v_dot2_f32_bf16 v178, v2, v148, 0
	v_dot2_f32_bf16 v179, v3, v149, 0
	v_dot2c_f32_bf16_e32 v176, v4, v152
	v_dot2c_f32_bf16_e32 v177, v5, v153
	v_dot2c_f32_bf16_e32 v178, v6, v156
	v_dot2c_f32_bf16_e32 v179, v7, v157
	v_add_f32_e32 v192, v180, v181
	v_add_f32_e32 v206, v182, v183
	v_add_f32_e32 v192, v192, v206
	s_nop 1
	v_add_f32_dpp v192, v192, v192 quad_perm:[1,0,3,2] row_mask:0xf bank_mask:0xf
	s_nop 1
	v_add_f32_dpp v192, v192, v192 quad_perm:[2,3,0,1] row_mask:0xf bank_mask:0xf
	v_cndmask_b32_e64 v118, v118, v192, s[14:15]
	v_dot2c_f32_bf16_e32 v176, v8, v160
	v_dot2c_f32_bf16_e32 v177, v9, v161
	v_dot2c_f32_bf16_e32 v178, v10, v164
	v_dot2c_f32_bf16_e32 v179, v11, v165
	v_dot2c_f32_bf16_e32 v176, v12, v168
	v_dot2c_f32_bf16_e32 v177, v13, v169
	v_dot2c_f32_bf16_e32 v178, v14, v172
	v_dot2c_f32_bf16_e32 v179, v15, v173
	v_dot2c_f32_bf16_e32 v176, v128, v146
	v_dot2c_f32_bf16_e32 v177, v129, v147
	v_dot2c_f32_bf16_e32 v178, v130, v150
	v_dot2c_f32_bf16_e32 v179, v131, v151
	v_dot2c_f32_bf16_e32 v176, v132, v154
	v_dot2c_f32_bf16_e32 v177, v133, v155
	v_dot2c_f32_bf16_e32 v178, v134, v158
	v_dot2c_f32_bf16_e32 v179, v135, v159
	v_dot2c_f32_bf16_e32 v176, v136, v162
	v_dot2c_f32_bf16_e32 v177, v137, v163
	v_dot2c_f32_bf16_e32 v178, v138, v166
	v_dot2c_f32_bf16_e32 v179, v139, v167
	v_dot2c_f32_bf16_e32 v176, v140, v170
	v_dot2c_f32_bf16_e32 v177, v141, v171
	v_dot2c_f32_bf16_e32 v178, v142, v174
	v_dot2c_f32_bf16_e32 v179, v143, v175
	s_waitcnt vmcnt(19)
	v_cvt_scalef32_pk32_bf16_fp6 v[0:15], v[52:57], 1.0
	v_cvt_scalef32_pk32_bf16_fp6 v[128:143], v[58:63], 1.0
	v_dot2_f32_bf16 v180, v0, v144, 0
	v_dot2_f32_bf16 v181, v1, v145, 0
	v_dot2_f32_bf16 v182, v2, v148, 0
	v_dot2_f32_bf16 v183, v3, v149, 0
	v_dot2c_f32_bf16_e32 v180, v4, v152
	v_dot2c_f32_bf16_e32 v181, v5, v153
	v_dot2c_f32_bf16_e32 v182, v6, v156
	v_dot2c_f32_bf16_e32 v183, v7, v157
	v_add_f32_e32 v192, v176, v177
	v_add_f32_e32 v206, v178, v179
	v_add_f32_e32 v192, v192, v206
	s_nop 1
	v_add_f32_dpp v192, v192, v192 quad_perm:[1,0,3,2] row_mask:0xf bank_mask:0xf
	s_nop 1
	v_add_f32_dpp v192, v192, v192 quad_perm:[2,3,0,1] row_mask:0xf bank_mask:0xf
	v_cndmask_b32_e64 v118, v118, v192, s[100:101]
	v_dot2c_f32_bf16_e32 v180, v8, v160
	v_dot2c_f32_bf16_e32 v181, v9, v161
	v_dot2c_f32_bf16_e32 v182, v10, v164
	v_dot2c_f32_bf16_e32 v183, v11, v165
	v_dot2c_f32_bf16_e32 v180, v12, v168
	v_dot2c_f32_bf16_e32 v181, v13, v169
	v_dot2c_f32_bf16_e32 v182, v14, v172
	v_dot2c_f32_bf16_e32 v183, v15, v173
	v_dot2c_f32_bf16_e32 v180, v128, v146
	v_dot2c_f32_bf16_e32 v181, v129, v147
	v_dot2c_f32_bf16_e32 v182, v130, v150
	v_dot2c_f32_bf16_e32 v183, v131, v151
	v_dot2c_f32_bf16_e32 v180, v132, v154
	v_dot2c_f32_bf16_e32 v181, v133, v155
	v_dot2c_f32_bf16_e32 v182, v134, v158
	v_dot2c_f32_bf16_e32 v183, v135, v159
	v_dot2c_f32_bf16_e32 v180, v136, v162
	v_dot2c_f32_bf16_e32 v181, v137, v163
	v_dot2c_f32_bf16_e32 v182, v138, v166
	v_dot2c_f32_bf16_e32 v183, v139, v167
	v_dot2c_f32_bf16_e32 v180, v140, v170
	v_dot2c_f32_bf16_e32 v181, v141, v171
	v_dot2c_f32_bf16_e32 v182, v142, v174
	v_dot2c_f32_bf16_e32 v183, v143, v175
	v_mad_u32_u24 v186, v186, s64, v197
	v_mad_u32_u24 v187, v187, s64, v197
	global_load_dwordx4 v[40:43], v186, s[4:5]
	global_load_dwordx4 v[44:47], v186, s[4:5] offset:64
	global_load_dwordx4 v[48:51], v186, s[4:5] offset:128
	global_load_dwordx4 v[52:55], v187, s[4:5]
	global_load_dwordx4 v[56:59], v187, s[4:5] offset:64
	global_load_dwordx4 v[60:63], v187, s[4:5] offset:128
	s_waitcnt vmcnt(22)
	v_cvt_scalef32_pk32_bf16_fp6 v[0:15], v[64:69], 1.0
	v_cvt_scalef32_pk32_bf16_fp6 v[128:143], v[70:75], 1.0
	v_dot2_f32_bf16 v176, v0, v144, 0
	v_dot2_f32_bf16 v177, v1, v145, 0
	v_dot2_f32_bf16 v178, v2, v148, 0
	v_dot2_f32_bf16 v179, v3, v149, 0
	v_dot2c_f32_bf16_e32 v176, v4, v152
	v_dot2c_f32_bf16_e32 v177, v5, v153
	v_dot2c_f32_bf16_e32 v178, v6, v156
	v_dot2c_f32_bf16_e32 v179, v7, v157
	v_add_f32_e32 v192, v180, v181
	v_add_f32_e32 v206, v182, v183
	v_add_f32_e32 v192, v192, v206
	s_nop 1
	v_add_f32_dpp v192, v192, v192 quad_perm:[1,0,3,2] row_mask:0xf bank_mask:0xf
	s_nop 1
	v_add_f32_dpp v192, v192, v192 quad_perm:[2,3,0,1] row_mask:0xf bank_mask:0xf
	v_cndmask_b32_e64 v118, v118, v192, s[98:99]
	ds_add_f32 v203, v118 offset:0
	v_dot2c_f32_bf16_e32 v176, v8, v160
	v_dot2c_f32_bf16_e32 v177, v9, v161
	v_dot2c_f32_bf16_e32 v178, v10, v164
	v_dot2c_f32_bf16_e32 v179, v11, v165
	v_dot2c_f32_bf16_e32 v176, v12, v168
	v_dot2c_f32_bf16_e32 v177, v13, v169
	v_dot2c_f32_bf16_e32 v178, v14, v172
	v_dot2c_f32_bf16_e32 v179, v15, v173
	v_dot2c_f32_bf16_e32 v176, v128, v146
	v_dot2c_f32_bf16_e32 v177, v129, v147
	v_dot2c_f32_bf16_e32 v178, v130, v150
	v_dot2c_f32_bf16_e32 v179, v131, v151
	v_dot2c_f32_bf16_e32 v176, v132, v154
	v_dot2c_f32_bf16_e32 v177, v133, v155
	v_dot2c_f32_bf16_e32 v178, v134, v158
	v_dot2c_f32_bf16_e32 v179, v135, v159
	v_dot2c_f32_bf16_e32 v176, v136, v162
	v_dot2c_f32_bf16_e32 v177, v137, v163
	v_dot2c_f32_bf16_e32 v178, v138, v166
	v_dot2c_f32_bf16_e32 v179, v139, v167
	v_dot2c_f32_bf16_e32 v176, v140, v170
	v_dot2c_f32_bf16_e32 v177, v141, v171
	v_dot2c_f32_bf16_e32 v178, v142, v174
	v_dot2c_f32_bf16_e32 v179, v143, v175
	s_waitcnt vmcnt(19)
	v_cvt_scalef32_pk32_bf16_fp6 v[0:15], v[76:81], 1.0
	v_cvt_scalef32_pk32_bf16_fp6 v[128:143], v[82:87], 1.0
	v_dot2_f32_bf16 v180, v0, v144, 0
	v_dot2_f32_bf16 v181, v1, v145, 0
	v_dot2_f32_bf16 v182, v2, v148, 0
	v_dot2_f32_bf16 v183, v3, v149, 0
	v_dot2c_f32_bf16_e32 v180, v4, v152
	v_dot2c_f32_bf16_e32 v181, v5, v153
	v_dot2c_f32_bf16_e32 v182, v6, v156
	v_dot2c_f32_bf16_e32 v183, v7, v157
	v_add_f32_e32 v192, v176, v177
	v_add_f32_e32 v206, v178, v179
	v_add_f32_e32 v192, v192, v206
	s_nop 1
	v_add_f32_dpp v192, v192, v192 quad_perm:[1,0,3,2] row_mask:0xf bank_mask:0xf
	s_nop 1
	v_add_f32_dpp v192, v192, v192 quad_perm:[2,3,0,1] row_mask:0xf bank_mask:0xf
	v_cndmask_b32_e64 v119, v119, v192, s[70:71]
	v_dot2c_f32_bf16_e32 v180, v8, v160
	v_dot2c_f32_bf16_e32 v181, v9, v161
	v_dot2c_f32_bf16_e32 v182, v10, v164
	v_dot2c_f32_bf16_e32 v183, v11, v165
	v_dot2c_f32_bf16_e32 v180, v12, v168
	v_dot2c_f32_bf16_e32 v181, v13, v169
	v_dot2c_f32_bf16_e32 v182, v14, v172
	v_dot2c_f32_bf16_e32 v183, v15, v173
	v_dot2c_f32_bf16_e32 v180, v128, v146
	v_dot2c_f32_bf16_e32 v181, v129, v147
	v_dot2c_f32_bf16_e32 v182, v130, v150
	v_dot2c_f32_bf16_e32 v183, v131, v151
	v_dot2c_f32_bf16_e32 v180, v132, v154
	v_dot2c_f32_bf16_e32 v181, v133, v155
	v_dot2c_f32_bf16_e32 v182, v134, v158
	v_dot2c_f32_bf16_e32 v183, v135, v159
	v_dot2c_f32_bf16_e32 v180, v136, v162
	v_dot2c_f32_bf16_e32 v181, v137, v163
	v_dot2c_f32_bf16_e32 v182, v138, v166
	v_dot2c_f32_bf16_e32 v183, v139, v167
	v_dot2c_f32_bf16_e32 v180, v140, v170
	v_dot2c_f32_bf16_e32 v181, v141, v171
	v_dot2c_f32_bf16_e32 v182, v142, v174
	v_dot2c_f32_bf16_e32 v183, v143, v175
	v_mad_u32_u24 v188, v188, s64, v197
	v_mad_u32_u24 v189, v189, s64, v197
	global_load_dwordx4 v[64:67], v188, s[4:5]
	global_load_dwordx4 v[68:71], v188, s[4:5] offset:64
	global_load_dwordx4 v[72:75], v188, s[4:5] offset:128
	global_load_dwordx4 v[76:79], v189, s[4:5]
	global_load_dwordx4 v[80:83], v189, s[4:5] offset:64
	global_load_dwordx4 v[84:87], v189, s[4:5] offset:128
	s_waitcnt vmcnt(22)
	v_cvt_scalef32_pk32_bf16_fp6 v[0:15], v[88:93], 1.0
	v_cvt_scalef32_pk32_bf16_fp6 v[128:143], v[94:99], 1.0
	v_dot2_f32_bf16 v176, v0, v144, 0
	v_dot2_f32_bf16 v177, v1, v145, 0
	v_dot2_f32_bf16 v178, v2, v148, 0
	v_dot2_f32_bf16 v179, v3, v149, 0
	v_dot2c_f32_bf16_e32 v176, v4, v152
	v_dot2c_f32_bf16_e32 v177, v5, v153
	v_dot2c_f32_bf16_e32 v178, v6, v156
	v_dot2c_f32_bf16_e32 v179, v7, v157
	v_add_f32_e32 v192, v180, v181
	v_add_f32_e32 v206, v182, v183
	v_add_f32_e32 v192, v192, v206
	s_nop 1
	v_add_f32_dpp v192, v192, v192 quad_perm:[1,0,3,2] row_mask:0xf bank_mask:0xf
	s_nop 1
	v_add_f32_dpp v192, v192, v192 quad_perm:[2,3,0,1] row_mask:0xf bank_mask:0xf
	v_cndmask_b32_e64 v119, v119, v192, s[14:15]
	v_dot2c_f32_bf16_e32 v176, v8, v160
	v_dot2c_f32_bf16_e32 v177, v9, v161
	v_dot2c_f32_bf16_e32 v178, v10, v164
	v_dot2c_f32_bf16_e32 v179, v11, v165
	v_dot2c_f32_bf16_e32 v176, v12, v168
	v_dot2c_f32_bf16_e32 v177, v13, v169
	v_dot2c_f32_bf16_e32 v178, v14, v172
	v_dot2c_f32_bf16_e32 v179, v15, v173
	v_dot2c_f32_bf16_e32 v176, v128, v146
	v_dot2c_f32_bf16_e32 v177, v129, v147
	v_dot2c_f32_bf16_e32 v178, v130, v150
	v_dot2c_f32_bf16_e32 v179, v131, v151
	v_dot2c_f32_bf16_e32 v176, v132, v154
	v_dot2c_f32_bf16_e32 v177, v133, v155
	v_dot2c_f32_bf16_e32 v178, v134, v158
	v_dot2c_f32_bf16_e32 v179, v135, v159
	v_dot2c_f32_bf16_e32 v176, v136, v162
	v_dot2c_f32_bf16_e32 v177, v137, v163
	v_dot2c_f32_bf16_e32 v178, v138, v166
	v_dot2c_f32_bf16_e32 v179, v139, v167
	v_dot2c_f32_bf16_e32 v176, v140, v170
	v_dot2c_f32_bf16_e32 v177, v141, v171
	v_dot2c_f32_bf16_e32 v178, v142, v174
	v_dot2c_f32_bf16_e32 v179, v143, v175
	s_waitcnt vmcnt(19)
	v_cvt_scalef32_pk32_bf16_fp6 v[0:15], v[100:105], 1.0
	v_cvt_scalef32_pk32_bf16_fp6 v[128:143], v[106:111], 1.0
	v_dot2_f32_bf16 v180, v0, v144, 0
	v_dot2_f32_bf16 v181, v1, v145, 0
	v_dot2_f32_bf16 v182, v2, v148, 0
	v_dot2_f32_bf16 v183, v3, v149, 0
	v_dot2c_f32_bf16_e32 v180, v4, v152
	v_dot2c_f32_bf16_e32 v181, v5, v153
	v_dot2c_f32_bf16_e32 v182, v6, v156
	v_dot2c_f32_bf16_e32 v183, v7, v157
	v_add_f32_e32 v192, v176, v177
	v_add_f32_e32 v206, v178, v179
	v_add_f32_e32 v192, v192, v206
	s_nop 1
	v_add_f32_dpp v192, v192, v192 quad_perm:[1,0,3,2] row_mask:0xf bank_mask:0xf
	s_nop 1
	v_add_f32_dpp v192, v192, v192 quad_perm:[2,3,0,1] row_mask:0xf bank_mask:0xf
	v_cndmask_b32_e64 v119, v119, v192, s[100:101]
	v_dot2c_f32_bf16_e32 v180, v8, v160
	v_dot2c_f32_bf16_e32 v181, v9, v161
	v_dot2c_f32_bf16_e32 v182, v10, v164
	v_dot2c_f32_bf16_e32 v183, v11, v165
	v_dot2c_f32_bf16_e32 v180, v12, v168
	v_dot2c_f32_bf16_e32 v181, v13, v169
	v_dot2c_f32_bf16_e32 v182, v14, v172
	v_dot2c_f32_bf16_e32 v183, v15, v173
	v_dot2c_f32_bf16_e32 v180, v128, v146
	v_dot2c_f32_bf16_e32 v181, v129, v147
	v_dot2c_f32_bf16_e32 v182, v130, v150
	v_dot2c_f32_bf16_e32 v183, v131, v151
	v_dot2c_f32_bf16_e32 v180, v132, v154
	v_dot2c_f32_bf16_e32 v181, v133, v155
	v_dot2c_f32_bf16_e32 v182, v134, v158
	v_dot2c_f32_bf16_e32 v183, v135, v159
	v_dot2c_f32_bf16_e32 v180, v136, v162
	v_dot2c_f32_bf16_e32 v181, v137, v163
	v_dot2c_f32_bf16_e32 v182, v138, v166
	v_dot2c_f32_bf16_e32 v183, v139, v167
	v_dot2c_f32_bf16_e32 v180, v140, v170
	v_dot2c_f32_bf16_e32 v181, v141, v171
	v_dot2c_f32_bf16_e32 v182, v142, v174
	v_dot2c_f32_bf16_e32 v183, v143, v175
	v_mad_u32_u24 v190, v190, s64, v197
	v_mad_u32_u24 v191, v191, s64, v197
	global_load_dwordx4 v[88:91], v190, s[4:5]
	global_load_dwordx4 v[92:95], v190, s[4:5] offset:64
	global_load_dwordx4 v[96:99], v190, s[4:5] offset:128
	global_load_dwordx4 v[100:103], v191, s[4:5]
	global_load_dwordx4 v[104:107], v191, s[4:5] offset:64
	global_load_dwordx4 v[108:111], v191, s[4:5] offset:128
	s_add_u32 s16, s16, 1
	s_and_b32 s16, s16, 63
	s_add_u32 s18, s16, 1
	s_and_b32 s18, s18, 63
	s_and_b32 s19, s18, 15
	s_lshr_b32 s50, s18, 4
	s_lshl_b32 s51, s19, 9
	s_mul_i32 s17, s19, s65
	s_lshl_b32 s18, s50, 6
	s_add_u32 s17, s17, s18
	s_add_u32 s10, s8, s17
	s_addc_u32 s11, s9, 0
	s_mul_i32 s17, s50, 0x300000
	s_add_u32 s4, s26, 0x1800000
	s_addc_u32 s5, s27, 0
	s_add_u32 s4, s4, s17
	s_addc_u32 s5, s5, 0
	v_add_u32_e32 v201, s51, v194
	ds_read2_b32 v[184:185], v201 offset0:0 offset1:16
	ds_read2_b32 v[186:187], v201 offset0:32 offset1:48
	ds_read2_b32 v[188:189], v201 offset0:64 offset1:80
	ds_read2_b32 v[190:191], v201 offset0:96 offset1:112
	v_add_f32_e32 v192, v180, v181
	v_add_f32_e32 v206, v182, v183
	v_add_f32_e32 v192, v192, v206
	s_nop 1
	v_add_f32_dpp v192, v192, v192 quad_perm:[1,0,3,2] row_mask:0xf bank_mask:0xf
	s_nop 1
	v_add_f32_dpp v192, v192, v192 quad_perm:[2,3,0,1] row_mask:0xf bank_mask:0xf
	v_cndmask_b32_e64 v119, v119, v192, s[98:99]
	ds_add_f32 v203, v119 offset:256
	s_and_b32 s19, s16, 15
	s_lshl_b32 s51, s19, 9
	v_add_u32_e32 v204, s51, v195
	s_waitcnt vmcnt(24)
	ds_write_b64 v115, v[112:113]
	ds_read_b128 v[144:147], v116 offset:0
	ds_read_b128 v[148:151], v116 offset:64
	ds_read_b128 v[152:155], v116 offset:128
	ds_read_b128 v[156:159], v116 offset:192
	ds_read_b128 v[160:163], v116 offset:256
	ds_read_b128 v[164:167], v116 offset:320
	ds_read_b128 v[168:171], v116 offset:384
	ds_read_b128 v[172:175], v116 offset:448
	s_waitcnt lgkmcnt(0)
	s_waitcnt vmcnt(21)
	v_cvt_scalef32_pk32_bf16_fp6 v[0:15], v[16:21], 1.0
	v_cvt_scalef32_pk32_bf16_fp6 v[128:143], v[22:27], 1.0
	v_dot2_f32_bf16 v176, v0, v144, 0
	v_dot2_f32_bf16 v177, v1, v145, 0
	v_dot2_f32_bf16 v178, v2, v148, 0
	v_dot2_f32_bf16 v179, v3, v149, 0
	v_dot2c_f32_bf16_e32 v176, v4, v152
	v_dot2c_f32_bf16_e32 v177, v5, v153
	v_dot2c_f32_bf16_e32 v178, v6, v156
	v_dot2c_f32_bf16_e32 v179, v7, v157
	v_dot2c_f32_bf16_e32 v176, v8, v160
	v_dot2c_f32_bf16_e32 v177, v9, v161
	v_dot2c_f32_bf16_e32 v178, v10, v164
	v_dot2c_f32_bf16_e32 v179, v11, v165
	v_dot2c_f32_bf16_e32 v176, v12, v168
	v_dot2c_f32_bf16_e32 v177, v13, v169
	v_dot2c_f32_bf16_e32 v178, v14, v172
	v_dot2c_f32_bf16_e32 v179, v15, v173
	v_dot2c_f32_bf16_e32 v176, v128, v146
	v_dot2c_f32_bf16_e32 v177, v129, v147
	v_dot2c_f32_bf16_e32 v178, v130, v150
	v_dot2c_f32_bf16_e32 v179, v131, v151
	v_dot2c_f32_bf16_e32 v176, v132, v154
	v_dot2c_f32_bf16_e32 v177, v133, v155
	v_dot2c_f32_bf16_e32 v178, v134, v158
	v_dot2c_f32_bf16_e32 v179, v135, v159
	v_dot2c_f32_bf16_e32 v176, v136, v162
	v_dot2c_f32_bf16_e32 v177, v137, v163
	v_dot2c_f32_bf16_e32 v178, v138, v166
	v_dot2c_f32_bf16_e32 v179, v139, v167
	v_dot2c_f32_bf16_e32 v176, v140, v170
	v_dot2c_f32_bf16_e32 v177, v141, v171
	v_dot2c_f32_bf16_e32 v178, v142, v174
	v_dot2c_f32_bf16_e32 v179, v143, v175
	s_waitcnt vmcnt(18)
	v_cvt_scalef32_pk32_bf16_fp6 v[0:15], v[28:33], 1.0
	v_cvt_scalef32_pk32_bf16_fp6 v[128:143], v[34:39], 1.0
	v_dot2_f32_bf16 v180, v0, v144, 0
	v_dot2_f32_bf16 v181, v1, v145, 0
	v_dot2_f32_bf16 v182, v2, v148, 0
	v_dot2_f32_bf16 v183, v3, v149, 0
	v_dot2c_f32_bf16_e32 v180, v4, v152
	v_dot2c_f32_bf16_e32 v181, v5, v153
	v_dot2c_f32_bf16_e32 v182, v6, v156
	v_dot2c_f32_bf16_e32 v183, v7, v157
	v_add_f32_e32 v192, v176, v177
	v_add_f32_e32 v206, v178, v179
	v_add_f32_e32 v192, v192, v206
	s_nop 1
	v_add_f32_dpp v192, v192, v192 quad_perm:[1,0,3,2] row_mask:0xf bank_mask:0xf
	s_nop 1
	v_add_f32_dpp v192, v192, v192 quad_perm:[2,3,0,1] row_mask:0xf bank_mask:0xf
	v_cndmask_b32_e64 v118, v118, v192, s[70:71]
	v_dot2c_f32_bf16_e32 v180, v8, v160
	v_dot2c_f32_bf16_e32 v181, v9, v161
	v_dot2c_f32_bf16_e32 v182, v10, v164
	v_dot2c_f32_bf16_e32 v183, v11, v165
	v_dot2c_f32_bf16_e32 v180, v12, v168
	v_dot2c_f32_bf16_e32 v181, v13, v169
	v_dot2c_f32_bf16_e32 v182, v14, v172
	v_dot2c_f32_bf16_e32 v183, v15, v173
	v_dot2c_f32_bf16_e32 v180, v128, v146
	v_dot2c_f32_bf16_e32 v181, v129, v147
	v_dot2c_f32_bf16_e32 v182, v130, v150
	v_dot2c_f32_bf16_e32 v183, v131, v151
	v_dot2c_f32_bf16_e32 v180, v132, v154
	v_dot2c_f32_bf16_e32 v181, v133, v155
	v_dot2c_f32_bf16_e32 v182, v134, v158
	v_dot2c_f32_bf16_e32 v183, v135, v159
	v_dot2c_f32_bf16_e32 v180, v136, v162
	v_dot2c_f32_bf16_e32 v181, v137, v163
	v_dot2c_f32_bf16_e32 v182, v138, v166
	v_dot2c_f32_bf16_e32 v183, v139, v167
	v_dot2c_f32_bf16_e32 v180, v140, v170
	v_dot2c_f32_bf16_e32 v181, v141, v171
	v_dot2c_f32_bf16_e32 v182, v142, v174
	v_dot2c_f32_bf16_e32 v183, v143, v175
	global_load_dwordx2 v[112:113], v114, s[10:11]
	s_waitcnt lgkmcnt(0)
	v_mad_u32_u24 v184, v184, s64, v197
	v_mad_u32_u24 v185, v185, s64, v197
	global_load_dwordx4 v[16:19], v184, s[4:5]
	global_load_dwordx4 v[20:23], v184, s[4:5] offset:64
	global_load_dwordx4 v[24:27], v184, s[4:5] offset:128
	global_load_dwordx4 v[28:31], v185, s[4:5]
	global_load_dwordx4 v[32:35], v185, s[4:5] offset:64
	global_load_dwordx4 v[36:39], v185, s[4:5] offset:128
	s_waitcnt vmcnt(22)
	v_cvt_scalef32_pk32_bf16_fp6 v[0:15], v[40:45], 1.0
	v_cvt_scalef32_pk32_bf16_fp6 v[128:143], v[46:51], 1.0
	v_dot2_f32_bf16 v176, v0, v144, 0
	v_dot2_f32_bf16 v177, v1, v145, 0
	v_dot2_f32_bf16 v178, v2, v148, 0
	v_dot2_f32_bf16 v179, v3, v149, 0
	v_dot2c_f32_bf16_e32 v176, v4, v152
	v_dot2c_f32_bf16_e32 v177, v5, v153
	v_dot2c_f32_bf16_e32 v178, v6, v156
	v_dot2c_f32_bf16_e32 v179, v7, v157
	v_add_f32_e32 v192, v180, v181
	v_add_f32_e32 v206, v182, v183
	v_add_f32_e32 v192, v192, v206
	s_nop 1
	v_add_f32_dpp v192, v192, v192 quad_perm:[1,0,3,2] row_mask:0xf bank_mask:0xf
	s_nop 1
	v_add_f32_dpp v192, v192, v192 quad_perm:[2,3,0,1] row_mask:0xf bank_mask:0xf
	v_cndmask_b32_e64 v118, v118, v192, s[14:15]
	v_dot2c_f32_bf16_e32 v176, v8, v160
	v_dot2c_f32_bf16_e32 v177, v9, v161
	v_dot2c_f32_bf16_e32 v178, v10, v164
	v_dot2c_f32_bf16_e32 v179, v11, v165
	v_dot2c_f32_bf16_e32 v176, v12, v168
	v_dot2c_f32_bf16_e32 v177, v13, v169
	v_dot2c_f32_bf16_e32 v178, v14, v172
	v_dot2c_f32_bf16_e32 v179, v15, v173
	v_dot2c_f32_bf16_e32 v176, v128, v146
	v_dot2c_f32_bf16_e32 v177, v129, v147
	v_dot2c_f32_bf16_e32 v178, v130, v150
	v_dot2c_f32_bf16_e32 v179, v131, v151
	v_dot2c_f32_bf16_e32 v176, v132, v154
	v_dot2c_f32_bf16_e32 v177, v133, v155
	v_dot2c_f32_bf16_e32 v178, v134, v158
	v_dot2c_f32_bf16_e32 v179, v135, v159
	v_dot2c_f32_bf16_e32 v176, v136, v162
	v_dot2c_f32_bf16_e32 v177, v137, v163
	v_dot2c_f32_bf16_e32 v178, v138, v166
	v_dot2c_f32_bf16_e32 v179, v139, v167
	v_dot2c_f32_bf16_e32 v176, v140, v170
	v_dot2c_f32_bf16_e32 v177, v141, v171
	v_dot2c_f32_bf16_e32 v178, v142, v174
	v_dot2c_f32_bf16_e32 v179, v143, v175
	s_waitcnt vmcnt(19)
	v_cvt_scalef32_pk32_bf16_fp6 v[0:15], v[52:57], 1.0
	v_cvt_scalef32_pk32_bf16_fp6 v[128:143], v[58:63], 1.0
	v_dot2_f32_bf16 v180, v0, v144, 0
	v_dot2_f32_bf16 v181, v1, v145, 0
	v_dot2_f32_bf16 v182, v2, v148, 0
	v_dot2_f32_bf16 v183, v3, v149, 0
	v_dot2c_f32_bf16_e32 v180, v4, v152
	v_dot2c_f32_bf16_e32 v181, v5, v153
	v_dot2c_f32_bf16_e32 v182, v6, v156
	v_dot2c_f32_bf16_e32 v183, v7, v157
	v_add_f32_e32 v192, v176, v177
	v_add_f32_e32 v206, v178, v179
	v_add_f32_e32 v192, v192, v206
	s_nop 1
	v_add_f32_dpp v192, v192, v192 quad_perm:[1,0,3,2] row_mask:0xf bank_mask:0xf
	s_nop 1
	v_add_f32_dpp v192, v192, v192 quad_perm:[2,3,0,1] row_mask:0xf bank_mask:0xf
	v_cndmask_b32_e64 v118, v118, v192, s[100:101]
	v_dot2c_f32_bf16_e32 v180, v8, v160
	v_dot2c_f32_bf16_e32 v181, v9, v161
	v_dot2c_f32_bf16_e32 v182, v10, v164
	v_dot2c_f32_bf16_e32 v183, v11, v165
	v_dot2c_f32_bf16_e32 v180, v12, v168
	v_dot2c_f32_bf16_e32 v181, v13, v169
	v_dot2c_f32_bf16_e32 v182, v14, v172
	v_dot2c_f32_bf16_e32 v183, v15, v173
	v_dot2c_f32_bf16_e32 v180, v128, v146
	v_dot2c_f32_bf16_e32 v181, v129, v147
	v_dot2c_f32_bf16_e32 v182, v130, v150
	v_dot2c_f32_bf16_e32 v183, v131, v151
	v_dot2c_f32_bf16_e32 v180, v132, v154
	v_dot2c_f32_bf16_e32 v181, v133, v155
	v_dot2c_f32_bf16_e32 v182, v134, v158
	v_dot2c_f32_bf16_e32 v183, v135, v159
	v_dot2c_f32_bf16_e32 v180, v136, v162
	v_dot2c_f32_bf16_e32 v181, v137, v163
	v_dot2c_f32_bf16_e32 v182, v138, v166
	v_dot2c_f32_bf16_e32 v183, v139, v167
	v_dot2c_f32_bf16_e32 v180, v140, v170
	v_dot2c_f32_bf16_e32 v181, v141, v171
	v_dot2c_f32_bf16_e32 v182, v142, v174
	v_dot2c_f32_bf16_e32 v183, v143, v175
	v_mad_u32_u24 v186, v186, s64, v197
	v_mad_u32_u24 v187, v187, s64, v197
	global_load_dwordx4 v[40:43], v186, s[4:5]
	global_load_dwordx4 v[44:47], v186, s[4:5] offset:64
	global_load_dwordx4 v[48:51], v186, s[4:5] offset:128
	global_load_dwordx4 v[52:55], v187, s[4:5]
	global_load_dwordx4 v[56:59], v187, s[4:5] offset:64
	global_load_dwordx4 v[60:63], v187, s[4:5] offset:128
	s_waitcnt vmcnt(22)
	v_cvt_scalef32_pk32_bf16_fp6 v[0:15], v[64:69], 1.0
	v_cvt_scalef32_pk32_bf16_fp6 v[128:143], v[70:75], 1.0
	v_dot2_f32_bf16 v176, v0, v144, 0
	v_dot2_f32_bf16 v177, v1, v145, 0
	v_dot2_f32_bf16 v178, v2, v148, 0
	v_dot2_f32_bf16 v179, v3, v149, 0
	v_dot2c_f32_bf16_e32 v176, v4, v152
	v_dot2c_f32_bf16_e32 v177, v5, v153
	v_dot2c_f32_bf16_e32 v178, v6, v156
	v_dot2c_f32_bf16_e32 v179, v7, v157
	v_add_f32_e32 v192, v180, v181
	v_add_f32_e32 v206, v182, v183
	v_add_f32_e32 v192, v192, v206
	s_nop 1
	v_add_f32_dpp v192, v192, v192 quad_perm:[1,0,3,2] row_mask:0xf bank_mask:0xf
	s_nop 1
	v_add_f32_dpp v192, v192, v192 quad_perm:[2,3,0,1] row_mask:0xf bank_mask:0xf
	v_cndmask_b32_e64 v118, v118, v192, s[98:99]
	ds_add_f32 v204, v118 offset:0
	v_dot2c_f32_bf16_e32 v176, v8, v160
	v_dot2c_f32_bf16_e32 v177, v9, v161
	v_dot2c_f32_bf16_e32 v178, v10, v164
	v_dot2c_f32_bf16_e32 v179, v11, v165
	v_dot2c_f32_bf16_e32 v176, v12, v168
	v_dot2c_f32_bf16_e32 v177, v13, v169
	v_dot2c_f32_bf16_e32 v178, v14, v172
	v_dot2c_f32_bf16_e32 v179, v15, v173
	v_dot2c_f32_bf16_e32 v176, v128, v146
	v_dot2c_f32_bf16_e32 v177, v129, v147
	v_dot2c_f32_bf16_e32 v178, v130, v150
	v_dot2c_f32_bf16_e32 v179, v131, v151
	v_dot2c_f32_bf16_e32 v176, v132, v154
	v_dot2c_f32_bf16_e32 v177, v133, v155
	v_dot2c_f32_bf16_e32 v178, v134, v158
	v_dot2c_f32_bf16_e32 v179, v135, v159
	v_dot2c_f32_bf16_e32 v176, v136, v162
	v_dot2c_f32_bf16_e32 v177, v137, v163
	v_dot2c_f32_bf16_e32 v178, v138, v166
	v_dot2c_f32_bf16_e32 v179, v139, v167
	v_dot2c_f32_bf16_e32 v176, v140, v170
	v_dot2c_f32_bf16_e32 v177, v141, v171
	v_dot2c_f32_bf16_e32 v178, v142, v174
	v_dot2c_f32_bf16_e32 v179, v143, v175
	s_waitcnt vmcnt(19)
	v_cvt_scalef32_pk32_bf16_fp6 v[0:15], v[76:81], 1.0
	v_cvt_scalef32_pk32_bf16_fp6 v[128:143], v[82:87], 1.0
	v_dot2_f32_bf16 v180, v0, v144, 0
	v_dot2_f32_bf16 v181, v1, v145, 0
	v_dot2_f32_bf16 v182, v2, v148, 0
	v_dot2_f32_bf16 v183, v3, v149, 0
	v_dot2c_f32_bf16_e32 v180, v4, v152
	v_dot2c_f32_bf16_e32 v181, v5, v153
	v_dot2c_f32_bf16_e32 v182, v6, v156
	v_dot2c_f32_bf16_e32 v183, v7, v157
	v_add_f32_e32 v192, v176, v177
	v_add_f32_e32 v206, v178, v179
	v_add_f32_e32 v192, v192, v206
	s_nop 1
	v_add_f32_dpp v192, v192, v192 quad_perm:[1,0,3,2] row_mask:0xf bank_mask:0xf
	s_nop 1
	v_add_f32_dpp v192, v192, v192 quad_perm:[2,3,0,1] row_mask:0xf bank_mask:0xf
	v_cndmask_b32_e64 v119, v119, v192, s[70:71]
	v_dot2c_f32_bf16_e32 v180, v8, v160
	v_dot2c_f32_bf16_e32 v181, v9, v161
	v_dot2c_f32_bf16_e32 v182, v10, v164
	v_dot2c_f32_bf16_e32 v183, v11, v165
	v_dot2c_f32_bf16_e32 v180, v12, v168
	v_dot2c_f32_bf16_e32 v181, v13, v169
	v_dot2c_f32_bf16_e32 v182, v14, v172
	v_dot2c_f32_bf16_e32 v183, v15, v173
	v_dot2c_f32_bf16_e32 v180, v128, v146
	v_dot2c_f32_bf16_e32 v181, v129, v147
	v_dot2c_f32_bf16_e32 v182, v130, v150
	v_dot2c_f32_bf16_e32 v183, v131, v151
	v_dot2c_f32_bf16_e32 v180, v132, v154
	v_dot2c_f32_bf16_e32 v181, v133, v155
	v_dot2c_f32_bf16_e32 v182, v134, v158
	v_dot2c_f32_bf16_e32 v183, v135, v159
	v_dot2c_f32_bf16_e32 v180, v136, v162
	v_dot2c_f32_bf16_e32 v181, v137, v163
	v_dot2c_f32_bf16_e32 v182, v138, v166
	v_dot2c_f32_bf16_e32 v183, v139, v167
	v_dot2c_f32_bf16_e32 v180, v140, v170
	v_dot2c_f32_bf16_e32 v181, v141, v171
	v_dot2c_f32_bf16_e32 v182, v142, v174
	v_dot2c_f32_bf16_e32 v183, v143, v175
	v_mad_u32_u24 v188, v188, s64, v197
	v_mad_u32_u24 v189, v189, s64, v197
	global_load_dwordx4 v[64:67], v188, s[4:5]
	global_load_dwordx4 v[68:71], v188, s[4:5] offset:64
	global_load_dwordx4 v[72:75], v188, s[4:5] offset:128
	global_load_dwordx4 v[76:79], v189, s[4:5]
	global_load_dwordx4 v[80:83], v189, s[4:5] offset:64
	global_load_dwordx4 v[84:87], v189, s[4:5] offset:128
	s_waitcnt vmcnt(22)
	v_cvt_scalef32_pk32_bf16_fp6 v[0:15], v[88:93], 1.0
	v_cvt_scalef32_pk32_bf16_fp6 v[128:143], v[94:99], 1.0
	v_dot2_f32_bf16 v176, v0, v144, 0
	v_dot2_f32_bf16 v177, v1, v145, 0
	v_dot2_f32_bf16 v178, v2, v148, 0
	v_dot2_f32_bf16 v179, v3, v149, 0
	v_dot2c_f32_bf16_e32 v176, v4, v152
	v_dot2c_f32_bf16_e32 v177, v5, v153
	v_dot2c_f32_bf16_e32 v178, v6, v156
	v_dot2c_f32_bf16_e32 v179, v7, v157
	v_add_f32_e32 v192, v180, v181
	v_add_f32_e32 v206, v182, v183
	v_add_f32_e32 v192, v192, v206
	s_nop 1
	v_add_f32_dpp v192, v192, v192 quad_perm:[1,0,3,2] row_mask:0xf bank_mask:0xf
	s_nop 1
	v_add_f32_dpp v192, v192, v192 quad_perm:[2,3,0,1] row_mask:0xf bank_mask:0xf
	v_cndmask_b32_e64 v119, v119, v192, s[14:15]
	v_dot2c_f32_bf16_e32 v176, v8, v160
	v_dot2c_f32_bf16_e32 v177, v9, v161
	v_dot2c_f32_bf16_e32 v178, v10, v164
	v_dot2c_f32_bf16_e32 v179, v11, v165
	v_dot2c_f32_bf16_e32 v176, v12, v168
	v_dot2c_f32_bf16_e32 v177, v13, v169
	v_dot2c_f32_bf16_e32 v178, v14, v172
	v_dot2c_f32_bf16_e32 v179, v15, v173
	v_dot2c_f32_bf16_e32 v176, v128, v146
	v_dot2c_f32_bf16_e32 v177, v129, v147
	v_dot2c_f32_bf16_e32 v178, v130, v150
	v_dot2c_f32_bf16_e32 v179, v131, v151
	v_dot2c_f32_bf16_e32 v176, v132, v154
	v_dot2c_f32_bf16_e32 v177, v133, v155
	v_dot2c_f32_bf16_e32 v178, v134, v158
	v_dot2c_f32_bf16_e32 v179, v135, v159
	v_dot2c_f32_bf16_e32 v176, v136, v162
	v_dot2c_f32_bf16_e32 v177, v137, v163
	v_dot2c_f32_bf16_e32 v178, v138, v166
	v_dot2c_f32_bf16_e32 v179, v139, v167
	v_dot2c_f32_bf16_e32 v176, v140, v170
	v_dot2c_f32_bf16_e32 v177, v141, v171
	v_dot2c_f32_bf16_e32 v178, v142, v174
	v_dot2c_f32_bf16_e32 v179, v143, v175
	s_waitcnt vmcnt(19)
	v_cvt_scalef32_pk32_bf16_fp6 v[0:15], v[100:105], 1.0
	v_cvt_scalef32_pk32_bf16_fp6 v[128:143], v[106:111], 1.0
	v_dot2_f32_bf16 v180, v0, v144, 0
	v_dot2_f32_bf16 v181, v1, v145, 0
	v_dot2_f32_bf16 v182, v2, v148, 0
	v_dot2_f32_bf16 v183, v3, v149, 0
	v_dot2c_f32_bf16_e32 v180, v4, v152
	v_dot2c_f32_bf16_e32 v181, v5, v153
	v_dot2c_f32_bf16_e32 v182, v6, v156
	v_dot2c_f32_bf16_e32 v183, v7, v157
	v_add_f32_e32 v192, v176, v177
	v_add_f32_e32 v206, v178, v179
	v_add_f32_e32 v192, v192, v206
	s_nop 1
	v_add_f32_dpp v192, v192, v192 quad_perm:[1,0,3,2] row_mask:0xf bank_mask:0xf
	s_nop 1
	v_add_f32_dpp v192, v192, v192 quad_perm:[2,3,0,1] row_mask:0xf bank_mask:0xf
	v_cndmask_b32_e64 v119, v119, v192, s[100:101]
	v_dot2c_f32_bf16_e32 v180, v8, v160
	v_dot2c_f32_bf16_e32 v181, v9, v161
	v_dot2c_f32_bf16_e32 v182, v10, v164
	v_dot2c_f32_bf16_e32 v183, v11, v165
	v_dot2c_f32_bf16_e32 v180, v12, v168
	v_dot2c_f32_bf16_e32 v181, v13, v169
	v_dot2c_f32_bf16_e32 v182, v14, v172
	v_dot2c_f32_bf16_e32 v183, v15, v173
	v_dot2c_f32_bf16_e32 v180, v128, v146
	v_dot2c_f32_bf16_e32 v181, v129, v147
	v_dot2c_f32_bf16_e32 v182, v130, v150
	v_dot2c_f32_bf16_e32 v183, v131, v151
	v_dot2c_f32_bf16_e32 v180, v132, v154
	v_dot2c_f32_bf16_e32 v181, v133, v155
	v_dot2c_f32_bf16_e32 v182, v134, v158
	v_dot2c_f32_bf16_e32 v183, v135, v159
	v_dot2c_f32_bf16_e32 v180, v136, v162
	v_dot2c_f32_bf16_e32 v181, v137, v163
	v_dot2c_f32_bf16_e32 v182, v138, v166
	v_dot2c_f32_bf16_e32 v183, v139, v167
	v_dot2c_f32_bf16_e32 v180, v140, v170
	v_dot2c_f32_bf16_e32 v181, v141, v171
	v_dot2c_f32_bf16_e32 v182, v142, v174
	v_dot2c_f32_bf16_e32 v183, v143, v175
	v_mad_u32_u24 v190, v190, s64, v197
	v_mad_u32_u24 v191, v191, s64, v197
	global_load_dwordx4 v[88:91], v190, s[4:5]
	global_load_dwordx4 v[92:95], v190, s[4:5] offset:64
	global_load_dwordx4 v[96:99], v190, s[4:5] offset:128
	global_load_dwordx4 v[100:103], v191, s[4:5]
	global_load_dwordx4 v[104:107], v191, s[4:5] offset:64
	global_load_dwordx4 v[108:111], v191, s[4:5] offset:128
	s_add_u32 s16, s16, 1
	s_and_b32 s16, s16, 63
	s_add_u32 s18, s16, 1
	s_and_b32 s18, s18, 63
	s_and_b32 s19, s18, 15
	s_lshr_b32 s50, s18, 4
	s_lshl_b32 s51, s19, 9
	s_mul_i32 s17, s19, s65
	s_lshl_b32 s18, s50, 6
	s_add_u32 s17, s17, s18
	s_add_u32 s12, s8, s17
	s_addc_u32 s13, s9, 0
	s_mul_i32 s17, s50, 0x300000
	s_add_u32 s4, s26, 0x1800000
	s_addc_u32 s5, s27, 0
	s_add_u32 s4, s4, s17
	s_addc_u32 s5, s5, 0
	v_add_u32_e32 v202, s51, v194
	ds_read2_b32 v[184:185], v202 offset0:0 offset1:16
	ds_read2_b32 v[186:187], v202 offset0:32 offset1:48
	ds_read2_b32 v[188:189], v202 offset0:64 offset1:80
	ds_read2_b32 v[190:191], v202 offset0:96 offset1:112
	v_add_f32_e32 v192, v180, v181
	v_add_f32_e32 v206, v182, v183
	v_add_f32_e32 v192, v192, v206
	s_nop 1
	v_add_f32_dpp v192, v192, v192 quad_perm:[1,0,3,2] row_mask:0xf bank_mask:0xf
	s_nop 1
	v_add_f32_dpp v192, v192, v192 quad_perm:[2,3,0,1] row_mask:0xf bank_mask:0xf
	v_cndmask_b32_e64 v119, v119, v192, s[98:99]
	ds_add_f32 v204, v119 offset:256
	s_cmp_lg_u32 s16, 0
	s_cbranch_scc1 .Lgu0_loop
	s_waitcnt vmcnt(0) lgkmcnt(0)
	s_add_u32 s4, s26, 0x1400000
	s_addc_u32 s5, s27, 0
	s_add_u32 s8, s26, 0x1410000
	s_addc_u32 s9, s27, 0
	s_lshl_b32 s17, s69, 9
	s_add_u32 s10, s26, 0xe800000
	s_addc_u32 s11, s27, 0
	s_add_u32 s10, s10, s17
	s_addc_u32 s11, s11, 0
	s_add_u32 s12, s26, 0xf800000
	s_addc_u32 s13, s27, 0
	s_add_u32 s12, s12, s17
	s_addc_u32 s13, s13, 0
	s_lshl_b32 s18, s92, 11
	s_mov_b32 s16, 0x378e98ab
	s_mov_b32 s19, 0x3b7cd369
	s_mov_b32 s50, 0xbcc618b2
	s_mov_b32 s51, 0x3dda74e4
	s_mov_b32 s64, 0x3f228afd
	s_mov_b32 s65, 0x3e03c728
	s_mov_b32 s98, 0xbfb8aa3b
	s_mov_b32 s70, 0x42ce8ed0
	s_mov_b32 s71, 0xc2b17218
	s_mov_b32 s14, 0x7fffffff
	v_mov_b32_e32 v176, 0x3ba10414
	v_mov_b32_e32 v177, 0xb9c68948
	v_mov_b32_e32 v178, 0x7f800000
	ds_read2st64_b32 v[16:17], v199 offset0:0 offset1:1
	ds_read2st64_b32 v[80:81], v200 offset0:0 offset1:1
	ds_read2st64_b32 v[18:19], v199 offset0:2 offset1:3
	ds_read2st64_b32 v[82:83], v200 offset0:2 offset1:3
	ds_read2st64_b32 v[20:21], v199 offset0:4 offset1:5
	ds_read2st64_b32 v[84:85], v200 offset0:4 offset1:5
	ds_read2st64_b32 v[22:23], v199 offset0:6 offset1:7
	ds_read2st64_b32 v[86:87], v200 offset0:6 offset1:7
	ds_read2st64_b32 v[24:25], v199 offset0:8 offset1:9
	ds_read2st64_b32 v[88:89], v200 offset0:8 offset1:9
	ds_read2st64_b32 v[26:27], v199 offset0:10 offset1:11
	ds_read2st64_b32 v[90:91], v200 offset0:10 offset1:11
	ds_read2st64_b32 v[28:29], v199 offset0:12 offset1:13
	ds_read2st64_b32 v[92:93], v200 offset0:12 offset1:13
	ds_read2st64_b32 v[30:31], v199 offset0:14 offset1:15
	ds_read2st64_b32 v[94:95], v200 offset0:14 offset1:15
	s_waitcnt lgkmcnt(0)
	v_lshlrev_b32_e32 v16, 2, v16
	v_lshlrev_b32_e32 v17, 2, v17
	v_lshlrev_b32_e32 v18, 2, v18
	v_lshlrev_b32_e32 v19, 2, v19
	v_lshlrev_b32_e32 v20, 2, v20
	v_lshlrev_b32_e32 v21, 2, v21
	v_lshlrev_b32_e32 v22, 2, v22
	v_lshlrev_b32_e32 v23, 2, v23
	v_lshlrev_b32_e32 v24, 2, v24
	v_lshlrev_b32_e32 v25, 2, v25
	v_lshlrev_b32_e32 v26, 2, v26
	v_lshlrev_b32_e32 v27, 2, v27
	v_lshlrev_b32_e32 v28, 2, v28
	v_lshlrev_b32_e32 v29, 2, v29
	v_lshlrev_b32_e32 v30, 2, v30
	v_lshlrev_b32_e32 v31, 2, v31
	global_load_dword v32, v193, s[10:11]
	global_load_dword v33, v193, s[10:11] offset:256
	global_load_dword v34, v16, s[4:5]
	global_load_dword v35, v17, s[4:5]
	global_load_dword v36, v16, s[8:9]
	global_load_dword v37, v17, s[8:9]
	s_add_u32 s10, s10, s18
	s_addc_u32 s11, s11, 0
	global_load_dword v38, v193, s[10:11]
	global_load_dword v39, v193, s[10:11] offset:256
	global_load_dword v40, v18, s[4:5]
	global_load_dword v41, v19, s[4:5]
	global_load_dword v42, v18, s[8:9]
	global_load_dword v43, v19, s[8:9]
	s_add_u32 s10, s10, s18
	s_addc_u32 s11, s11, 0
	global_load_dword v44, v193, s[10:11]
	global_load_dword v45, v193, s[10:11] offset:256
	global_load_dword v46, v20, s[4:5]
	global_load_dword v47, v21, s[4:5]
	global_load_dword v48, v20, s[8:9]
	global_load_dword v49, v21, s[8:9]
	s_add_u32 s10, s10, s18
	s_addc_u32 s11, s11, 0
	global_load_dword v50, v193, s[10:11]
	global_load_dword v51, v193, s[10:11] offset:256
	global_load_dword v52, v22, s[4:5]
	global_load_dword v53, v23, s[4:5]
	global_load_dword v54, v22, s[8:9]
	global_load_dword v55, v23, s[8:9]
	s_add_u32 s10, s10, s18
	s_addc_u32 s11, s11, 0
	global_load_dword v56, v193, s[10:11]
	global_load_dword v57, v193, s[10:11] offset:256
	global_load_dword v58, v24, s[4:5]
	global_load_dword v59, v25, s[4:5]
	global_load_dword v60, v24, s[8:9]
	global_load_dword v61, v25, s[8:9]
	s_add_u32 s10, s10, s18
	s_addc_u32 s11, s11, 0
	global_load_dword v62, v193, s[10:11]
	global_load_dword v63, v193, s[10:11] offset:256
	global_load_dword v64, v26, s[4:5]
	global_load_dword v65, v27, s[4:5]
	global_load_dword v66, v26, s[8:9]
	global_load_dword v67, v27, s[8:9]
	s_add_u32 s10, s10, s18
	s_addc_u32 s11, s11, 0
	global_load_dword v68, v193, s[10:11]
	global_load_dword v69, v193, s[10:11] offset:256
	global_load_dword v70, v28, s[4:5]
	global_load_dword v71, v29, s[4:5]
	global_load_dword v72, v28, s[8:9]
	global_load_dword v73, v29, s[8:9]
	s_add_u32 s10, s10, s18
	s_addc_u32 s11, s11, 0
	global_load_dword v74, v193, s[10:11]
	global_load_dword v75, v193, s[10:11] offset:256
	global_load_dword v76, v30, s[4:5]
	global_load_dword v77, v31, s[4:5]
	global_load_dword v78, v30, s[8:9]
	global_load_dword v79, v31, s[8:9]
	s_add_u32 s10, s10, s18
	s_addc_u32 s11, s11, 0
	s_waitcnt vmcnt(0)
	v_mul_f32_e32 v80, v34, v80
	v_mul_f32_e32 v180, 0x3f3504f3, v80
	v_fma_f32 v182, |v180|, s16, v177
	v_fma_f32 v182, |v180|, v182, s19
	v_fma_f32 v182, |v180|, v182, s50
	v_fma_f32 v182, |v180|, v182, s51
	v_fma_f32 v182, |v180|, v182, s64
	v_fma_f32 v182, |v180|, v182, s65
	v_fma_f32 v182, |v180|, v182, |v180|
	v_mul_f32_e32 v184, 0xbfb8aa3b, v182
	v_fma_f32 v185, v182, s98, -v184
	v_rndne_f32_e32 v186, v184
	v_fmac_f32_e32 v185, 0xb2a5705f, v182
	v_sub_f32_e32 v184, v184, v186
	v_add_f32_e32 v184, v184, v185
	v_cvt_i32_f32_e32 v185, v186
	v_exp_f32_e32 v184, v184
	v_cmp_nlt_f32_e32 vcc, s70, v182
	v_ldexp_f32 v184, v184, v185
	s_nop 0
	v_cndmask_b32_e32 v184, 0, v184, vcc
	v_cmp_ngt_f32_e32 vcc, s71, v182
	s_nop 1
	v_cndmask_b32_e32 v184, v178, v184, vcc
	v_sub_f32_e32 v184, 1.0, v184
	v_mul_f32_e32 v183, v180, v180
	v_fmamk_f32 v185, v183, 0xba1345e1, v176
	v_fmaak_f32 v185, v183, v185, 0xbcdac9b8
	v_fmaak_f32 v185, v183, v185, 0x3de703be
	v_fmaak_f32 v185, v183, v185, 0xbec09330
	v_fmaak_f32 v183, v183, v185, 0x3e0375d0
	v_fma_f32 v183, |v180|, v183, |v180|
	v_cmp_nlt_f32_e64 vcc, |v180|, 1.0
	s_nop 1
	v_cndmask_b32_e32 v184, v183, v184, vcc
	v_bfi_b32 v184, s14, v184, v180
	v_add_f32_e32 v184, 1.0, v184
	v_mul_f32_e32 v80, 0.5, v80
	v_mul_f32_e32 v32, v32, v36
	v_mul_f32_e32 v80, v80, v184
	v_mul_f32_e32 v80, v32, v80
	v_mul_f32_e32 v81, v35, v81
	v_mul_f32_e32 v180, 0x3f3504f3, v81
	v_fma_f32 v182, |v180|, s16, v177
	v_fma_f32 v182, |v180|, v182, s19
	v_fma_f32 v182, |v180|, v182, s50
	v_fma_f32 v182, |v180|, v182, s51
	v_fma_f32 v182, |v180|, v182, s64
	v_fma_f32 v182, |v180|, v182, s65
	v_fma_f32 v182, |v180|, v182, |v180|
	v_mul_f32_e32 v184, 0xbfb8aa3b, v182
	v_fma_f32 v185, v182, s98, -v184
	v_rndne_f32_e32 v186, v184
	v_fmac_f32_e32 v185, 0xb2a5705f, v182
	v_sub_f32_e32 v184, v184, v186
	v_add_f32_e32 v184, v184, v185
	v_cvt_i32_f32_e32 v185, v186
	v_exp_f32_e32 v184, v184
	v_cmp_nlt_f32_e32 vcc, s70, v182
	v_ldexp_f32 v184, v184, v185
	s_nop 0
	v_cndmask_b32_e32 v184, 0, v184, vcc
	v_cmp_ngt_f32_e32 vcc, s71, v182
	s_nop 1
	v_cndmask_b32_e32 v184, v178, v184, vcc
	v_sub_f32_e32 v184, 1.0, v184
	v_mul_f32_e32 v183, v180, v180
	v_fmamk_f32 v185, v183, 0xba1345e1, v176
	v_fmaak_f32 v185, v183, v185, 0xbcdac9b8
	v_fmaak_f32 v185, v183, v185, 0x3de703be
	v_fmaak_f32 v185, v183, v185, 0xbec09330
	v_fmaak_f32 v183, v183, v185, 0x3e0375d0
	v_fma_f32 v183, |v180|, v183, |v180|
	v_cmp_nlt_f32_e64 vcc, |v180|, 1.0
	s_nop 1
	v_cndmask_b32_e32 v184, v183, v184, vcc
	v_bfi_b32 v184, s14, v184, v180
	v_add_f32_e32 v184, 1.0, v184
	v_mul_f32_e32 v81, 0.5, v81
	v_mul_f32_e32 v33, v33, v37
	v_mul_f32_e32 v81, v81, v184
	v_mul_f32_e32 v81, v33, v81
	global_store_dword v193, v80, s[12:13]
	global_store_dword v193, v81, s[12:13] offset:256
	s_add_u32 s12, s12, s18
	s_addc_u32 s13, s13, 0
	v_mul_f32_e32 v82, v40, v82
	v_mul_f32_e32 v180, 0x3f3504f3, v82
	v_fma_f32 v182, |v180|, s16, v177
	v_fma_f32 v182, |v180|, v182, s19
	v_fma_f32 v182, |v180|, v182, s50
	v_fma_f32 v182, |v180|, v182, s51
	v_fma_f32 v182, |v180|, v182, s64
	v_fma_f32 v182, |v180|, v182, s65
	v_fma_f32 v182, |v180|, v182, |v180|
	v_mul_f32_e32 v184, 0xbfb8aa3b, v182
	v_fma_f32 v185, v182, s98, -v184
	v_rndne_f32_e32 v186, v184
	v_fmac_f32_e32 v185, 0xb2a5705f, v182
	v_sub_f32_e32 v184, v184, v186
	v_add_f32_e32 v184, v184, v185
	v_cvt_i32_f32_e32 v185, v186
	v_exp_f32_e32 v184, v184
	v_cmp_nlt_f32_e32 vcc, s70, v182
	v_ldexp_f32 v184, v184, v185
	s_nop 0
	v_cndmask_b32_e32 v184, 0, v184, vcc
	v_cmp_ngt_f32_e32 vcc, s71, v182
	s_nop 1
	v_cndmask_b32_e32 v184, v178, v184, vcc
	v_sub_f32_e32 v184, 1.0, v184
	v_mul_f32_e32 v183, v180, v180
	v_fmamk_f32 v185, v183, 0xba1345e1, v176
	v_fmaak_f32 v185, v183, v185, 0xbcdac9b8
	v_fmaak_f32 v185, v183, v185, 0x3de703be
	v_fmaak_f32 v185, v183, v185, 0xbec09330
	v_fmaak_f32 v183, v183, v185, 0x3e0375d0
	v_fma_f32 v183, |v180|, v183, |v180|
	v_cmp_nlt_f32_e64 vcc, |v180|, 1.0
	s_nop 1
	v_cndmask_b32_e32 v184, v183, v184, vcc
	v_bfi_b32 v184, s14, v184, v180
	v_add_f32_e32 v184, 1.0, v184
	v_mul_f32_e32 v82, 0.5, v82
	v_mul_f32_e32 v38, v38, v42
	v_mul_f32_e32 v82, v82, v184
	v_mul_f32_e32 v82, v38, v82
	v_mul_f32_e32 v83, v41, v83
	v_mul_f32_e32 v180, 0x3f3504f3, v83
	v_fma_f32 v182, |v180|, s16, v177
	v_fma_f32 v182, |v180|, v182, s19
	v_fma_f32 v182, |v180|, v182, s50
	v_fma_f32 v182, |v180|, v182, s51
	v_fma_f32 v182, |v180|, v182, s64
	v_fma_f32 v182, |v180|, v182, s65
	v_fma_f32 v182, |v180|, v182, |v180|
	v_mul_f32_e32 v184, 0xbfb8aa3b, v182
	v_fma_f32 v185, v182, s98, -v184
	v_rndne_f32_e32 v186, v184
	v_fmac_f32_e32 v185, 0xb2a5705f, v182
	v_sub_f32_e32 v184, v184, v186
	v_add_f32_e32 v184, v184, v185
	v_cvt_i32_f32_e32 v185, v186
	v_exp_f32_e32 v184, v184
	v_cmp_nlt_f32_e32 vcc, s70, v182
	v_ldexp_f32 v184, v184, v185
	s_nop 0
	v_cndmask_b32_e32 v184, 0, v184, vcc
	v_cmp_ngt_f32_e32 vcc, s71, v182
	s_nop 1
	v_cndmask_b32_e32 v184, v178, v184, vcc
	v_sub_f32_e32 v184, 1.0, v184
	v_mul_f32_e32 v183, v180, v180
	v_fmamk_f32 v185, v183, 0xba1345e1, v176
	v_fmaak_f32 v185, v183, v185, 0xbcdac9b8
	v_fmaak_f32 v185, v183, v185, 0x3de703be
	v_fmaak_f32 v185, v183, v185, 0xbec09330
	v_fmaak_f32 v183, v183, v185, 0x3e0375d0
	v_fma_f32 v183, |v180|, v183, |v180|
	v_cmp_nlt_f32_e64 vcc, |v180|, 1.0
	s_nop 1
	v_cndmask_b32_e32 v184, v183, v184, vcc
	v_bfi_b32 v184, s14, v184, v180
	v_add_f32_e32 v184, 1.0, v184
	v_mul_f32_e32 v83, 0.5, v83
	v_mul_f32_e32 v39, v39, v43
	v_mul_f32_e32 v83, v83, v184
	v_mul_f32_e32 v83, v39, v83
	global_store_dword v193, v82, s[12:13]
	global_store_dword v193, v83, s[12:13] offset:256
	s_add_u32 s12, s12, s18
	s_addc_u32 s13, s13, 0
	v_mul_f32_e32 v84, v46, v84
	v_mul_f32_e32 v180, 0x3f3504f3, v84
	v_fma_f32 v182, |v180|, s16, v177
	v_fma_f32 v182, |v180|, v182, s19
	v_fma_f32 v182, |v180|, v182, s50
	v_fma_f32 v182, |v180|, v182, s51
	v_fma_f32 v182, |v180|, v182, s64
	v_fma_f32 v182, |v180|, v182, s65
	v_fma_f32 v182, |v180|, v182, |v180|
	v_mul_f32_e32 v184, 0xbfb8aa3b, v182
	v_fma_f32 v185, v182, s98, -v184
	v_rndne_f32_e32 v186, v184
	v_fmac_f32_e32 v185, 0xb2a5705f, v182
	v_sub_f32_e32 v184, v184, v186
	v_add_f32_e32 v184, v184, v185
	v_cvt_i32_f32_e32 v185, v186
	v_exp_f32_e32 v184, v184
	v_cmp_nlt_f32_e32 vcc, s70, v182
	v_ldexp_f32 v184, v184, v185
	s_nop 0
	v_cndmask_b32_e32 v184, 0, v184, vcc
	v_cmp_ngt_f32_e32 vcc, s71, v182
	s_nop 1
	v_cndmask_b32_e32 v184, v178, v184, vcc
	v_sub_f32_e32 v184, 1.0, v184
	v_mul_f32_e32 v183, v180, v180
	v_fmamk_f32 v185, v183, 0xba1345e1, v176
	v_fmaak_f32 v185, v183, v185, 0xbcdac9b8
	v_fmaak_f32 v185, v183, v185, 0x3de703be
	v_fmaak_f32 v185, v183, v185, 0xbec09330
	v_fmaak_f32 v183, v183, v185, 0x3e0375d0
	v_fma_f32 v183, |v180|, v183, |v180|
	v_cmp_nlt_f32_e64 vcc, |v180|, 1.0
	s_nop 1
	v_cndmask_b32_e32 v184, v183, v184, vcc
	v_bfi_b32 v184, s14, v184, v180
	v_add_f32_e32 v184, 1.0, v184
	v_mul_f32_e32 v84, 0.5, v84
	v_mul_f32_e32 v44, v44, v48
	v_mul_f32_e32 v84, v84, v184
	v_mul_f32_e32 v84, v44, v84
	v_mul_f32_e32 v85, v47, v85
	v_mul_f32_e32 v180, 0x3f3504f3, v85
	v_fma_f32 v182, |v180|, s16, v177
	v_fma_f32 v182, |v180|, v182, s19
	v_fma_f32 v182, |v180|, v182, s50
	v_fma_f32 v182, |v180|, v182, s51
	v_fma_f32 v182, |v180|, v182, s64
	v_fma_f32 v182, |v180|, v182, s65
	v_fma_f32 v182, |v180|, v182, |v180|
	v_mul_f32_e32 v184, 0xbfb8aa3b, v182
	v_fma_f32 v185, v182, s98, -v184
	v_rndne_f32_e32 v186, v184
	v_fmac_f32_e32 v185, 0xb2a5705f, v182
	v_sub_f32_e32 v184, v184, v186
	v_add_f32_e32 v184, v184, v185
	v_cvt_i32_f32_e32 v185, v186
	v_exp_f32_e32 v184, v184
	v_cmp_nlt_f32_e32 vcc, s70, v182
	v_ldexp_f32 v184, v184, v185
	s_nop 0
	v_cndmask_b32_e32 v184, 0, v184, vcc
	v_cmp_ngt_f32_e32 vcc, s71, v182
	s_nop 1
	v_cndmask_b32_e32 v184, v178, v184, vcc
	v_sub_f32_e32 v184, 1.0, v184
	v_mul_f32_e32 v183, v180, v180
	v_fmamk_f32 v185, v183, 0xba1345e1, v176
	v_fmaak_f32 v185, v183, v185, 0xbcdac9b8
	v_fmaak_f32 v185, v183, v185, 0x3de703be
	v_fmaak_f32 v185, v183, v185, 0xbec09330
	v_fmaak_f32 v183, v183, v185, 0x3e0375d0
	v_fma_f32 v183, |v180|, v183, |v180|
	v_cmp_nlt_f32_e64 vcc, |v180|, 1.0
	s_nop 1
	v_cndmask_b32_e32 v184, v183, v184, vcc
	v_bfi_b32 v184, s14, v184, v180
	v_add_f32_e32 v184, 1.0, v184
	v_mul_f32_e32 v85, 0.5, v85
	v_mul_f32_e32 v45, v45, v49
	v_mul_f32_e32 v85, v85, v184
	v_mul_f32_e32 v85, v45, v85
	global_store_dword v193, v84, s[12:13]
	global_store_dword v193, v85, s[12:13] offset:256
	s_add_u32 s12, s12, s18
	s_addc_u32 s13, s13, 0
	v_mul_f32_e32 v86, v52, v86
	v_mul_f32_e32 v180, 0x3f3504f3, v86
	v_fma_f32 v182, |v180|, s16, v177
	v_fma_f32 v182, |v180|, v182, s19
	v_fma_f32 v182, |v180|, v182, s50
	v_fma_f32 v182, |v180|, v182, s51
	v_fma_f32 v182, |v180|, v182, s64
	v_fma_f32 v182, |v180|, v182, s65
	v_fma_f32 v182, |v180|, v182, |v180|
	v_mul_f32_e32 v184, 0xbfb8aa3b, v182
	v_fma_f32 v185, v182, s98, -v184
	v_rndne_f32_e32 v186, v184
	v_fmac_f32_e32 v185, 0xb2a5705f, v182
	v_sub_f32_e32 v184, v184, v186
	v_add_f32_e32 v184, v184, v185
	v_cvt_i32_f32_e32 v185, v186
	v_exp_f32_e32 v184, v184
	v_cmp_nlt_f32_e32 vcc, s70, v182
	v_ldexp_f32 v184, v184, v185
	s_nop 0
	v_cndmask_b32_e32 v184, 0, v184, vcc
	v_cmp_ngt_f32_e32 vcc, s71, v182
	s_nop 1
	v_cndmask_b32_e32 v184, v178, v184, vcc
	v_sub_f32_e32 v184, 1.0, v184
	v_mul_f32_e32 v183, v180, v180
	v_fmamk_f32 v185, v183, 0xba1345e1, v176
	v_fmaak_f32 v185, v183, v185, 0xbcdac9b8
	v_fmaak_f32 v185, v183, v185, 0x3de703be
	v_fmaak_f32 v185, v183, v185, 0xbec09330
	v_fmaak_f32 v183, v183, v185, 0x3e0375d0
	v_fma_f32 v183, |v180|, v183, |v180|
	v_cmp_nlt_f32_e64 vcc, |v180|, 1.0
	s_nop 1
	v_cndmask_b32_e32 v184, v183, v184, vcc
	v_bfi_b32 v184, s14, v184, v180
	v_add_f32_e32 v184, 1.0, v184
	v_mul_f32_e32 v86, 0.5, v86
	v_mul_f32_e32 v50, v50, v54
	v_mul_f32_e32 v86, v86, v184
	v_mul_f32_e32 v86, v50, v86
	v_mul_f32_e32 v87, v53, v87
	v_mul_f32_e32 v180, 0x3f3504f3, v87
	v_fma_f32 v182, |v180|, s16, v177
	v_fma_f32 v182, |v180|, v182, s19
	v_fma_f32 v182, |v180|, v182, s50
	v_fma_f32 v182, |v180|, v182, s51
	v_fma_f32 v182, |v180|, v182, s64
	v_fma_f32 v182, |v180|, v182, s65
	v_fma_f32 v182, |v180|, v182, |v180|
	v_mul_f32_e32 v184, 0xbfb8aa3b, v182
	v_fma_f32 v185, v182, s98, -v184
	v_rndne_f32_e32 v186, v184
	v_fmac_f32_e32 v185, 0xb2a5705f, v182
	v_sub_f32_e32 v184, v184, v186
	v_add_f32_e32 v184, v184, v185
	v_cvt_i32_f32_e32 v185, v186
	v_exp_f32_e32 v184, v184
	v_cmp_nlt_f32_e32 vcc, s70, v182
	v_ldexp_f32 v184, v184, v185
	s_nop 0
	v_cndmask_b32_e32 v184, 0, v184, vcc
	v_cmp_ngt_f32_e32 vcc, s71, v182
	s_nop 1
	v_cndmask_b32_e32 v184, v178, v184, vcc
	v_sub_f32_e32 v184, 1.0, v184
	v_mul_f32_e32 v183, v180, v180
	v_fmamk_f32 v185, v183, 0xba1345e1, v176
	v_fmaak_f32 v185, v183, v185, 0xbcdac9b8
	v_fmaak_f32 v185, v183, v185, 0x3de703be
	v_fmaak_f32 v185, v183, v185, 0xbec09330
	v_fmaak_f32 v183, v183, v185, 0x3e0375d0
	v_fma_f32 v183, |v180|, v183, |v180|
	v_cmp_nlt_f32_e64 vcc, |v180|, 1.0
	s_nop 1
	v_cndmask_b32_e32 v184, v183, v184, vcc
	v_bfi_b32 v184, s14, v184, v180
	v_add_f32_e32 v184, 1.0, v184
	v_mul_f32_e32 v87, 0.5, v87
	v_mul_f32_e32 v51, v51, v55
	v_mul_f32_e32 v87, v87, v184
	v_mul_f32_e32 v87, v51, v87
	global_store_dword v193, v86, s[12:13]
	global_store_dword v193, v87, s[12:13] offset:256
	s_add_u32 s12, s12, s18
	s_addc_u32 s13, s13, 0
	v_mul_f32_e32 v88, v58, v88
	v_mul_f32_e32 v180, 0x3f3504f3, v88
	v_fma_f32 v182, |v180|, s16, v177
	v_fma_f32 v182, |v180|, v182, s19
	v_fma_f32 v182, |v180|, v182, s50
	v_fma_f32 v182, |v180|, v182, s51
	v_fma_f32 v182, |v180|, v182, s64
	v_fma_f32 v182, |v180|, v182, s65
	v_fma_f32 v182, |v180|, v182, |v180|
	v_mul_f32_e32 v184, 0xbfb8aa3b, v182
	v_fma_f32 v185, v182, s98, -v184
	v_rndne_f32_e32 v186, v184
	v_fmac_f32_e32 v185, 0xb2a5705f, v182
	v_sub_f32_e32 v184, v184, v186
	v_add_f32_e32 v184, v184, v185
	v_cvt_i32_f32_e32 v185, v186
	v_exp_f32_e32 v184, v184
	v_cmp_nlt_f32_e32 vcc, s70, v182
	v_ldexp_f32 v184, v184, v185
	s_nop 0
	v_cndmask_b32_e32 v184, 0, v184, vcc
	v_cmp_ngt_f32_e32 vcc, s71, v182
	s_nop 1
	v_cndmask_b32_e32 v184, v178, v184, vcc
	v_sub_f32_e32 v184, 1.0, v184
	v_mul_f32_e32 v183, v180, v180
	v_fmamk_f32 v185, v183, 0xba1345e1, v176
	v_fmaak_f32 v185, v183, v185, 0xbcdac9b8
	v_fmaak_f32 v185, v183, v185, 0x3de703be
	v_fmaak_f32 v185, v183, v185, 0xbec09330
	v_fmaak_f32 v183, v183, v185, 0x3e0375d0
	v_fma_f32 v183, |v180|, v183, |v180|
	v_cmp_nlt_f32_e64 vcc, |v180|, 1.0
	s_nop 1
	v_cndmask_b32_e32 v184, v183, v184, vcc
	v_bfi_b32 v184, s14, v184, v180
	v_add_f32_e32 v184, 1.0, v184
	v_mul_f32_e32 v88, 0.5, v88
	v_mul_f32_e32 v56, v56, v60
	v_mul_f32_e32 v88, v88, v184
	v_mul_f32_e32 v88, v56, v88
	v_mul_f32_e32 v89, v59, v89
	v_mul_f32_e32 v180, 0x3f3504f3, v89
	v_fma_f32 v182, |v180|, s16, v177
	v_fma_f32 v182, |v180|, v182, s19
	v_fma_f32 v182, |v180|, v182, s50
	v_fma_f32 v182, |v180|, v182, s51
	v_fma_f32 v182, |v180|, v182, s64
	v_fma_f32 v182, |v180|, v182, s65
	v_fma_f32 v182, |v180|, v182, |v180|
	v_mul_f32_e32 v184, 0xbfb8aa3b, v182
	v_fma_f32 v185, v182, s98, -v184
	v_rndne_f32_e32 v186, v184
	v_fmac_f32_e32 v185, 0xb2a5705f, v182
	v_sub_f32_e32 v184, v184, v186
	v_add_f32_e32 v184, v184, v185
	v_cvt_i32_f32_e32 v185, v186
	v_exp_f32_e32 v184, v184
	v_cmp_nlt_f32_e32 vcc, s70, v182
	v_ldexp_f32 v184, v184, v185
	s_nop 0
	v_cndmask_b32_e32 v184, 0, v184, vcc
	v_cmp_ngt_f32_e32 vcc, s71, v182
	s_nop 1
	v_cndmask_b32_e32 v184, v178, v184, vcc
	v_sub_f32_e32 v184, 1.0, v184
	v_mul_f32_e32 v183, v180, v180
	v_fmamk_f32 v185, v183, 0xba1345e1, v176
	v_fmaak_f32 v185, v183, v185, 0xbcdac9b8
	v_fmaak_f32 v185, v183, v185, 0x3de703be
	v_fmaak_f32 v185, v183, v185, 0xbec09330
	v_fmaak_f32 v183, v183, v185, 0x3e0375d0
	v_fma_f32 v183, |v180|, v183, |v180|
	v_cmp_nlt_f32_e64 vcc, |v180|, 1.0
	s_nop 1
	v_cndmask_b32_e32 v184, v183, v184, vcc
	v_bfi_b32 v184, s14, v184, v180
	v_add_f32_e32 v184, 1.0, v184
	v_mul_f32_e32 v89, 0.5, v89
	v_mul_f32_e32 v57, v57, v61
	v_mul_f32_e32 v89, v89, v184
	v_mul_f32_e32 v89, v57, v89
	global_store_dword v193, v88, s[12:13]
	global_store_dword v193, v89, s[12:13] offset:256
	s_add_u32 s12, s12, s18
	s_addc_u32 s13, s13, 0
	v_mul_f32_e32 v90, v64, v90
	v_mul_f32_e32 v180, 0x3f3504f3, v90
	v_fma_f32 v182, |v180|, s16, v177
	v_fma_f32 v182, |v180|, v182, s19
	v_fma_f32 v182, |v180|, v182, s50
	v_fma_f32 v182, |v180|, v182, s51
	v_fma_f32 v182, |v180|, v182, s64
	v_fma_f32 v182, |v180|, v182, s65
	v_fma_f32 v182, |v180|, v182, |v180|
	v_mul_f32_e32 v184, 0xbfb8aa3b, v182
	v_fma_f32 v185, v182, s98, -v184
	v_rndne_f32_e32 v186, v184
	v_fmac_f32_e32 v185, 0xb2a5705f, v182
	v_sub_f32_e32 v184, v184, v186
	v_add_f32_e32 v184, v184, v185
	v_cvt_i32_f32_e32 v185, v186
	v_exp_f32_e32 v184, v184
	v_cmp_nlt_f32_e32 vcc, s70, v182
	v_ldexp_f32 v184, v184, v185
	s_nop 0
	v_cndmask_b32_e32 v184, 0, v184, vcc
	v_cmp_ngt_f32_e32 vcc, s71, v182
	s_nop 1
	v_cndmask_b32_e32 v184, v178, v184, vcc
	v_sub_f32_e32 v184, 1.0, v184
	v_mul_f32_e32 v183, v180, v180
	v_fmamk_f32 v185, v183, 0xba1345e1, v176
	v_fmaak_f32 v185, v183, v185, 0xbcdac9b8
	v_fmaak_f32 v185, v183, v185, 0x3de703be
	v_fmaak_f32 v185, v183, v185, 0xbec09330
	v_fmaak_f32 v183, v183, v185, 0x3e0375d0
	v_fma_f32 v183, |v180|, v183, |v180|
	v_cmp_nlt_f32_e64 vcc, |v180|, 1.0
	s_nop 1
	v_cndmask_b32_e32 v184, v183, v184, vcc
	v_bfi_b32 v184, s14, v184, v180
	v_add_f32_e32 v184, 1.0, v184
	v_mul_f32_e32 v90, 0.5, v90
	v_mul_f32_e32 v62, v62, v66
	v_mul_f32_e32 v90, v90, v184
	v_mul_f32_e32 v90, v62, v90
	v_mul_f32_e32 v91, v65, v91
	v_mul_f32_e32 v180, 0x3f3504f3, v91
	v_fma_f32 v182, |v180|, s16, v177
	v_fma_f32 v182, |v180|, v182, s19
	v_fma_f32 v182, |v180|, v182, s50
	v_fma_f32 v182, |v180|, v182, s51
	v_fma_f32 v182, |v180|, v182, s64
	v_fma_f32 v182, |v180|, v182, s65
	v_fma_f32 v182, |v180|, v182, |v180|
	v_mul_f32_e32 v184, 0xbfb8aa3b, v182
	v_fma_f32 v185, v182, s98, -v184
	v_rndne_f32_e32 v186, v184
	v_fmac_f32_e32 v185, 0xb2a5705f, v182
	v_sub_f32_e32 v184, v184, v186
	v_add_f32_e32 v184, v184, v185
	v_cvt_i32_f32_e32 v185, v186
	v_exp_f32_e32 v184, v184
	v_cmp_nlt_f32_e32 vcc, s70, v182
	v_ldexp_f32 v184, v184, v185
	s_nop 0
	v_cndmask_b32_e32 v184, 0, v184, vcc
	v_cmp_ngt_f32_e32 vcc, s71, v182
	s_nop 1
	v_cndmask_b32_e32 v184, v178, v184, vcc
	v_sub_f32_e32 v184, 1.0, v184
	v_mul_f32_e32 v183, v180, v180
	v_fmamk_f32 v185, v183, 0xba1345e1, v176
	v_fmaak_f32 v185, v183, v185, 0xbcdac9b8
	v_fmaak_f32 v185, v183, v185, 0x3de703be
	v_fmaak_f32 v185, v183, v185, 0xbec09330
	v_fmaak_f32 v183, v183, v185, 0x3e0375d0
	v_fma_f32 v183, |v180|, v183, |v180|
	v_cmp_nlt_f32_e64 vcc, |v180|, 1.0
	s_nop 1
	v_cndmask_b32_e32 v184, v183, v184, vcc
	v_bfi_b32 v184, s14, v184, v180
	v_add_f32_e32 v184, 1.0, v184
	v_mul_f32_e32 v91, 0.5, v91
	v_mul_f32_e32 v63, v63, v67
	v_mul_f32_e32 v91, v91, v184
	v_mul_f32_e32 v91, v63, v91
	global_store_dword v193, v90, s[12:13]
	global_store_dword v193, v91, s[12:13] offset:256
	s_add_u32 s12, s12, s18
	s_addc_u32 s13, s13, 0
	v_mul_f32_e32 v92, v70, v92
	v_mul_f32_e32 v180, 0x3f3504f3, v92
	v_fma_f32 v182, |v180|, s16, v177
	v_fma_f32 v182, |v180|, v182, s19
	v_fma_f32 v182, |v180|, v182, s50
	v_fma_f32 v182, |v180|, v182, s51
	v_fma_f32 v182, |v180|, v182, s64
	v_fma_f32 v182, |v180|, v182, s65
	v_fma_f32 v182, |v180|, v182, |v180|
	v_mul_f32_e32 v184, 0xbfb8aa3b, v182
	v_fma_f32 v185, v182, s98, -v184
	v_rndne_f32_e32 v186, v184
	v_fmac_f32_e32 v185, 0xb2a5705f, v182
	v_sub_f32_e32 v184, v184, v186
	v_add_f32_e32 v184, v184, v185
	v_cvt_i32_f32_e32 v185, v186
	v_exp_f32_e32 v184, v184
	v_cmp_nlt_f32_e32 vcc, s70, v182
	v_ldexp_f32 v184, v184, v185
	s_nop 0
	v_cndmask_b32_e32 v184, 0, v184, vcc
	v_cmp_ngt_f32_e32 vcc, s71, v182
	s_nop 1
	v_cndmask_b32_e32 v184, v178, v184, vcc
	v_sub_f32_e32 v184, 1.0, v184
	v_mul_f32_e32 v183, v180, v180
	v_fmamk_f32 v185, v183, 0xba1345e1, v176
	v_fmaak_f32 v185, v183, v185, 0xbcdac9b8
	v_fmaak_f32 v185, v183, v185, 0x3de703be
	v_fmaak_f32 v185, v183, v185, 0xbec09330
	v_fmaak_f32 v183, v183, v185, 0x3e0375d0
	v_fma_f32 v183, |v180|, v183, |v180|
	v_cmp_nlt_f32_e64 vcc, |v180|, 1.0
	s_nop 1
	v_cndmask_b32_e32 v184, v183, v184, vcc
	v_bfi_b32 v184, s14, v184, v180
	v_add_f32_e32 v184, 1.0, v184
	v_mul_f32_e32 v92, 0.5, v92
	v_mul_f32_e32 v68, v68, v72
	v_mul_f32_e32 v92, v92, v184
	v_mul_f32_e32 v92, v68, v92
	v_mul_f32_e32 v93, v71, v93
	v_mul_f32_e32 v180, 0x3f3504f3, v93
	v_fma_f32 v182, |v180|, s16, v177
	v_fma_f32 v182, |v180|, v182, s19
	v_fma_f32 v182, |v180|, v182, s50
	v_fma_f32 v182, |v180|, v182, s51
	v_fma_f32 v182, |v180|, v182, s64
	v_fma_f32 v182, |v180|, v182, s65
	v_fma_f32 v182, |v180|, v182, |v180|
	v_mul_f32_e32 v184, 0xbfb8aa3b, v182
	v_fma_f32 v185, v182, s98, -v184
	v_rndne_f32_e32 v186, v184
	v_fmac_f32_e32 v185, 0xb2a5705f, v182
	v_sub_f32_e32 v184, v184, v186
	v_add_f32_e32 v184, v184, v185
	v_cvt_i32_f32_e32 v185, v186
	v_exp_f32_e32 v184, v184
	v_cmp_nlt_f32_e32 vcc, s70, v182
	v_ldexp_f32 v184, v184, v185
	s_nop 0
	v_cndmask_b32_e32 v184, 0, v184, vcc
	v_cmp_ngt_f32_e32 vcc, s71, v182
	s_nop 1
	v_cndmask_b32_e32 v184, v178, v184, vcc
	v_sub_f32_e32 v184, 1.0, v184
	v_mul_f32_e32 v183, v180, v180
	v_fmamk_f32 v185, v183, 0xba1345e1, v176
	v_fmaak_f32 v185, v183, v185, 0xbcdac9b8
	v_fmaak_f32 v185, v183, v185, 0x3de703be
	v_fmaak_f32 v185, v183, v185, 0xbec09330
	v_fmaak_f32 v183, v183, v185, 0x3e0375d0
	v_fma_f32 v183, |v180|, v183, |v180|
	v_cmp_nlt_f32_e64 vcc, |v180|, 1.0
	s_nop 1
	v_cndmask_b32_e32 v184, v183, v184, vcc
	v_bfi_b32 v184, s14, v184, v180
	v_add_f32_e32 v184, 1.0, v184
	v_mul_f32_e32 v93, 0.5, v93
	v_mul_f32_e32 v69, v69, v73
	v_mul_f32_e32 v93, v93, v184
	v_mul_f32_e32 v93, v69, v93
	global_store_dword v193, v92, s[12:13]
	global_store_dword v193, v93, s[12:13] offset:256
	s_add_u32 s12, s12, s18
	s_addc_u32 s13, s13, 0
	v_mul_f32_e32 v94, v76, v94
	v_mul_f32_e32 v180, 0x3f3504f3, v94
	v_fma_f32 v182, |v180|, s16, v177
	v_fma_f32 v182, |v180|, v182, s19
	v_fma_f32 v182, |v180|, v182, s50
	v_fma_f32 v182, |v180|, v182, s51
	v_fma_f32 v182, |v180|, v182, s64
	v_fma_f32 v182, |v180|, v182, s65
	v_fma_f32 v182, |v180|, v182, |v180|
	v_mul_f32_e32 v184, 0xbfb8aa3b, v182
	v_fma_f32 v185, v182, s98, -v184
	v_rndne_f32_e32 v186, v184
	v_fmac_f32_e32 v185, 0xb2a5705f, v182
	v_sub_f32_e32 v184, v184, v186
	v_add_f32_e32 v184, v184, v185
	v_cvt_i32_f32_e32 v185, v186
	v_exp_f32_e32 v184, v184
	v_cmp_nlt_f32_e32 vcc, s70, v182
	v_ldexp_f32 v184, v184, v185
	s_nop 0
	v_cndmask_b32_e32 v184, 0, v184, vcc
	v_cmp_ngt_f32_e32 vcc, s71, v182
	s_nop 1
	v_cndmask_b32_e32 v184, v178, v184, vcc
	v_sub_f32_e32 v184, 1.0, v184
	v_mul_f32_e32 v183, v180, v180
	v_fmamk_f32 v185, v183, 0xba1345e1, v176
	v_fmaak_f32 v185, v183, v185, 0xbcdac9b8
	v_fmaak_f32 v185, v183, v185, 0x3de703be
	v_fmaak_f32 v185, v183, v185, 0xbec09330
	v_fmaak_f32 v183, v183, v185, 0x3e0375d0
	v_fma_f32 v183, |v180|, v183, |v180|
	v_cmp_nlt_f32_e64 vcc, |v180|, 1.0
	s_nop 1
	v_cndmask_b32_e32 v184, v183, v184, vcc
	v_bfi_b32 v184, s14, v184, v180
	v_add_f32_e32 v184, 1.0, v184
	v_mul_f32_e32 v94, 0.5, v94
	v_mul_f32_e32 v74, v74, v78
	v_mul_f32_e32 v94, v94, v184
	v_mul_f32_e32 v94, v74, v94
	v_mul_f32_e32 v95, v77, v95
	v_mul_f32_e32 v180, 0x3f3504f3, v95
	v_fma_f32 v182, |v180|, s16, v177
	v_fma_f32 v182, |v180|, v182, s19
	v_fma_f32 v182, |v180|, v182, s50
	v_fma_f32 v182, |v180|, v182, s51
	v_fma_f32 v182, |v180|, v182, s64
	v_fma_f32 v182, |v180|, v182, s65
	v_fma_f32 v182, |v180|, v182, |v180|
	v_mul_f32_e32 v184, 0xbfb8aa3b, v182
	v_fma_f32 v185, v182, s98, -v184
	v_rndne_f32_e32 v186, v184
	v_fmac_f32_e32 v185, 0xb2a5705f, v182
	v_sub_f32_e32 v184, v184, v186
	v_add_f32_e32 v184, v184, v185
	v_cvt_i32_f32_e32 v185, v186
	v_exp_f32_e32 v184, v184
	v_cmp_nlt_f32_e32 vcc, s70, v182
	v_ldexp_f32 v184, v184, v185
	s_nop 0
	v_cndmask_b32_e32 v184, 0, v184, vcc
	v_cmp_ngt_f32_e32 vcc, s71, v182
	s_nop 1
	v_cndmask_b32_e32 v184, v178, v184, vcc
	v_sub_f32_e32 v184, 1.0, v184
	v_mul_f32_e32 v183, v180, v180
	v_fmamk_f32 v185, v183, 0xba1345e1, v176
	v_fmaak_f32 v185, v183, v185, 0xbcdac9b8
	v_fmaak_f32 v185, v183, v185, 0x3de703be
	v_fmaak_f32 v185, v183, v185, 0xbec09330
	v_fmaak_f32 v183, v183, v185, 0x3e0375d0
	v_fma_f32 v183, |v180|, v183, |v180|
	v_cmp_nlt_f32_e64 vcc, |v180|, 1.0
	s_nop 1
	v_cndmask_b32_e32 v184, v183, v184, vcc
	v_bfi_b32 v184, s14, v184, v180
	v_add_f32_e32 v184, 1.0, v184
	v_mul_f32_e32 v95, 0.5, v95
	v_mul_f32_e32 v75, v75, v79
	v_mul_f32_e32 v95, v95, v184
	v_mul_f32_e32 v95, v75, v95
	global_store_dword v193, v94, s[12:13]
	global_store_dword v193, v95, s[12:13] offset:256
	s_add_u32 s12, s12, s18
	s_addc_u32 s13, s13, 0
	ds_read2st64_b32 v[16:17], v199 offset0:16 offset1:17
	ds_read2st64_b32 v[80:81], v200 offset0:16 offset1:17
	ds_read2st64_b32 v[18:19], v199 offset0:18 offset1:19
	ds_read2st64_b32 v[82:83], v200 offset0:18 offset1:19
	ds_read2st64_b32 v[20:21], v199 offset0:20 offset1:21
	ds_read2st64_b32 v[84:85], v200 offset0:20 offset1:21
	ds_read2st64_b32 v[22:23], v199 offset0:22 offset1:23
	ds_read2st64_b32 v[86:87], v200 offset0:22 offset1:23
	ds_read2st64_b32 v[24:25], v199 offset0:24 offset1:25
	ds_read2st64_b32 v[88:89], v200 offset0:24 offset1:25
	ds_read2st64_b32 v[26:27], v199 offset0:26 offset1:27
	ds_read2st64_b32 v[90:91], v200 offset0:26 offset1:27
	ds_read2st64_b32 v[28:29], v199 offset0:28 offset1:29
	ds_read2st64_b32 v[92:93], v200 offset0:28 offset1:29
	ds_read2st64_b32 v[30:31], v199 offset0:30 offset1:31
	ds_read2st64_b32 v[94:95], v200 offset0:30 offset1:31
	s_waitcnt lgkmcnt(0)
	v_lshlrev_b32_e32 v16, 2, v16
	v_lshlrev_b32_e32 v17, 2, v17
	v_lshlrev_b32_e32 v18, 2, v18
	v_lshlrev_b32_e32 v19, 2, v19
	v_lshlrev_b32_e32 v20, 2, v20
	v_lshlrev_b32_e32 v21, 2, v21
	v_lshlrev_b32_e32 v22, 2, v22
	v_lshlrev_b32_e32 v23, 2, v23
	v_lshlrev_b32_e32 v24, 2, v24
	v_lshlrev_b32_e32 v25, 2, v25
	v_lshlrev_b32_e32 v26, 2, v26
	v_lshlrev_b32_e32 v27, 2, v27
	v_lshlrev_b32_e32 v28, 2, v28
	v_lshlrev_b32_e32 v29, 2, v29
	v_lshlrev_b32_e32 v30, 2, v30
	v_lshlrev_b32_e32 v31, 2, v31
	global_load_dword v32, v193, s[10:11]
	global_load_dword v33, v193, s[10:11] offset:256
	global_load_dword v34, v16, s[4:5]
	global_load_dword v35, v17, s[4:5]
	global_load_dword v36, v16, s[8:9]
	global_load_dword v37, v17, s[8:9]
	s_add_u32 s10, s10, s18
	s_addc_u32 s11, s11, 0
	global_load_dword v38, v193, s[10:11]
	global_load_dword v39, v193, s[10:11] offset:256
	global_load_dword v40, v18, s[4:5]
	global_load_dword v41, v19, s[4:5]
	global_load_dword v42, v18, s[8:9]
	global_load_dword v43, v19, s[8:9]
	s_add_u32 s10, s10, s18
	s_addc_u32 s11, s11, 0
	global_load_dword v44, v193, s[10:11]
	global_load_dword v45, v193, s[10:11] offset:256
	global_load_dword v46, v20, s[4:5]
	global_load_dword v47, v21, s[4:5]
	global_load_dword v48, v20, s[8:9]
	global_load_dword v49, v21, s[8:9]
	s_add_u32 s10, s10, s18
	s_addc_u32 s11, s11, 0
	global_load_dword v50, v193, s[10:11]
	global_load_dword v51, v193, s[10:11] offset:256
	global_load_dword v52, v22, s[4:5]
	global_load_dword v53, v23, s[4:5]
	global_load_dword v54, v22, s[8:9]
	global_load_dword v55, v23, s[8:9]
	s_add_u32 s10, s10, s18
	s_addc_u32 s11, s11, 0
	global_load_dword v56, v193, s[10:11]
	global_load_dword v57, v193, s[10:11] offset:256
	global_load_dword v58, v24, s[4:5]
	global_load_dword v59, v25, s[4:5]
	global_load_dword v60, v24, s[8:9]
	global_load_dword v61, v25, s[8:9]
	s_add_u32 s10, s10, s18
	s_addc_u32 s11, s11, 0
	global_load_dword v62, v193, s[10:11]
	global_load_dword v63, v193, s[10:11] offset:256
	global_load_dword v64, v26, s[4:5]
	global_load_dword v65, v27, s[4:5]
	global_load_dword v66, v26, s[8:9]
	global_load_dword v67, v27, s[8:9]
	s_add_u32 s10, s10, s18
	s_addc_u32 s11, s11, 0
	global_load_dword v68, v193, s[10:11]
	global_load_dword v69, v193, s[10:11] offset:256
	global_load_dword v70, v28, s[4:5]
	global_load_dword v71, v29, s[4:5]
	global_load_dword v72, v28, s[8:9]
	global_load_dword v73, v29, s[8:9]
	s_add_u32 s10, s10, s18
	s_addc_u32 s11, s11, 0
	global_load_dword v74, v193, s[10:11]
	global_load_dword v75, v193, s[10:11] offset:256
	global_load_dword v76, v30, s[4:5]
	global_load_dword v77, v31, s[4:5]
	global_load_dword v78, v30, s[8:9]
	global_load_dword v79, v31, s[8:9]
	s_add_u32 s10, s10, s18
	s_addc_u32 s11, s11, 0
	s_waitcnt vmcnt(0)
	v_mul_f32_e32 v80, v34, v80
	v_mul_f32_e32 v180, 0x3f3504f3, v80
	v_fma_f32 v182, |v180|, s16, v177
	v_fma_f32 v182, |v180|, v182, s19
	v_fma_f32 v182, |v180|, v182, s50
	v_fma_f32 v182, |v180|, v182, s51
	v_fma_f32 v182, |v180|, v182, s64
	v_fma_f32 v182, |v180|, v182, s65
	v_fma_f32 v182, |v180|, v182, |v180|
	v_mul_f32_e32 v184, 0xbfb8aa3b, v182
	v_fma_f32 v185, v182, s98, -v184
	v_rndne_f32_e32 v186, v184
	v_fmac_f32_e32 v185, 0xb2a5705f, v182
	v_sub_f32_e32 v184, v184, v186
	v_add_f32_e32 v184, v184, v185
	v_cvt_i32_f32_e32 v185, v186
	v_exp_f32_e32 v184, v184
	v_cmp_nlt_f32_e32 vcc, s70, v182
	v_ldexp_f32 v184, v184, v185
	s_nop 0
	v_cndmask_b32_e32 v184, 0, v184, vcc
	v_cmp_ngt_f32_e32 vcc, s71, v182
	s_nop 1
	v_cndmask_b32_e32 v184, v178, v184, vcc
	v_sub_f32_e32 v184, 1.0, v184
	v_mul_f32_e32 v183, v180, v180
	v_fmamk_f32 v185, v183, 0xba1345e1, v176
	v_fmaak_f32 v185, v183, v185, 0xbcdac9b8
	v_fmaak_f32 v185, v183, v185, 0x3de703be
	v_fmaak_f32 v185, v183, v185, 0xbec09330
	v_fmaak_f32 v183, v183, v185, 0x3e0375d0
	v_fma_f32 v183, |v180|, v183, |v180|
	v_cmp_nlt_f32_e64 vcc, |v180|, 1.0
	s_nop 1
	v_cndmask_b32_e32 v184, v183, v184, vcc
	v_bfi_b32 v184, s14, v184, v180
	v_add_f32_e32 v184, 1.0, v184
	v_mul_f32_e32 v80, 0.5, v80
	v_mul_f32_e32 v32, v32, v36
	v_mul_f32_e32 v80, v80, v184
	v_mul_f32_e32 v80, v32, v80
	v_mul_f32_e32 v81, v35, v81
	v_mul_f32_e32 v180, 0x3f3504f3, v81
	v_fma_f32 v182, |v180|, s16, v177
	v_fma_f32 v182, |v180|, v182, s19
	v_fma_f32 v182, |v180|, v182, s50
	v_fma_f32 v182, |v180|, v182, s51
	v_fma_f32 v182, |v180|, v182, s64
	v_fma_f32 v182, |v180|, v182, s65
	v_fma_f32 v182, |v180|, v182, |v180|
	v_mul_f32_e32 v184, 0xbfb8aa3b, v182
	v_fma_f32 v185, v182, s98, -v184
	v_rndne_f32_e32 v186, v184
	v_fmac_f32_e32 v185, 0xb2a5705f, v182
	v_sub_f32_e32 v184, v184, v186
	v_add_f32_e32 v184, v184, v185
	v_cvt_i32_f32_e32 v185, v186
	v_exp_f32_e32 v184, v184
	v_cmp_nlt_f32_e32 vcc, s70, v182
	v_ldexp_f32 v184, v184, v185
	s_nop 0
	v_cndmask_b32_e32 v184, 0, v184, vcc
	v_cmp_ngt_f32_e32 vcc, s71, v182
	s_nop 1
	v_cndmask_b32_e32 v184, v178, v184, vcc
	v_sub_f32_e32 v184, 1.0, v184
	v_mul_f32_e32 v183, v180, v180
	v_fmamk_f32 v185, v183, 0xba1345e1, v176
	v_fmaak_f32 v185, v183, v185, 0xbcdac9b8
	v_fmaak_f32 v185, v183, v185, 0x3de703be
	v_fmaak_f32 v185, v183, v185, 0xbec09330
	v_fmaak_f32 v183, v183, v185, 0x3e0375d0
	v_fma_f32 v183, |v180|, v183, |v180|
	v_cmp_nlt_f32_e64 vcc, |v180|, 1.0
	s_nop 1
	v_cndmask_b32_e32 v184, v183, v184, vcc
	v_bfi_b32 v184, s14, v184, v180
	v_add_f32_e32 v184, 1.0, v184
	v_mul_f32_e32 v81, 0.5, v81
	v_mul_f32_e32 v33, v33, v37
	v_mul_f32_e32 v81, v81, v184
	v_mul_f32_e32 v81, v33, v81
	global_store_dword v193, v80, s[12:13]
	global_store_dword v193, v81, s[12:13] offset:256
	s_add_u32 s12, s12, s18
	s_addc_u32 s13, s13, 0
	v_mul_f32_e32 v82, v40, v82
	v_mul_f32_e32 v180, 0x3f3504f3, v82
	v_fma_f32 v182, |v180|, s16, v177
	v_fma_f32 v182, |v180|, v182, s19
	v_fma_f32 v182, |v180|, v182, s50
	v_fma_f32 v182, |v180|, v182, s51
	v_fma_f32 v182, |v180|, v182, s64
	v_fma_f32 v182, |v180|, v182, s65
	v_fma_f32 v182, |v180|, v182, |v180|
	v_mul_f32_e32 v184, 0xbfb8aa3b, v182
	v_fma_f32 v185, v182, s98, -v184
	v_rndne_f32_e32 v186, v184
	v_fmac_f32_e32 v185, 0xb2a5705f, v182
	v_sub_f32_e32 v184, v184, v186
	v_add_f32_e32 v184, v184, v185
	v_cvt_i32_f32_e32 v185, v186
	v_exp_f32_e32 v184, v184
	v_cmp_nlt_f32_e32 vcc, s70, v182
	v_ldexp_f32 v184, v184, v185
	s_nop 0
	v_cndmask_b32_e32 v184, 0, v184, vcc
	v_cmp_ngt_f32_e32 vcc, s71, v182
	s_nop 1
	v_cndmask_b32_e32 v184, v178, v184, vcc
	v_sub_f32_e32 v184, 1.0, v184
	v_mul_f32_e32 v183, v180, v180
	v_fmamk_f32 v185, v183, 0xba1345e1, v176
	v_fmaak_f32 v185, v183, v185, 0xbcdac9b8
	v_fmaak_f32 v185, v183, v185, 0x3de703be
	v_fmaak_f32 v185, v183, v185, 0xbec09330
	v_fmaak_f32 v183, v183, v185, 0x3e0375d0
	v_fma_f32 v183, |v180|, v183, |v180|
	v_cmp_nlt_f32_e64 vcc, |v180|, 1.0
	s_nop 1
	v_cndmask_b32_e32 v184, v183, v184, vcc
	v_bfi_b32 v184, s14, v184, v180
	v_add_f32_e32 v184, 1.0, v184
	v_mul_f32_e32 v82, 0.5, v82
	v_mul_f32_e32 v38, v38, v42
	v_mul_f32_e32 v82, v82, v184
	v_mul_f32_e32 v82, v38, v82
	v_mul_f32_e32 v83, v41, v83
	v_mul_f32_e32 v180, 0x3f3504f3, v83
	v_fma_f32 v182, |v180|, s16, v177
	v_fma_f32 v182, |v180|, v182, s19
	v_fma_f32 v182, |v180|, v182, s50
	v_fma_f32 v182, |v180|, v182, s51
	v_fma_f32 v182, |v180|, v182, s64
	v_fma_f32 v182, |v180|, v182, s65
	v_fma_f32 v182, |v180|, v182, |v180|
	v_mul_f32_e32 v184, 0xbfb8aa3b, v182
	v_fma_f32 v185, v182, s98, -v184
	v_rndne_f32_e32 v186, v184
	v_fmac_f32_e32 v185, 0xb2a5705f, v182
	v_sub_f32_e32 v184, v184, v186
	v_add_f32_e32 v184, v184, v185
	v_cvt_i32_f32_e32 v185, v186
	v_exp_f32_e32 v184, v184
	v_cmp_nlt_f32_e32 vcc, s70, v182
	v_ldexp_f32 v184, v184, v185
	s_nop 0
	v_cndmask_b32_e32 v184, 0, v184, vcc
	v_cmp_ngt_f32_e32 vcc, s71, v182
	s_nop 1
	v_cndmask_b32_e32 v184, v178, v184, vcc
	v_sub_f32_e32 v184, 1.0, v184
	v_mul_f32_e32 v183, v180, v180
	v_fmamk_f32 v185, v183, 0xba1345e1, v176
	v_fmaak_f32 v185, v183, v185, 0xbcdac9b8
	v_fmaak_f32 v185, v183, v185, 0x3de703be
	v_fmaak_f32 v185, v183, v185, 0xbec09330
	v_fmaak_f32 v183, v183, v185, 0x3e0375d0
	v_fma_f32 v183, |v180|, v183, |v180|
	v_cmp_nlt_f32_e64 vcc, |v180|, 1.0
	s_nop 1
	v_cndmask_b32_e32 v184, v183, v184, vcc
	v_bfi_b32 v184, s14, v184, v180
	v_add_f32_e32 v184, 1.0, v184
	v_mul_f32_e32 v83, 0.5, v83
	v_mul_f32_e32 v39, v39, v43
	v_mul_f32_e32 v83, v83, v184
	v_mul_f32_e32 v83, v39, v83
	global_store_dword v193, v82, s[12:13]
	global_store_dword v193, v83, s[12:13] offset:256
	s_add_u32 s12, s12, s18
	s_addc_u32 s13, s13, 0
	v_mul_f32_e32 v84, v46, v84
	v_mul_f32_e32 v180, 0x3f3504f3, v84
	v_fma_f32 v182, |v180|, s16, v177
	v_fma_f32 v182, |v180|, v182, s19
	v_fma_f32 v182, |v180|, v182, s50
	v_fma_f32 v182, |v180|, v182, s51
	v_fma_f32 v182, |v180|, v182, s64
	v_fma_f32 v182, |v180|, v182, s65
	v_fma_f32 v182, |v180|, v182, |v180|
	v_mul_f32_e32 v184, 0xbfb8aa3b, v182
	v_fma_f32 v185, v182, s98, -v184
	v_rndne_f32_e32 v186, v184
	v_fmac_f32_e32 v185, 0xb2a5705f, v182
	v_sub_f32_e32 v184, v184, v186
	v_add_f32_e32 v184, v184, v185
	v_cvt_i32_f32_e32 v185, v186
	v_exp_f32_e32 v184, v184
	v_cmp_nlt_f32_e32 vcc, s70, v182
	v_ldexp_f32 v184, v184, v185
	s_nop 0
	v_cndmask_b32_e32 v184, 0, v184, vcc
	v_cmp_ngt_f32_e32 vcc, s71, v182
	s_nop 1
	v_cndmask_b32_e32 v184, v178, v184, vcc
	v_sub_f32_e32 v184, 1.0, v184
	v_mul_f32_e32 v183, v180, v180
	v_fmamk_f32 v185, v183, 0xba1345e1, v176
	v_fmaak_f32 v185, v183, v185, 0xbcdac9b8
	v_fmaak_f32 v185, v183, v185, 0x3de703be
	v_fmaak_f32 v185, v183, v185, 0xbec09330
	v_fmaak_f32 v183, v183, v185, 0x3e0375d0
	v_fma_f32 v183, |v180|, v183, |v180|
	v_cmp_nlt_f32_e64 vcc, |v180|, 1.0
	s_nop 1
	v_cndmask_b32_e32 v184, v183, v184, vcc
	v_bfi_b32 v184, s14, v184, v180
	v_add_f32_e32 v184, 1.0, v184
	v_mul_f32_e32 v84, 0.5, v84
	v_mul_f32_e32 v44, v44, v48
	v_mul_f32_e32 v84, v84, v184
	v_mul_f32_e32 v84, v44, v84
	v_mul_f32_e32 v85, v47, v85
	v_mul_f32_e32 v180, 0x3f3504f3, v85
	v_fma_f32 v182, |v180|, s16, v177
	v_fma_f32 v182, |v180|, v182, s19
	v_fma_f32 v182, |v180|, v182, s50
	v_fma_f32 v182, |v180|, v182, s51
	v_fma_f32 v182, |v180|, v182, s64
	v_fma_f32 v182, |v180|, v182, s65
	v_fma_f32 v182, |v180|, v182, |v180|
	v_mul_f32_e32 v184, 0xbfb8aa3b, v182
	v_fma_f32 v185, v182, s98, -v184
	v_rndne_f32_e32 v186, v184
	v_fmac_f32_e32 v185, 0xb2a5705f, v182
	v_sub_f32_e32 v184, v184, v186
	v_add_f32_e32 v184, v184, v185
	v_cvt_i32_f32_e32 v185, v186
	v_exp_f32_e32 v184, v184
	v_cmp_nlt_f32_e32 vcc, s70, v182
	v_ldexp_f32 v184, v184, v185
	s_nop 0
	v_cndmask_b32_e32 v184, 0, v184, vcc
	v_cmp_ngt_f32_e32 vcc, s71, v182
	s_nop 1
	v_cndmask_b32_e32 v184, v178, v184, vcc
	v_sub_f32_e32 v184, 1.0, v184
	v_mul_f32_e32 v183, v180, v180
	v_fmamk_f32 v185, v183, 0xba1345e1, v176
	v_fmaak_f32 v185, v183, v185, 0xbcdac9b8
	v_fmaak_f32 v185, v183, v185, 0x3de703be
	v_fmaak_f32 v185, v183, v185, 0xbec09330
	v_fmaak_f32 v183, v183, v185, 0x3e0375d0
	v_fma_f32 v183, |v180|, v183, |v180|
	v_cmp_nlt_f32_e64 vcc, |v180|, 1.0
	s_nop 1
	v_cndmask_b32_e32 v184, v183, v184, vcc
	v_bfi_b32 v184, s14, v184, v180
	v_add_f32_e32 v184, 1.0, v184
	v_mul_f32_e32 v85, 0.5, v85
	v_mul_f32_e32 v45, v45, v49
	v_mul_f32_e32 v85, v85, v184
	v_mul_f32_e32 v85, v45, v85
	global_store_dword v193, v84, s[12:13]
	global_store_dword v193, v85, s[12:13] offset:256
	s_add_u32 s12, s12, s18
	s_addc_u32 s13, s13, 0
	v_mul_f32_e32 v86, v52, v86
	v_mul_f32_e32 v180, 0x3f3504f3, v86
	v_fma_f32 v182, |v180|, s16, v177
	v_fma_f32 v182, |v180|, v182, s19
	v_fma_f32 v182, |v180|, v182, s50
	v_fma_f32 v182, |v180|, v182, s51
	v_fma_f32 v182, |v180|, v182, s64
	v_fma_f32 v182, |v180|, v182, s65
	v_fma_f32 v182, |v180|, v182, |v180|
	v_mul_f32_e32 v184, 0xbfb8aa3b, v182
	v_fma_f32 v185, v182, s98, -v184
	v_rndne_f32_e32 v186, v184
	v_fmac_f32_e32 v185, 0xb2a5705f, v182
	v_sub_f32_e32 v184, v184, v186
	v_add_f32_e32 v184, v184, v185
	v_cvt_i32_f32_e32 v185, v186
	v_exp_f32_e32 v184, v184
	v_cmp_nlt_f32_e32 vcc, s70, v182
	v_ldexp_f32 v184, v184, v185
	s_nop 0
	v_cndmask_b32_e32 v184, 0, v184, vcc
	v_cmp_ngt_f32_e32 vcc, s71, v182
	s_nop 1
	v_cndmask_b32_e32 v184, v178, v184, vcc
	v_sub_f32_e32 v184, 1.0, v184
	v_mul_f32_e32 v183, v180, v180
	v_fmamk_f32 v185, v183, 0xba1345e1, v176
	v_fmaak_f32 v185, v183, v185, 0xbcdac9b8
	v_fmaak_f32 v185, v183, v185, 0x3de703be
	v_fmaak_f32 v185, v183, v185, 0xbec09330
	v_fmaak_f32 v183, v183, v185, 0x3e0375d0
	v_fma_f32 v183, |v180|, v183, |v180|
	v_cmp_nlt_f32_e64 vcc, |v180|, 1.0
	s_nop 1
	v_cndmask_b32_e32 v184, v183, v184, vcc
	v_bfi_b32 v184, s14, v184, v180
	v_add_f32_e32 v184, 1.0, v184
	v_mul_f32_e32 v86, 0.5, v86
	v_mul_f32_e32 v50, v50, v54
	v_mul_f32_e32 v86, v86, v184
	v_mul_f32_e32 v86, v50, v86
	v_mul_f32_e32 v87, v53, v87
	v_mul_f32_e32 v180, 0x3f3504f3, v87
	v_fma_f32 v182, |v180|, s16, v177
	v_fma_f32 v182, |v180|, v182, s19
	v_fma_f32 v182, |v180|, v182, s50
	v_fma_f32 v182, |v180|, v182, s51
	v_fma_f32 v182, |v180|, v182, s64
	v_fma_f32 v182, |v180|, v182, s65
	v_fma_f32 v182, |v180|, v182, |v180|
	v_mul_f32_e32 v184, 0xbfb8aa3b, v182
	v_fma_f32 v185, v182, s98, -v184
	v_rndne_f32_e32 v186, v184
	v_fmac_f32_e32 v185, 0xb2a5705f, v182
	v_sub_f32_e32 v184, v184, v186
	v_add_f32_e32 v184, v184, v185
	v_cvt_i32_f32_e32 v185, v186
	v_exp_f32_e32 v184, v184
	v_cmp_nlt_f32_e32 vcc, s70, v182
	v_ldexp_f32 v184, v184, v185
	s_nop 0
	v_cndmask_b32_e32 v184, 0, v184, vcc
	v_cmp_ngt_f32_e32 vcc, s71, v182
	s_nop 1
	v_cndmask_b32_e32 v184, v178, v184, vcc
	v_sub_f32_e32 v184, 1.0, v184
	v_mul_f32_e32 v183, v180, v180
	v_fmamk_f32 v185, v183, 0xba1345e1, v176
	v_fmaak_f32 v185, v183, v185, 0xbcdac9b8
	v_fmaak_f32 v185, v183, v185, 0x3de703be
	v_fmaak_f32 v185, v183, v185, 0xbec09330
	v_fmaak_f32 v183, v183, v185, 0x3e0375d0
	v_fma_f32 v183, |v180|, v183, |v180|
	v_cmp_nlt_f32_e64 vcc, |v180|, 1.0
	s_nop 1
	v_cndmask_b32_e32 v184, v183, v184, vcc
	v_bfi_b32 v184, s14, v184, v180
	v_add_f32_e32 v184, 1.0, v184
	v_mul_f32_e32 v87, 0.5, v87
	v_mul_f32_e32 v51, v51, v55
	v_mul_f32_e32 v87, v87, v184
	v_mul_f32_e32 v87, v51, v87
	global_store_dword v193, v86, s[12:13]
	global_store_dword v193, v87, s[12:13] offset:256
	s_add_u32 s12, s12, s18
	s_addc_u32 s13, s13, 0
	v_mul_f32_e32 v88, v58, v88
	v_mul_f32_e32 v180, 0x3f3504f3, v88
	v_fma_f32 v182, |v180|, s16, v177
	v_fma_f32 v182, |v180|, v182, s19
	v_fma_f32 v182, |v180|, v182, s50
	v_fma_f32 v182, |v180|, v182, s51
	v_fma_f32 v182, |v180|, v182, s64
	v_fma_f32 v182, |v180|, v182, s65
	v_fma_f32 v182, |v180|, v182, |v180|
	v_mul_f32_e32 v184, 0xbfb8aa3b, v182
	v_fma_f32 v185, v182, s98, -v184
	v_rndne_f32_e32 v186, v184
	v_fmac_f32_e32 v185, 0xb2a5705f, v182
	v_sub_f32_e32 v184, v184, v186
	v_add_f32_e32 v184, v184, v185
	v_cvt_i32_f32_e32 v185, v186
	v_exp_f32_e32 v184, v184
	v_cmp_nlt_f32_e32 vcc, s70, v182
	v_ldexp_f32 v184, v184, v185
	s_nop 0
	v_cndmask_b32_e32 v184, 0, v184, vcc
	v_cmp_ngt_f32_e32 vcc, s71, v182
	s_nop 1
	v_cndmask_b32_e32 v184, v178, v184, vcc
	v_sub_f32_e32 v184, 1.0, v184
	v_mul_f32_e32 v183, v180, v180
	v_fmamk_f32 v185, v183, 0xba1345e1, v176
	v_fmaak_f32 v185, v183, v185, 0xbcdac9b8
	v_fmaak_f32 v185, v183, v185, 0x3de703be
	v_fmaak_f32 v185, v183, v185, 0xbec09330
	v_fmaak_f32 v183, v183, v185, 0x3e0375d0
	v_fma_f32 v183, |v180|, v183, |v180|
	v_cmp_nlt_f32_e64 vcc, |v180|, 1.0
	s_nop 1
	v_cndmask_b32_e32 v184, v183, v184, vcc
	v_bfi_b32 v184, s14, v184, v180
	v_add_f32_e32 v184, 1.0, v184
	v_mul_f32_e32 v88, 0.5, v88
	v_mul_f32_e32 v56, v56, v60
	v_mul_f32_e32 v88, v88, v184
	v_mul_f32_e32 v88, v56, v88
	v_mul_f32_e32 v89, v59, v89
	v_mul_f32_e32 v180, 0x3f3504f3, v89
	v_fma_f32 v182, |v180|, s16, v177
	v_fma_f32 v182, |v180|, v182, s19
	v_fma_f32 v182, |v180|, v182, s50
	v_fma_f32 v182, |v180|, v182, s51
	v_fma_f32 v182, |v180|, v182, s64
	v_fma_f32 v182, |v180|, v182, s65
	v_fma_f32 v182, |v180|, v182, |v180|
	v_mul_f32_e32 v184, 0xbfb8aa3b, v182
	v_fma_f32 v185, v182, s98, -v184
	v_rndne_f32_e32 v186, v184
	v_fmac_f32_e32 v185, 0xb2a5705f, v182
	v_sub_f32_e32 v184, v184, v186
	v_add_f32_e32 v184, v184, v185
	v_cvt_i32_f32_e32 v185, v186
	v_exp_f32_e32 v184, v184
	v_cmp_nlt_f32_e32 vcc, s70, v182
	v_ldexp_f32 v184, v184, v185
	s_nop 0
	v_cndmask_b32_e32 v184, 0, v184, vcc
	v_cmp_ngt_f32_e32 vcc, s71, v182
	s_nop 1
	v_cndmask_b32_e32 v184, v178, v184, vcc
	v_sub_f32_e32 v184, 1.0, v184
	v_mul_f32_e32 v183, v180, v180
	v_fmamk_f32 v185, v183, 0xba1345e1, v176
	v_fmaak_f32 v185, v183, v185, 0xbcdac9b8
	v_fmaak_f32 v185, v183, v185, 0x3de703be
	v_fmaak_f32 v185, v183, v185, 0xbec09330
	v_fmaak_f32 v183, v183, v185, 0x3e0375d0
	v_fma_f32 v183, |v180|, v183, |v180|
	v_cmp_nlt_f32_e64 vcc, |v180|, 1.0
	s_nop 1
	v_cndmask_b32_e32 v184, v183, v184, vcc
	v_bfi_b32 v184, s14, v184, v180
	v_add_f32_e32 v184, 1.0, v184
	v_mul_f32_e32 v89, 0.5, v89
	v_mul_f32_e32 v57, v57, v61
	v_mul_f32_e32 v89, v89, v184
	v_mul_f32_e32 v89, v57, v89
	global_store_dword v193, v88, s[12:13]
	global_store_dword v193, v89, s[12:13] offset:256
	s_add_u32 s12, s12, s18
	s_addc_u32 s13, s13, 0
	v_mul_f32_e32 v90, v64, v90
	v_mul_f32_e32 v180, 0x3f3504f3, v90
	v_fma_f32 v182, |v180|, s16, v177
	v_fma_f32 v182, |v180|, v182, s19
	v_fma_f32 v182, |v180|, v182, s50
	v_fma_f32 v182, |v180|, v182, s51
	v_fma_f32 v182, |v180|, v182, s64
	v_fma_f32 v182, |v180|, v182, s65
	v_fma_f32 v182, |v180|, v182, |v180|
	v_mul_f32_e32 v184, 0xbfb8aa3b, v182
	v_fma_f32 v185, v182, s98, -v184
	v_rndne_f32_e32 v186, v184
	v_fmac_f32_e32 v185, 0xb2a5705f, v182
	v_sub_f32_e32 v184, v184, v186
	v_add_f32_e32 v184, v184, v185
	v_cvt_i32_f32_e32 v185, v186
	v_exp_f32_e32 v184, v184
	v_cmp_nlt_f32_e32 vcc, s70, v182
	v_ldexp_f32 v184, v184, v185
	s_nop 0
	v_cndmask_b32_e32 v184, 0, v184, vcc
	v_cmp_ngt_f32_e32 vcc, s71, v182
	s_nop 1
	v_cndmask_b32_e32 v184, v178, v184, vcc
	v_sub_f32_e32 v184, 1.0, v184
	v_mul_f32_e32 v183, v180, v180
	v_fmamk_f32 v185, v183, 0xba1345e1, v176
	v_fmaak_f32 v185, v183, v185, 0xbcdac9b8
	v_fmaak_f32 v185, v183, v185, 0x3de703be
	v_fmaak_f32 v185, v183, v185, 0xbec09330
	v_fmaak_f32 v183, v183, v185, 0x3e0375d0
	v_fma_f32 v183, |v180|, v183, |v180|
	v_cmp_nlt_f32_e64 vcc, |v180|, 1.0
	s_nop 1
	v_cndmask_b32_e32 v184, v183, v184, vcc
	v_bfi_b32 v184, s14, v184, v180
	v_add_f32_e32 v184, 1.0, v184
	v_mul_f32_e32 v90, 0.5, v90
	v_mul_f32_e32 v62, v62, v66
	v_mul_f32_e32 v90, v90, v184
	v_mul_f32_e32 v90, v62, v90
	v_mul_f32_e32 v91, v65, v91
	v_mul_f32_e32 v180, 0x3f3504f3, v91
	v_fma_f32 v182, |v180|, s16, v177
	v_fma_f32 v182, |v180|, v182, s19
	v_fma_f32 v182, |v180|, v182, s50
	v_fma_f32 v182, |v180|, v182, s51
	v_fma_f32 v182, |v180|, v182, s64
	v_fma_f32 v182, |v180|, v182, s65
	v_fma_f32 v182, |v180|, v182, |v180|
	v_mul_f32_e32 v184, 0xbfb8aa3b, v182
	v_fma_f32 v185, v182, s98, -v184
	v_rndne_f32_e32 v186, v184
	v_fmac_f32_e32 v185, 0xb2a5705f, v182
	v_sub_f32_e32 v184, v184, v186
	v_add_f32_e32 v184, v184, v185
	v_cvt_i32_f32_e32 v185, v186
	v_exp_f32_e32 v184, v184
	v_cmp_nlt_f32_e32 vcc, s70, v182
	v_ldexp_f32 v184, v184, v185
	s_nop 0
	v_cndmask_b32_e32 v184, 0, v184, vcc
	v_cmp_ngt_f32_e32 vcc, s71, v182
	s_nop 1
	v_cndmask_b32_e32 v184, v178, v184, vcc
	v_sub_f32_e32 v184, 1.0, v184
	v_mul_f32_e32 v183, v180, v180
	v_fmamk_f32 v185, v183, 0xba1345e1, v176
	v_fmaak_f32 v185, v183, v185, 0xbcdac9b8
	v_fmaak_f32 v185, v183, v185, 0x3de703be
	v_fmaak_f32 v185, v183, v185, 0xbec09330
	v_fmaak_f32 v183, v183, v185, 0x3e0375d0
	v_fma_f32 v183, |v180|, v183, |v180|
	v_cmp_nlt_f32_e64 vcc, |v180|, 1.0
	s_nop 1
	v_cndmask_b32_e32 v184, v183, v184, vcc
	v_bfi_b32 v184, s14, v184, v180
	v_add_f32_e32 v184, 1.0, v184
	v_mul_f32_e32 v91, 0.5, v91
	v_mul_f32_e32 v63, v63, v67
	v_mul_f32_e32 v91, v91, v184
	v_mul_f32_e32 v91, v63, v91
	global_store_dword v193, v90, s[12:13]
	global_store_dword v193, v91, s[12:13] offset:256
	s_add_u32 s12, s12, s18
	s_addc_u32 s13, s13, 0
	v_mul_f32_e32 v92, v70, v92
	v_mul_f32_e32 v180, 0x3f3504f3, v92
	v_fma_f32 v182, |v180|, s16, v177
	v_fma_f32 v182, |v180|, v182, s19
	v_fma_f32 v182, |v180|, v182, s50
	v_fma_f32 v182, |v180|, v182, s51
	v_fma_f32 v182, |v180|, v182, s64
	v_fma_f32 v182, |v180|, v182, s65
	v_fma_f32 v182, |v180|, v182, |v180|
	v_mul_f32_e32 v184, 0xbfb8aa3b, v182
	v_fma_f32 v185, v182, s98, -v184
	v_rndne_f32_e32 v186, v184
	v_fmac_f32_e32 v185, 0xb2a5705f, v182
	v_sub_f32_e32 v184, v184, v186
	v_add_f32_e32 v184, v184, v185
	v_cvt_i32_f32_e32 v185, v186
	v_exp_f32_e32 v184, v184
	v_cmp_nlt_f32_e32 vcc, s70, v182
	v_ldexp_f32 v184, v184, v185
	s_nop 0
	v_cndmask_b32_e32 v184, 0, v184, vcc
	v_cmp_ngt_f32_e32 vcc, s71, v182
	s_nop 1
	v_cndmask_b32_e32 v184, v178, v184, vcc
	v_sub_f32_e32 v184, 1.0, v184
	v_mul_f32_e32 v183, v180, v180
	v_fmamk_f32 v185, v183, 0xba1345e1, v176
	v_fmaak_f32 v185, v183, v185, 0xbcdac9b8
	v_fmaak_f32 v185, v183, v185, 0x3de703be
	v_fmaak_f32 v185, v183, v185, 0xbec09330
	v_fmaak_f32 v183, v183, v185, 0x3e0375d0
	v_fma_f32 v183, |v180|, v183, |v180|
	v_cmp_nlt_f32_e64 vcc, |v180|, 1.0
	s_nop 1
	v_cndmask_b32_e32 v184, v183, v184, vcc
	v_bfi_b32 v184, s14, v184, v180
	v_add_f32_e32 v184, 1.0, v184
	v_mul_f32_e32 v92, 0.5, v92
	v_mul_f32_e32 v68, v68, v72
	v_mul_f32_e32 v92, v92, v184
	v_mul_f32_e32 v92, v68, v92
	v_mul_f32_e32 v93, v71, v93
	v_mul_f32_e32 v180, 0x3f3504f3, v93
	v_fma_f32 v182, |v180|, s16, v177
	v_fma_f32 v182, |v180|, v182, s19
	v_fma_f32 v182, |v180|, v182, s50
	v_fma_f32 v182, |v180|, v182, s51
	v_fma_f32 v182, |v180|, v182, s64
	v_fma_f32 v182, |v180|, v182, s65
	v_fma_f32 v182, |v180|, v182, |v180|
	v_mul_f32_e32 v184, 0xbfb8aa3b, v182
	v_fma_f32 v185, v182, s98, -v184
	v_rndne_f32_e32 v186, v184
	v_fmac_f32_e32 v185, 0xb2a5705f, v182
	v_sub_f32_e32 v184, v184, v186
	v_add_f32_e32 v184, v184, v185
	v_cvt_i32_f32_e32 v185, v186
	v_exp_f32_e32 v184, v184
	v_cmp_nlt_f32_e32 vcc, s70, v182
	v_ldexp_f32 v184, v184, v185
	s_nop 0
	v_cndmask_b32_e32 v184, 0, v184, vcc
	v_cmp_ngt_f32_e32 vcc, s71, v182
	s_nop 1
	v_cndmask_b32_e32 v184, v178, v184, vcc
	v_sub_f32_e32 v184, 1.0, v184
	v_mul_f32_e32 v183, v180, v180
	v_fmamk_f32 v185, v183, 0xba1345e1, v176
	v_fmaak_f32 v185, v183, v185, 0xbcdac9b8
	v_fmaak_f32 v185, v183, v185, 0x3de703be
	v_fmaak_f32 v185, v183, v185, 0xbec09330
	v_fmaak_f32 v183, v183, v185, 0x3e0375d0
	v_fma_f32 v183, |v180|, v183, |v180|
	v_cmp_nlt_f32_e64 vcc, |v180|, 1.0
	s_nop 1
	v_cndmask_b32_e32 v184, v183, v184, vcc
	v_bfi_b32 v184, s14, v184, v180
	v_add_f32_e32 v184, 1.0, v184
	v_mul_f32_e32 v93, 0.5, v93
	v_mul_f32_e32 v69, v69, v73
	v_mul_f32_e32 v93, v93, v184
	v_mul_f32_e32 v93, v69, v93
	global_store_dword v193, v92, s[12:13]
	global_store_dword v193, v93, s[12:13] offset:256
	s_add_u32 s12, s12, s18
	s_addc_u32 s13, s13, 0
	v_mul_f32_e32 v94, v76, v94
	v_mul_f32_e32 v180, 0x3f3504f3, v94
	v_fma_f32 v182, |v180|, s16, v177
	v_fma_f32 v182, |v180|, v182, s19
	v_fma_f32 v182, |v180|, v182, s50
	v_fma_f32 v182, |v180|, v182, s51
	v_fma_f32 v182, |v180|, v182, s64
	v_fma_f32 v182, |v180|, v182, s65
	v_fma_f32 v182, |v180|, v182, |v180|
	v_mul_f32_e32 v184, 0xbfb8aa3b, v182
	v_fma_f32 v185, v182, s98, -v184
	v_rndne_f32_e32 v186, v184
	v_fmac_f32_e32 v185, 0xb2a5705f, v182
	v_sub_f32_e32 v184, v184, v186
	v_add_f32_e32 v184, v184, v185
	v_cvt_i32_f32_e32 v185, v186
	v_exp_f32_e32 v184, v184
	v_cmp_nlt_f32_e32 vcc, s70, v182
	v_ldexp_f32 v184, v184, v185
	s_nop 0
	v_cndmask_b32_e32 v184, 0, v184, vcc
	v_cmp_ngt_f32_e32 vcc, s71, v182
	s_nop 1
	v_cndmask_b32_e32 v184, v178, v184, vcc
	v_sub_f32_e32 v184, 1.0, v184
	v_mul_f32_e32 v183, v180, v180
	v_fmamk_f32 v185, v183, 0xba1345e1, v176
	v_fmaak_f32 v185, v183, v185, 0xbcdac9b8
	v_fmaak_f32 v185, v183, v185, 0x3de703be
	v_fmaak_f32 v185, v183, v185, 0xbec09330
	v_fmaak_f32 v183, v183, v185, 0x3e0375d0
	v_fma_f32 v183, |v180|, v183, |v180|
	v_cmp_nlt_f32_e64 vcc, |v180|, 1.0
	s_nop 1
	v_cndmask_b32_e32 v184, v183, v184, vcc
	v_bfi_b32 v184, s14, v184, v180
	v_add_f32_e32 v184, 1.0, v184
	v_mul_f32_e32 v94, 0.5, v94
	v_mul_f32_e32 v74, v74, v78
	v_mul_f32_e32 v94, v94, v184
	v_mul_f32_e32 v94, v74, v94
	v_mul_f32_e32 v95, v77, v95
	v_mul_f32_e32 v180, 0x3f3504f3, v95
	v_fma_f32 v182, |v180|, s16, v177
	v_fma_f32 v182, |v180|, v182, s19
	v_fma_f32 v182, |v180|, v182, s50
	v_fma_f32 v182, |v180|, v182, s51
	v_fma_f32 v182, |v180|, v182, s64
	v_fma_f32 v182, |v180|, v182, s65
	v_fma_f32 v182, |v180|, v182, |v180|
	v_mul_f32_e32 v184, 0xbfb8aa3b, v182
	v_fma_f32 v185, v182, s98, -v184
	v_rndne_f32_e32 v186, v184
	v_fmac_f32_e32 v185, 0xb2a5705f, v182
	v_sub_f32_e32 v184, v184, v186
	v_add_f32_e32 v184, v184, v185
	v_cvt_i32_f32_e32 v185, v186
	v_exp_f32_e32 v184, v184
	v_cmp_nlt_f32_e32 vcc, s70, v182
	v_ldexp_f32 v184, v184, v185
	s_nop 0
	v_cndmask_b32_e32 v184, 0, v184, vcc
	v_cmp_ngt_f32_e32 vcc, s71, v182
	s_nop 1
	v_cndmask_b32_e32 v184, v178, v184, vcc
	v_sub_f32_e32 v184, 1.0, v184
	v_mul_f32_e32 v183, v180, v180
	v_fmamk_f32 v185, v183, 0xba1345e1, v176
	v_fmaak_f32 v185, v183, v185, 0xbcdac9b8
	v_fmaak_f32 v185, v183, v185, 0x3de703be
	v_fmaak_f32 v185, v183, v185, 0xbec09330
	v_fmaak_f32 v183, v183, v185, 0x3e0375d0
	v_fma_f32 v183, |v180|, v183, |v180|
	v_cmp_nlt_f32_e64 vcc, |v180|, 1.0
	s_nop 1
	v_cndmask_b32_e32 v184, v183, v184, vcc
	v_bfi_b32 v184, s14, v184, v180
	v_add_f32_e32 v184, 1.0, v184
	v_mul_f32_e32 v95, 0.5, v95
	v_mul_f32_e32 v75, v75, v79
	v_mul_f32_e32 v95, v95, v184
	v_mul_f32_e32 v95, v75, v95
	global_store_dword v193, v94, s[12:13]
	global_store_dword v193, v95, s[12:13] offset:256
	s_add_u32 s12, s12, s18
	s_addc_u32 s13, s13, 0
	s_lshl_b32 s17, s92, 6
	s_add_u32 s69, s69, s17
	s_cmpk_lt_u32 s69, 0x8000
	s_cbranch_scc1 .Lgu0_chunk
	s_branch .LBB0_578

.Lgu1_start:
	s_mov_b64 exec, -1
	v_and_b32_e32 v0, 63, v205
	v_lshrrev_b32_e32 v1, 6, v205
	v_lshlrev_b32_e32 v193, 2, v0
	v_readfirstlane_b32 s34, v1
	v_and_b32_e32 v1, 3, v0
	v_lshlrev_b32_e32 v196, 4, v1
	v_lshlrev_b32_e32 v197, 4, v1
	s_nop 3
	s_lshl_b32 s13, s34, 14
	s_add_i32 s35, s93, s34
	v_and_b32_e32 v1, 3, v0
	v_lshlrev_b32_e32 v195, 4, v1
	v_lshrrev_b32_e32 v1, 2, v0
	v_add_u32_e32 v195, v195, v1
	v_lshl_add_u32 v195, v195, 2, s13
	v_lshrrev_b32_e32 v1, 2, v0
	v_lshl_add_u32 v194, v1, 2, s13
	v_add_u32_e32 v194, 0x2000, v194
	v_lshl_add_u32 v198, v0, 4, s13
	v_add_u32_e32 v200, s13, v193
	v_add_u32_e32 v199, 0x2000, v200
	v_lshrrev_b32_e32 v114, 3, v0
	v_lshlrev_b32_e32 v114, 8, v114
	v_and_b32_e32 v1, 7, v0
	v_lshl_add_u32 v114, v1, 3, v114
	s_lshl_b32 s14, s34, 9
	s_add_u32 s14, s14, 0x10000
	v_lshl_add_u32 v115, v0, 3, s14
	v_and_b32_e32 v1, 3, v0
	v_lshl_add_u32 v116, v1, 4, s14
.Lgu1_chunk:
	s_movk_i32 s18, 0xc0
	s_lshl_b32 s19, s92, 13
	s_mov_b32 s38, 0x11111111
	s_mov_b32 s39, 0x11111111
	s_mov_b32 s10, 0x22222222
	s_mov_b32 s11, 0x22222222
	s_mov_b32 s100, 0x44444444
	s_mov_b32 s101, 0x44444444
	s_mov_b32 s98, 0x88888888
	s_mov_b32 s99, 0x88888888
	s_add_u32 s6, s26, 0xd800000
	s_addc_u32 s7, s27, 0
	s_lshl_b32 s13, s35, 9
	s_add_u32 s6, s6, s13
	s_addc_u32 s7, s7, 0
	s_lshl_b32 s14, s92, 11
	global_load_dword v16, v193, s[6:7]
	global_load_dword v17, v193, s[6:7] offset:256
	s_add_u32 s6, s6, s14
	s_addc_u32 s7, s7, 0
	global_load_dword v18, v193, s[6:7]
	global_load_dword v19, v193, s[6:7] offset:256
	s_add_u32 s6, s6, s14
	s_addc_u32 s7, s7, 0
	global_load_dword v20, v193, s[6:7]
	global_load_dword v21, v193, s[6:7] offset:256
	s_add_u32 s6, s6, s14
	s_addc_u32 s7, s7, 0
	global_load_dword v22, v193, s[6:7]
	global_load_dword v23, v193, s[6:7] offset:256
	s_add_u32 s6, s6, s14
	s_addc_u32 s7, s7, 0
	global_load_dword v24, v193, s[6:7]
	global_load_dword v25, v193, s[6:7] offset:256
	s_add_u32 s6, s6, s14
	s_addc_u32 s7, s7, 0
	global_load_dword v26, v193, s[6:7]
	global_load_dword v27, v193, s[6:7] offset:256
	s_add_u32 s6, s6, s14
	s_addc_u32 s7, s7, 0
	global_load_dword v28, v193, s[6:7]
	global_load_dword v29, v193, s[6:7] offset:256
	s_add_u32 s6, s6, s14
	s_addc_u32 s7, s7, 0
	global_load_dword v30, v193, s[6:7]
	global_load_dword v31, v193, s[6:7] offset:256
	s_add_u32 s6, s6, s14
	s_addc_u32 s7, s7, 0
	global_load_dword v32, v193, s[6:7]
	global_load_dword v33, v193, s[6:7] offset:256
	s_add_u32 s6, s6, s14
	s_addc_u32 s7, s7, 0
	global_load_dword v34, v193, s[6:7]
	global_load_dword v35, v193, s[6:7] offset:256
	s_add_u32 s6, s6, s14
	s_addc_u32 s7, s7, 0
	global_load_dword v36, v193, s[6:7]
	global_load_dword v37, v193, s[6:7] offset:256
	s_add_u32 s6, s6, s14
	s_addc_u32 s7, s7, 0
	global_load_dword v38, v193, s[6:7]
	global_load_dword v39, v193, s[6:7] offset:256
	s_add_u32 s6, s6, s14
	s_addc_u32 s7, s7, 0
	global_load_dword v40, v193, s[6:7]
	global_load_dword v41, v193, s[6:7] offset:256
	s_add_u32 s6, s6, s14
	s_addc_u32 s7, s7, 0
	global_load_dword v42, v193, s[6:7]
	global_load_dword v43, v193, s[6:7] offset:256
	s_add_u32 s6, s6, s14
	s_addc_u32 s7, s7, 0
	global_load_dword v44, v193, s[6:7]
	global_load_dword v45, v193, s[6:7] offset:256
	s_add_u32 s6, s6, s14
	s_addc_u32 s7, s7, 0
	global_load_dword v46, v193, s[6:7]
	global_load_dword v47, v193, s[6:7] offset:256
	s_add_u32 s6, s6, s14
	s_addc_u32 s7, s7, 0
	v_mov_b32_e32 v0, 0
	v_mov_b32_e32 v1, 0
	v_mov_b32_e32 v2, 0
	v_mov_b32_e32 v3, 0
	ds_write_b128 v198, v[0:3] offset:0
	ds_write_b128 v198, v[0:3] offset:1024
	ds_write_b128 v198, v[0:3] offset:2048
	ds_write_b128 v198, v[0:3] offset:3072
	ds_write_b128 v198, v[0:3] offset:4096
	ds_write_b128 v198, v[0:3] offset:5120
	ds_write_b128 v198, v[0:3] offset:6144
	ds_write_b128 v198, v[0:3] offset:7168
	s_waitcnt vmcnt(0)
	ds_write2st64_b32 v199, v16, v17 offset0:0 offset1:1
	ds_write2st64_b32 v199, v18, v19 offset0:2 offset1:3
	ds_write2st64_b32 v199, v20, v21 offset0:4 offset1:5
	ds_write2st64_b32 v199, v22, v23 offset0:6 offset1:7
	ds_write2st64_b32 v199, v24, v25 offset0:8 offset1:9
	ds_write2st64_b32 v199, v26, v27 offset0:10 offset1:11
	ds_write2st64_b32 v199, v28, v29 offset0:12 offset1:13
	ds_write2st64_b32 v199, v30, v31 offset0:14 offset1:15
	ds_write2st64_b32 v199, v32, v33 offset0:16 offset1:17
	ds_write2st64_b32 v199, v34, v35 offset0:18 offset1:19
	ds_write2st64_b32 v199, v36, v37 offset0:20 offset1:21
	ds_write2st64_b32 v199, v38, v39 offset0:22 offset1:23
	ds_write2st64_b32 v199, v40, v41 offset0:24 offset1:25
	ds_write2st64_b32 v199, v42, v43 offset0:26 offset1:27
	ds_write2st64_b32 v199, v44, v45 offset0:28 offset1:29
	ds_write2st64_b32 v199, v46, v47 offset0:30 offset1:31
	s_waitcnt lgkmcnt(0)
	s_add_u32 s0, s26, 0x2800000
	s_addc_u32 s1, s27, 0
	s_add_u32 s4, s26, 0x5800000
	s_addc_u32 s5, s27, 0
	s_lshl_b32 s13, s35, 11
	s_add_u32 s4, s4, s13
	s_addc_u32 s5, s5, 0
	s_mov_b32 s12, 0
	s_and_b32 s15, s12, 15
	s_lshr_b32 s16, s12, 4
	s_lshl_b32 s17, s15, 9
	s_mul_i32 s13, s15, s19
	s_lshl_b32 s14, s16, 6
	s_add_u32 s13, s13, s14
	s_add_u32 s6, s4, s13
	s_addc_u32 s7, s5, 0
	s_mul_i32 s13, s16, 0x300000
	s_add_u32 s0, s26, 0x2800000
	s_addc_u32 s1, s27, 0
	s_add_u32 s0, s0, s13
	s_addc_u32 s1, s1, 0
	v_add_u32_e32 v201, s17, v194
	ds_read2_b32 v[184:185], v201 offset0:0 offset1:16
	ds_read2_b32 v[186:187], v201 offset0:32 offset1:48
	ds_read2_b32 v[188:189], v201 offset0:64 offset1:80
	ds_read2_b32 v[190:191], v201 offset0:96 offset1:112
	global_load_dwordx2 v[112:113], v114, s[6:7]
	s_waitcnt lgkmcnt(0)
	v_mad_u32_u24 v184, v184, s18, v197
	v_mad_u32_u24 v185, v185, s18, v197
	global_load_dwordx4 v[16:19], v184, s[0:1]
	global_load_dwordx4 v[20:23], v184, s[0:1] offset:64
	global_load_dwordx4 v[24:27], v184, s[0:1] offset:128
	global_load_dwordx4 v[28:31], v185, s[0:1]
	global_load_dwordx4 v[32:35], v185, s[0:1] offset:64
	global_load_dwordx4 v[36:39], v185, s[0:1] offset:128
	v_mad_u32_u24 v186, v186, s18, v197
	v_mad_u32_u24 v187, v187, s18, v197
	global_load_dwordx4 v[40:43], v186, s[0:1]
	global_load_dwordx4 v[44:47], v186, s[0:1] offset:64
	global_load_dwordx4 v[48:51], v186, s[0:1] offset:128
	global_load_dwordx4 v[52:55], v187, s[0:1]
	global_load_dwordx4 v[56:59], v187, s[0:1] offset:64
	global_load_dwordx4 v[60:63], v187, s[0:1] offset:128
	v_mad_u32_u24 v188, v188, s18, v197
	v_mad_u32_u24 v189, v189, s18, v197
	global_load_dwordx4 v[64:67], v188, s[0:1]
	global_load_dwordx4 v[68:71], v188, s[0:1] offset:64
	global_load_dwordx4 v[72:75], v188, s[0:1] offset:128
	global_load_dwordx4 v[76:79], v189, s[0:1]
	global_load_dwordx4 v[80:83], v189, s[0:1] offset:64
	global_load_dwordx4 v[84:87], v189, s[0:1] offset:128
	v_mad_u32_u24 v190, v190, s18, v197
	v_mad_u32_u24 v191, v191, s18, v197
	global_load_dwordx4 v[88:91], v190, s[0:1]
	global_load_dwordx4 v[92:95], v190, s[0:1] offset:64
	global_load_dwordx4 v[96:99], v190, s[0:1] offset:128
	global_load_dwordx4 v[100:103], v191, s[0:1]
	global_load_dwordx4 v[104:107], v191, s[0:1] offset:64
	global_load_dwordx4 v[108:111], v191, s[0:1] offset:128
	s_mov_b32 s14, 1
	s_and_b32 s15, s14, 15
	s_lshr_b32 s16, s14, 4
	s_lshl_b32 s17, s15, 9
	s_mul_i32 s13, s15, s19
	s_lshl_b32 s14, s16, 6
	s_add_u32 s13, s13, s14
	s_add_u32 s8, s4, s13
	s_addc_u32 s9, s5, 0
	s_mul_i32 s13, s16, 0x300000
	s_add_u32 s0, s26, 0x2800000
	s_addc_u32 s1, s27, 0
	s_add_u32 s0, s0, s13
	s_addc_u32 s1, s1, 0
	v_add_u32_e32 v202, s17, v194
	ds_read2_b32 v[184:185], v202 offset0:0 offset1:16
	ds_read2_b32 v[186:187], v202 offset0:32 offset1:48
	ds_read2_b32 v[188:189], v202 offset0:64 offset1:80
	ds_read2_b32 v[190:191], v202 offset0:96 offset1:112
.Lgu1_loop:
	s_and_b32 s15, s12, 15
	s_lshl_b32 s17, s15, 9
	v_add_u32_e32 v203, s17, v195
	s_waitcnt vmcnt(24)
	ds_write_b64 v115, v[112:113]
	ds_read_b128 v[144:147], v116 offset:0
	ds_read_b128 v[148:151], v116 offset:64
	ds_read_b128 v[152:155], v116 offset:128
	ds_read_b128 v[156:159], v116 offset:192
	ds_read_b128 v[160:163], v116 offset:256
	ds_read_b128 v[164:167], v116 offset:320
	ds_read_b128 v[168:171], v116 offset:384
	ds_read_b128 v[172:175], v116 offset:448
	s_waitcnt lgkmcnt(0)
	s_waitcnt vmcnt(21)
	v_cvt_scalef32_pk32_bf16_fp6 v[0:15], v[16:21], 1.0
	v_cvt_scalef32_pk32_bf16_fp6 v[128:143], v[22:27], 1.0
	v_dot2_f32_bf16 v176, v0, v144, 0
	v_dot2_f32_bf16 v177, v1, v145, 0
	v_dot2_f32_bf16 v178, v2, v148, 0
	v_dot2_f32_bf16 v179, v3, v149, 0
	v_dot2c_f32_bf16_e32 v176, v4, v152
	v_dot2c_f32_bf16_e32 v177, v5, v153
	v_dot2c_f32_bf16_e32 v178, v6, v156
	v_dot2c_f32_bf16_e32 v179, v7, v157
	v_dot2c_f32_bf16_e32 v176, v8, v160
	v_dot2c_f32_bf16_e32 v177, v9, v161
	v_dot2c_f32_bf16_e32 v178, v10, v164
	v_dot2c_f32_bf16_e32 v179, v11, v165
	v_dot2c_f32_bf16_e32 v176, v12, v168
	v_dot2c_f32_bf16_e32 v177, v13, v169
	v_dot2c_f32_bf16_e32 v178, v14, v172
	v_dot2c_f32_bf16_e32 v179, v15, v173
	v_dot2c_f32_bf16_e32 v176, v128, v146
	v_dot2c_f32_bf16_e32 v177, v129, v147
	v_dot2c_f32_bf16_e32 v178, v130, v150
	v_dot2c_f32_bf16_e32 v179, v131, v151
	v_dot2c_f32_bf16_e32 v176, v132, v154
	v_dot2c_f32_bf16_e32 v177, v133, v155
	v_dot2c_f32_bf16_e32 v178, v134, v158
	v_dot2c_f32_bf16_e32 v179, v135, v159
	v_dot2c_f32_bf16_e32 v176, v136, v162
	v_dot2c_f32_bf16_e32 v177, v137, v163
	v_dot2c_f32_bf16_e32 v178, v138, v166
	v_dot2c_f32_bf16_e32 v179, v139, v167
	v_dot2c_f32_bf16_e32 v176, v140, v170
	v_dot2c_f32_bf16_e32 v177, v141, v171
	v_dot2c_f32_bf16_e32 v178, v142, v174
	v_dot2c_f32_bf16_e32 v179, v143, v175
	s_waitcnt vmcnt(18)
	v_cvt_scalef32_pk32_bf16_fp6 v[0:15], v[28:33], 1.0
	v_cvt_scalef32_pk32_bf16_fp6 v[128:143], v[34:39], 1.0
	v_dot2_f32_bf16 v180, v0, v144, 0
	v_dot2_f32_bf16 v181, v1, v145, 0
	v_dot2_f32_bf16 v182, v2, v148, 0
	v_dot2_f32_bf16 v183, v3, v149, 0
	v_dot2c_f32_bf16_e32 v180, v4, v152
	v_dot2c_f32_bf16_e32 v181, v5, v153
	v_dot2c_f32_bf16_e32 v182, v6, v156
	v_dot2c_f32_bf16_e32 v183, v7, v157
	v_add_f32_e32 v192, v176, v177
	v_add_f32_e32 v206, v178, v179
	v_add_f32_e32 v192, v192, v206
	s_nop 1
	v_add_f32_dpp v192, v192, v192 quad_perm:[1,0,3,2] row_mask:0xf bank_mask:0xf
	s_nop 1
	v_add_f32_dpp v192, v192, v192 quad_perm:[2,3,0,1] row_mask:0xf bank_mask:0xf
	v_cndmask_b32_e64 v118, v118, v192, s[38:39]
	v_dot2c_f32_bf16_e32 v180, v8, v160
	v_dot2c_f32_bf16_e32 v181, v9, v161
	v_dot2c_f32_bf16_e32 v182, v10, v164
	v_dot2c_f32_bf16_e32 v183, v11, v165
	v_dot2c_f32_bf16_e32 v180, v12, v168
	v_dot2c_f32_bf16_e32 v181, v13, v169
	v_dot2c_f32_bf16_e32 v182, v14, v172
	v_dot2c_f32_bf16_e32 v183, v15, v173
	v_dot2c_f32_bf16_e32 v180, v128, v146
	v_dot2c_f32_bf16_e32 v181, v129, v147
	v_dot2c_f32_bf16_e32 v182, v130, v150
	v_dot2c_f32_bf16_e32 v183, v131, v151
	v_dot2c_f32_bf16_e32 v180, v132, v154
	v_dot2c_f32_bf16_e32 v181, v133, v155
	v_dot2c_f32_bf16_e32 v182, v134, v158
	v_dot2c_f32_bf16_e32 v183, v135, v159
	v_dot2c_f32_bf16_e32 v180, v136, v162
	v_dot2c_f32_bf16_e32 v181, v137, v163
	v_dot2c_f32_bf16_e32 v182, v138, v166
	v_dot2c_f32_bf16_e32 v183, v139, v167
	v_dot2c_f32_bf16_e32 v180, v140, v170
	v_dot2c_f32_bf16_e32 v181, v141, v171
	v_dot2c_f32_bf16_e32 v182, v142, v174
	v_dot2c_f32_bf16_e32 v183, v143, v175
	global_load_dwordx2 v[112:113], v114, s[8:9]
	s_waitcnt lgkmcnt(0)
	v_mad_u32_u24 v184, v184, s18, v197
	v_mad_u32_u24 v185, v185, s18, v197
	global_load_dwordx4 v[16:19], v184, s[0:1]
	global_load_dwordx4 v[20:23], v184, s[0:1] offset:64
	global_load_dwordx4 v[24:27], v184, s[0:1] offset:128
	global_load_dwordx4 v[28:31], v185, s[0:1]
	global_load_dwordx4 v[32:35], v185, s[0:1] offset:64
	global_load_dwordx4 v[36:39], v185, s[0:1] offset:128
	s_waitcnt vmcnt(22)
	v_cvt_scalef32_pk32_bf16_fp6 v[0:15], v[40:45], 1.0
	v_cvt_scalef32_pk32_bf16_fp6 v[128:143], v[46:51], 1.0
	v_dot2_f32_bf16 v176, v0, v144, 0
	v_dot2_f32_bf16 v177, v1, v145, 0
	v_dot2_f32_bf16 v178, v2, v148, 0
	v_dot2_f32_bf16 v179, v3, v149, 0
	v_dot2c_f32_bf16_e32 v176, v4, v152
	v_dot2c_f32_bf16_e32 v177, v5, v153
	v_dot2c_f32_bf16_e32 v178, v6, v156
	v_dot2c_f32_bf16_e32 v179, v7, v157
	v_add_f32_e32 v192, v180, v181
	v_add_f32_e32 v206, v182, v183
	v_add_f32_e32 v192, v192, v206
	s_nop 1
	v_add_f32_dpp v192, v192, v192 quad_perm:[1,0,3,2] row_mask:0xf bank_mask:0xf
	s_nop 1
	v_add_f32_dpp v192, v192, v192 quad_perm:[2,3,0,1] row_mask:0xf bank_mask:0xf
	v_cndmask_b32_e64 v118, v118, v192, s[10:11]
	v_dot2c_f32_bf16_e32 v176, v8, v160
	v_dot2c_f32_bf16_e32 v177, v9, v161
	v_dot2c_f32_bf16_e32 v178, v10, v164
	v_dot2c_f32_bf16_e32 v179, v11, v165
	v_dot2c_f32_bf16_e32 v176, v12, v168
	v_dot2c_f32_bf16_e32 v177, v13, v169
	v_dot2c_f32_bf16_e32 v178, v14, v172
	v_dot2c_f32_bf16_e32 v179, v15, v173
	v_dot2c_f32_bf16_e32 v176, v128, v146
	v_dot2c_f32_bf16_e32 v177, v129, v147
	v_dot2c_f32_bf16_e32 v178, v130, v150
	v_dot2c_f32_bf16_e32 v179, v131, v151
	v_dot2c_f32_bf16_e32 v176, v132, v154
	v_dot2c_f32_bf16_e32 v177, v133, v155
	v_dot2c_f32_bf16_e32 v178, v134, v158
	v_dot2c_f32_bf16_e32 v179, v135, v159
	v_dot2c_f32_bf16_e32 v176, v136, v162
	v_dot2c_f32_bf16_e32 v177, v137, v163
	v_dot2c_f32_bf16_e32 v178, v138, v166
	v_dot2c_f32_bf16_e32 v179, v139, v167
	v_dot2c_f32_bf16_e32 v176, v140, v170
	v_dot2c_f32_bf16_e32 v177, v141, v171
	v_dot2c_f32_bf16_e32 v178, v142, v174
	v_dot2c_f32_bf16_e32 v179, v143, v175
	s_waitcnt vmcnt(19)
	v_cvt_scalef32_pk32_bf16_fp6 v[0:15], v[52:57], 1.0
	v_cvt_scalef32_pk32_bf16_fp6 v[128:143], v[58:63], 1.0
	v_dot2_f32_bf16 v180, v0, v144, 0
	v_dot2_f32_bf16 v181, v1, v145, 0
	v_dot2_f32_bf16 v182, v2, v148, 0
	v_dot2_f32_bf16 v183, v3, v149, 0
	v_dot2c_f32_bf16_e32 v180, v4, v152
	v_dot2c_f32_bf16_e32 v181, v5, v153
	v_dot2c_f32_bf16_e32 v182, v6, v156
	v_dot2c_f32_bf16_e32 v183, v7, v157
	v_add_f32_e32 v192, v176, v177
	v_add_f32_e32 v206, v178, v179
	v_add_f32_e32 v192, v192, v206
	s_nop 1
	v_add_f32_dpp v192, v192, v192 quad_perm:[1,0,3,2] row_mask:0xf bank_mask:0xf
	s_nop 1
	v_add_f32_dpp v192, v192, v192 quad_perm:[2,3,0,1] row_mask:0xf bank_mask:0xf
	v_cndmask_b32_e64 v118, v118, v192, s[100:101]
	v_dot2c_f32_bf16_e32 v180, v8, v160
	v_dot2c_f32_bf16_e32 v181, v9, v161
	v_dot2c_f32_bf16_e32 v182, v10, v164
	v_dot2c_f32_bf16_e32 v183, v11, v165
	v_dot2c_f32_bf16_e32 v180, v12, v168
	v_dot2c_f32_bf16_e32 v181, v13, v169
	v_dot2c_f32_bf16_e32 v182, v14, v172
	v_dot2c_f32_bf16_e32 v183, v15, v173
	v_dot2c_f32_bf16_e32 v180, v128, v146
	v_dot2c_f32_bf16_e32 v181, v129, v147
	v_dot2c_f32_bf16_e32 v182, v130, v150
	v_dot2c_f32_bf16_e32 v183, v131, v151
	v_dot2c_f32_bf16_e32 v180, v132, v154
	v_dot2c_f32_bf16_e32 v181, v133, v155
	v_dot2c_f32_bf16_e32 v182, v134, v158
	v_dot2c_f32_bf16_e32 v183, v135, v159
	v_dot2c_f32_bf16_e32 v180, v136, v162
	v_dot2c_f32_bf16_e32 v181, v137, v163
	v_dot2c_f32_bf16_e32 v182, v138, v166
	v_dot2c_f32_bf16_e32 v183, v139, v167
	v_dot2c_f32_bf16_e32 v180, v140, v170
	v_dot2c_f32_bf16_e32 v181, v141, v171
	v_dot2c_f32_bf16_e32 v182, v142, v174
	v_dot2c_f32_bf16_e32 v183, v143, v175
	v_mad_u32_u24 v186, v186, s18, v197
	v_mad_u32_u24 v187, v187, s18, v197
	global_load_dwordx4 v[40:43], v186, s[0:1]
	global_load_dwordx4 v[44:47], v186, s[0:1] offset:64
	global_load_dwordx4 v[48:51], v186, s[0:1] offset:128
	global_load_dwordx4 v[52:55], v187, s[0:1]
	global_load_dwordx4 v[56:59], v187, s[0:1] offset:64
	global_load_dwordx4 v[60:63], v187, s[0:1] offset:128
	s_waitcnt vmcnt(22)
	v_cvt_scalef32_pk32_bf16_fp6 v[0:15], v[64:69], 1.0
	v_cvt_scalef32_pk32_bf16_fp6 v[128:143], v[70:75], 1.0
	v_dot2_f32_bf16 v176, v0, v144, 0
	v_dot2_f32_bf16 v177, v1, v145, 0
	v_dot2_f32_bf16 v178, v2, v148, 0
	v_dot2_f32_bf16 v179, v3, v149, 0
	v_dot2c_f32_bf16_e32 v176, v4, v152
	v_dot2c_f32_bf16_e32 v177, v5, v153
	v_dot2c_f32_bf16_e32 v178, v6, v156
	v_dot2c_f32_bf16_e32 v179, v7, v157
	v_add_f32_e32 v192, v180, v181
	v_add_f32_e32 v206, v182, v183
	v_add_f32_e32 v192, v192, v206
	s_nop 1
	v_add_f32_dpp v192, v192, v192 quad_perm:[1,0,3,2] row_mask:0xf bank_mask:0xf
	s_nop 1
	v_add_f32_dpp v192, v192, v192 quad_perm:[2,3,0,1] row_mask:0xf bank_mask:0xf
	v_cndmask_b32_e64 v118, v118, v192, s[98:99]
	ds_add_f32 v203, v118 offset:0
	v_dot2c_f32_bf16_e32 v176, v8, v160
	v_dot2c_f32_bf16_e32 v177, v9, v161
	v_dot2c_f32_bf16_e32 v178, v10, v164
	v_dot2c_f32_bf16_e32 v179, v11, v165
	v_dot2c_f32_bf16_e32 v176, v12, v168
	v_dot2c_f32_bf16_e32 v177, v13, v169
	v_dot2c_f32_bf16_e32 v178, v14, v172
	v_dot2c_f32_bf16_e32 v179, v15, v173
	v_dot2c_f32_bf16_e32 v176, v128, v146
	v_dot2c_f32_bf16_e32 v177, v129, v147
	v_dot2c_f32_bf16_e32 v178, v130, v150
	v_dot2c_f32_bf16_e32 v179, v131, v151
	v_dot2c_f32_bf16_e32 v176, v132, v154
	v_dot2c_f32_bf16_e32 v177, v133, v155
	v_dot2c_f32_bf16_e32 v178, v134, v158
	v_dot2c_f32_bf16_e32 v179, v135, v159
	v_dot2c_f32_bf16_e32 v176, v136, v162
	v_dot2c_f32_bf16_e32 v177, v137, v163
	v_dot2c_f32_bf16_e32 v178, v138, v166
	v_dot2c_f32_bf16_e32 v179, v139, v167
	v_dot2c_f32_bf16_e32 v176, v140, v170
	v_dot2c_f32_bf16_e32 v177, v141, v171
	v_dot2c_f32_bf16_e32 v178, v142, v174
	v_dot2c_f32_bf16_e32 v179, v143, v175
	s_waitcnt vmcnt(19)
	v_cvt_scalef32_pk32_bf16_fp6 v[0:15], v[76:81], 1.0
	v_cvt_scalef32_pk32_bf16_fp6 v[128:143], v[82:87], 1.0
	v_dot2_f32_bf16 v180, v0, v144, 0
	v_dot2_f32_bf16 v181, v1, v145, 0
	v_dot2_f32_bf16 v182, v2, v148, 0
	v_dot2_f32_bf16 v183, v3, v149, 0
	v_dot2c_f32_bf16_e32 v180, v4, v152
	v_dot2c_f32_bf16_e32 v181, v5, v153
	v_dot2c_f32_bf16_e32 v182, v6, v156
	v_dot2c_f32_bf16_e32 v183, v7, v157
	v_add_f32_e32 v192, v176, v177
	v_add_f32_e32 v206, v178, v179
	v_add_f32_e32 v192, v192, v206
	s_nop 1
	v_add_f32_dpp v192, v192, v192 quad_perm:[1,0,3,2] row_mask:0xf bank_mask:0xf
	s_nop 1
	v_add_f32_dpp v192, v192, v192 quad_perm:[2,3,0,1] row_mask:0xf bank_mask:0xf
	v_cndmask_b32_e64 v119, v119, v192, s[38:39]
	v_dot2c_f32_bf16_e32 v180, v8, v160
	v_dot2c_f32_bf16_e32 v181, v9, v161
	v_dot2c_f32_bf16_e32 v182, v10, v164
	v_dot2c_f32_bf16_e32 v183, v11, v165
	v_dot2c_f32_bf16_e32 v180, v12, v168
	v_dot2c_f32_bf16_e32 v181, v13, v169
	v_dot2c_f32_bf16_e32 v182, v14, v172
	v_dot2c_f32_bf16_e32 v183, v15, v173
	v_dot2c_f32_bf16_e32 v180, v128, v146
	v_dot2c_f32_bf16_e32 v181, v129, v147
	v_dot2c_f32_bf16_e32 v182, v130, v150
	v_dot2c_f32_bf16_e32 v183, v131, v151
	v_dot2c_f32_bf16_e32 v180, v132, v154
	v_dot2c_f32_bf16_e32 v181, v133, v155
	v_dot2c_f32_bf16_e32 v182, v134, v158
	v_dot2c_f32_bf16_e32 v183, v135, v159
	v_dot2c_f32_bf16_e32 v180, v136, v162
	v_dot2c_f32_bf16_e32 v181, v137, v163
	v_dot2c_f32_bf16_e32 v182, v138, v166
	v_dot2c_f32_bf16_e32 v183, v139, v167
	v_dot2c_f32_bf16_e32 v180, v140, v170
	v_dot2c_f32_bf16_e32 v181, v141, v171
	v_dot2c_f32_bf16_e32 v182, v142, v174
	v_dot2c_f32_bf16_e32 v183, v143, v175
	v_mad_u32_u24 v188, v188, s18, v197
	v_mad_u32_u24 v189, v189, s18, v197
	global_load_dwordx4 v[64:67], v188, s[0:1]
	global_load_dwordx4 v[68:71], v188, s[0:1] offset:64
	global_load_dwordx4 v[72:75], v188, s[0:1] offset:128
	global_load_dwordx4 v[76:79], v189, s[0:1]
	global_load_dwordx4 v[80:83], v189, s[0:1] offset:64
	global_load_dwordx4 v[84:87], v189, s[0:1] offset:128
	s_waitcnt vmcnt(22)
	v_cvt_scalef32_pk32_bf16_fp6 v[0:15], v[88:93], 1.0
	v_cvt_scalef32_pk32_bf16_fp6 v[128:143], v[94:99], 1.0
	v_dot2_f32_bf16 v176, v0, v144, 0
	v_dot2_f32_bf16 v177, v1, v145, 0
	v_dot2_f32_bf16 v178, v2, v148, 0
	v_dot2_f32_bf16 v179, v3, v149, 0
	v_dot2c_f32_bf16_e32 v176, v4, v152
	v_dot2c_f32_bf16_e32 v177, v5, v153
	v_dot2c_f32_bf16_e32 v178, v6, v156
	v_dot2c_f32_bf16_e32 v179, v7, v157
	v_add_f32_e32 v192, v180, v181
	v_add_f32_e32 v206, v182, v183
	v_add_f32_e32 v192, v192, v206
	s_nop 1
	v_add_f32_dpp v192, v192, v192 quad_perm:[1,0,3,2] row_mask:0xf bank_mask:0xf
	s_nop 1
	v_add_f32_dpp v192, v192, v192 quad_perm:[2,3,0,1] row_mask:0xf bank_mask:0xf
	v_cndmask_b32_e64 v119, v119, v192, s[10:11]
	v_dot2c_f32_bf16_e32 v176, v8, v160
	v_dot2c_f32_bf16_e32 v177, v9, v161
	v_dot2c_f32_bf16_e32 v178, v10, v164
	v_dot2c_f32_bf16_e32 v179, v11, v165
	v_dot2c_f32_bf16_e32 v176, v12, v168
	v_dot2c_f32_bf16_e32 v177, v13, v169
	v_dot2c_f32_bf16_e32 v178, v14, v172
	v_dot2c_f32_bf16_e32 v179, v15, v173
	v_dot2c_f32_bf16_e32 v176, v128, v146
	v_dot2c_f32_bf16_e32 v177, v129, v147
	v_dot2c_f32_bf16_e32 v178, v130, v150
	v_dot2c_f32_bf16_e32 v179, v131, v151
	v_dot2c_f32_bf16_e32 v176, v132, v154
	v_dot2c_f32_bf16_e32 v177, v133, v155
	v_dot2c_f32_bf16_e32 v178, v134, v158
	v_dot2c_f32_bf16_e32 v179, v135, v159
	v_dot2c_f32_bf16_e32 v176, v136, v162
	v_dot2c_f32_bf16_e32 v177, v137, v163
	v_dot2c_f32_bf16_e32 v178, v138, v166
	v_dot2c_f32_bf16_e32 v179, v139, v167
	v_dot2c_f32_bf16_e32 v176, v140, v170
	v_dot2c_f32_bf16_e32 v177, v141, v171
	v_dot2c_f32_bf16_e32 v178, v142, v174
	v_dot2c_f32_bf16_e32 v179, v143, v175
	s_waitcnt vmcnt(19)
	v_cvt_scalef32_pk32_bf16_fp6 v[0:15], v[100:105], 1.0
	v_cvt_scalef32_pk32_bf16_fp6 v[128:143], v[106:111], 1.0
	v_dot2_f32_bf16 v180, v0, v144, 0
	v_dot2_f32_bf16 v181, v1, v145, 0
	v_dot2_f32_bf16 v182, v2, v148, 0
	v_dot2_f32_bf16 v183, v3, v149, 0
	v_dot2c_f32_bf16_e32 v180, v4, v152
	v_dot2c_f32_bf16_e32 v181, v5, v153
	v_dot2c_f32_bf16_e32 v182, v6, v156
	v_dot2c_f32_bf16_e32 v183, v7, v157
	v_add_f32_e32 v192, v176, v177
	v_add_f32_e32 v206, v178, v179
	v_add_f32_e32 v192, v192, v206
	s_nop 1
	v_add_f32_dpp v192, v192, v192 quad_perm:[1,0,3,2] row_mask:0xf bank_mask:0xf
	s_nop 1
	v_add_f32_dpp v192, v192, v192 quad_perm:[2,3,0,1] row_mask:0xf bank_mask:0xf
	v_cndmask_b32_e64 v119, v119, v192, s[100:101]
	v_dot2c_f32_bf16_e32 v180, v8, v160
	v_dot2c_f32_bf16_e32 v181, v9, v161
	v_dot2c_f32_bf16_e32 v182, v10, v164
	v_dot2c_f32_bf16_e32 v183, v11, v165
	v_dot2c_f32_bf16_e32 v180, v12, v168
	v_dot2c_f32_bf16_e32 v181, v13, v169
	v_dot2c_f32_bf16_e32 v182, v14, v172
	v_dot2c_f32_bf16_e32 v183, v15, v173
	v_dot2c_f32_bf16_e32 v180, v128, v146
	v_dot2c_f32_bf16_e32 v181, v129, v147
	v_dot2c_f32_bf16_e32 v182, v130, v150
	v_dot2c_f32_bf16_e32 v183, v131, v151
	v_dot2c_f32_bf16_e32 v180, v132, v154
	v_dot2c_f32_bf16_e32 v181, v133, v155
	v_dot2c_f32_bf16_e32 v182, v134, v158
	v_dot2c_f32_bf16_e32 v183, v135, v159
	v_dot2c_f32_bf16_e32 v180, v136, v162
	v_dot2c_f32_bf16_e32 v181, v137, v163
	v_dot2c_f32_bf16_e32 v182, v138, v166
	v_dot2c_f32_bf16_e32 v183, v139, v167
	v_dot2c_f32_bf16_e32 v180, v140, v170
	v_dot2c_f32_bf16_e32 v181, v141, v171
	v_dot2c_f32_bf16_e32 v182, v142, v174
	v_dot2c_f32_bf16_e32 v183, v143, v175
	v_mad_u32_u24 v190, v190, s18, v197
	v_mad_u32_u24 v191, v191, s18, v197
	global_load_dwordx4 v[88:91], v190, s[0:1]
	global_load_dwordx4 v[92:95], v190, s[0:1] offset:64
	global_load_dwordx4 v[96:99], v190, s[0:1] offset:128
	global_load_dwordx4 v[100:103], v191, s[0:1]
	global_load_dwordx4 v[104:107], v191, s[0:1] offset:64
	global_load_dwordx4 v[108:111], v191, s[0:1] offset:128
	s_add_u32 s12, s12, 1
	s_and_b32 s12, s12, 63
	s_add_u32 s14, s12, 1
	s_and_b32 s14, s14, 63
	s_and_b32 s15, s14, 15
	s_lshr_b32 s16, s14, 4
	s_lshl_b32 s17, s15, 9
	s_mul_i32 s13, s15, s19
	s_lshl_b32 s14, s16, 6
	s_add_u32 s13, s13, s14
	s_add_u32 s6, s4, s13
	s_addc_u32 s7, s5, 0
	s_mul_i32 s13, s16, 0x300000
	s_add_u32 s0, s26, 0x2800000
	s_addc_u32 s1, s27, 0
	s_add_u32 s0, s0, s13
	s_addc_u32 s1, s1, 0
	v_add_u32_e32 v201, s17, v194
	ds_read2_b32 v[184:185], v201 offset0:0 offset1:16
	ds_read2_b32 v[186:187], v201 offset0:32 offset1:48
	ds_read2_b32 v[188:189], v201 offset0:64 offset1:80
	ds_read2_b32 v[190:191], v201 offset0:96 offset1:112
	v_add_f32_e32 v192, v180, v181
	v_add_f32_e32 v206, v182, v183
	v_add_f32_e32 v192, v192, v206
	s_nop 1
	v_add_f32_dpp v192, v192, v192 quad_perm:[1,0,3,2] row_mask:0xf bank_mask:0xf
	s_nop 1
	v_add_f32_dpp v192, v192, v192 quad_perm:[2,3,0,1] row_mask:0xf bank_mask:0xf
	v_cndmask_b32_e64 v119, v119, v192, s[98:99]
	ds_add_f32 v203, v119 offset:256
	s_and_b32 s15, s12, 15
	s_lshl_b32 s17, s15, 9
	v_add_u32_e32 v204, s17, v195
	s_waitcnt vmcnt(24)
	ds_write_b64 v115, v[112:113]
	ds_read_b128 v[144:147], v116 offset:0
	ds_read_b128 v[148:151], v116 offset:64
	ds_read_b128 v[152:155], v116 offset:128
	ds_read_b128 v[156:159], v116 offset:192
	ds_read_b128 v[160:163], v116 offset:256
	ds_read_b128 v[164:167], v116 offset:320
	ds_read_b128 v[168:171], v116 offset:384
	ds_read_b128 v[172:175], v116 offset:448
	s_waitcnt lgkmcnt(0)
	s_waitcnt vmcnt(21)
	v_cvt_scalef32_pk32_bf16_fp6 v[0:15], v[16:21], 1.0
	v_cvt_scalef32_pk32_bf16_fp6 v[128:143], v[22:27], 1.0
	v_dot2_f32_bf16 v176, v0, v144, 0
	v_dot2_f32_bf16 v177, v1, v145, 0
	v_dot2_f32_bf16 v178, v2, v148, 0
	v_dot2_f32_bf16 v179, v3, v149, 0
	v_dot2c_f32_bf16_e32 v176, v4, v152
	v_dot2c_f32_bf16_e32 v177, v5, v153
	v_dot2c_f32_bf16_e32 v178, v6, v156
	v_dot2c_f32_bf16_e32 v179, v7, v157
	v_dot2c_f32_bf16_e32 v176, v8, v160
	v_dot2c_f32_bf16_e32 v177, v9, v161
	v_dot2c_f32_bf16_e32 v178, v10, v164
	v_dot2c_f32_bf16_e32 v179, v11, v165
	v_dot2c_f32_bf16_e32 v176, v12, v168
	v_dot2c_f32_bf16_e32 v177, v13, v169
	v_dot2c_f32_bf16_e32 v178, v14, v172
	v_dot2c_f32_bf16_e32 v179, v15, v173
	v_dot2c_f32_bf16_e32 v176, v128, v146
	v_dot2c_f32_bf16_e32 v177, v129, v147
	v_dot2c_f32_bf16_e32 v178, v130, v150
	v_dot2c_f32_bf16_e32 v179, v131, v151
	v_dot2c_f32_bf16_e32 v176, v132, v154
	v_dot2c_f32_bf16_e32 v177, v133, v155
	v_dot2c_f32_bf16_e32 v178, v134, v158
	v_dot2c_f32_bf16_e32 v179, v135, v159
	v_dot2c_f32_bf16_e32 v176, v136, v162
	v_dot2c_f32_bf16_e32 v177, v137, v163
	v_dot2c_f32_bf16_e32 v178, v138, v166
	v_dot2c_f32_bf16_e32 v179, v139, v167
	v_dot2c_f32_bf16_e32 v176, v140, v170
	v_dot2c_f32_bf16_e32 v177, v141, v171
	v_dot2c_f32_bf16_e32 v178, v142, v174
	v_dot2c_f32_bf16_e32 v179, v143, v175
	s_waitcnt vmcnt(18)
	v_cvt_scalef32_pk32_bf16_fp6 v[0:15], v[28:33], 1.0
	v_cvt_scalef32_pk32_bf16_fp6 v[128:143], v[34:39], 1.0
	v_dot2_f32_bf16 v180, v0, v144, 0
	v_dot2_f32_bf16 v181, v1, v145, 0
	v_dot2_f32_bf16 v182, v2, v148, 0
	v_dot2_f32_bf16 v183, v3, v149, 0
	v_dot2c_f32_bf16_e32 v180, v4, v152
	v_dot2c_f32_bf16_e32 v181, v5, v153
	v_dot2c_f32_bf16_e32 v182, v6, v156
	v_dot2c_f32_bf16_e32 v183, v7, v157
	v_add_f32_e32 v192, v176, v177
	v_add_f32_e32 v206, v178, v179
	v_add_f32_e32 v192, v192, v206
	s_nop 1
	v_add_f32_dpp v192, v192, v192 quad_perm:[1,0,3,2] row_mask:0xf bank_mask:0xf
	s_nop 1
	v_add_f32_dpp v192, v192, v192 quad_perm:[2,3,0,1] row_mask:0xf bank_mask:0xf
	v_cndmask_b32_e64 v118, v118, v192, s[38:39]
	v_dot2c_f32_bf16_e32 v180, v8, v160
	v_dot2c_f32_bf16_e32 v181, v9, v161
	v_dot2c_f32_bf16_e32 v182, v10, v164
	v_dot2c_f32_bf16_e32 v183, v11, v165
	v_dot2c_f32_bf16_e32 v180, v12, v168
	v_dot2c_f32_bf16_e32 v181, v13, v169
	v_dot2c_f32_bf16_e32 v182, v14, v172
	v_dot2c_f32_bf16_e32 v183, v15, v173
	v_dot2c_f32_bf16_e32 v180, v128, v146
	v_dot2c_f32_bf16_e32 v181, v129, v147
	v_dot2c_f32_bf16_e32 v182, v130, v150
	v_dot2c_f32_bf16_e32 v183, v131, v151
	v_dot2c_f32_bf16_e32 v180, v132, v154
	v_dot2c_f32_bf16_e32 v181, v133, v155
	v_dot2c_f32_bf16_e32 v182, v134, v158
	v_dot2c_f32_bf16_e32 v183, v135, v159
	v_dot2c_f32_bf16_e32 v180, v136, v162
	v_dot2c_f32_bf16_e32 v181, v137, v163
	v_dot2c_f32_bf16_e32 v182, v138, v166
	v_dot2c_f32_bf16_e32 v183, v139, v167
	v_dot2c_f32_bf16_e32 v180, v140, v170
	v_dot2c_f32_bf16_e32 v181, v141, v171
	v_dot2c_f32_bf16_e32 v182, v142, v174
	v_dot2c_f32_bf16_e32 v183, v143, v175
	global_load_dwordx2 v[112:113], v114, s[6:7]
	s_waitcnt lgkmcnt(0)
	v_mad_u32_u24 v184, v184, s18, v197
	v_mad_u32_u24 v185, v185, s18, v197
	global_load_dwordx4 v[16:19], v184, s[0:1]
	global_load_dwordx4 v[20:23], v184, s[0:1] offset:64
	global_load_dwordx4 v[24:27], v184, s[0:1] offset:128
	global_load_dwordx4 v[28:31], v185, s[0:1]
	global_load_dwordx4 v[32:35], v185, s[0:1] offset:64
	global_load_dwordx4 v[36:39], v185, s[0:1] offset:128
	s_waitcnt vmcnt(22)
	v_cvt_scalef32_pk32_bf16_fp6 v[0:15], v[40:45], 1.0
	v_cvt_scalef32_pk32_bf16_fp6 v[128:143], v[46:51], 1.0
	v_dot2_f32_bf16 v176, v0, v144, 0
	v_dot2_f32_bf16 v177, v1, v145, 0
	v_dot2_f32_bf16 v178, v2, v148, 0
	v_dot2_f32_bf16 v179, v3, v149, 0
	v_dot2c_f32_bf16_e32 v176, v4, v152
	v_dot2c_f32_bf16_e32 v177, v5, v153
	v_dot2c_f32_bf16_e32 v178, v6, v156
	v_dot2c_f32_bf16_e32 v179, v7, v157
	v_add_f32_e32 v192, v180, v181
	v_add_f32_e32 v206, v182, v183
	v_add_f32_e32 v192, v192, v206
	s_nop 1
	v_add_f32_dpp v192, v192, v192 quad_perm:[1,0,3,2] row_mask:0xf bank_mask:0xf
	s_nop 1
	v_add_f32_dpp v192, v192, v192 quad_perm:[2,3,0,1] row_mask:0xf bank_mask:0xf
	v_cndmask_b32_e64 v118, v118, v192, s[10:11]
	v_dot2c_f32_bf16_e32 v176, v8, v160
	v_dot2c_f32_bf16_e32 v177, v9, v161
	v_dot2c_f32_bf16_e32 v178, v10, v164
	v_dot2c_f32_bf16_e32 v179, v11, v165
	v_dot2c_f32_bf16_e32 v176, v12, v168
	v_dot2c_f32_bf16_e32 v177, v13, v169
	v_dot2c_f32_bf16_e32 v178, v14, v172
	v_dot2c_f32_bf16_e32 v179, v15, v173
	v_dot2c_f32_bf16_e32 v176, v128, v146
	v_dot2c_f32_bf16_e32 v177, v129, v147
	v_dot2c_f32_bf16_e32 v178, v130, v150
	v_dot2c_f32_bf16_e32 v179, v131, v151
	v_dot2c_f32_bf16_e32 v176, v132, v154
	v_dot2c_f32_bf16_e32 v177, v133, v155
	v_dot2c_f32_bf16_e32 v178, v134, v158
	v_dot2c_f32_bf16_e32 v179, v135, v159
	v_dot2c_f32_bf16_e32 v176, v136, v162
	v_dot2c_f32_bf16_e32 v177, v137, v163
	v_dot2c_f32_bf16_e32 v178, v138, v166
	v_dot2c_f32_bf16_e32 v179, v139, v167
	v_dot2c_f32_bf16_e32 v176, v140, v170
	v_dot2c_f32_bf16_e32 v177, v141, v171
	v_dot2c_f32_bf16_e32 v178, v142, v174
	v_dot2c_f32_bf16_e32 v179, v143, v175
	s_waitcnt vmcnt(19)
	v_cvt_scalef32_pk32_bf16_fp6 v[0:15], v[52:57], 1.0
	v_cvt_scalef32_pk32_bf16_fp6 v[128:143], v[58:63], 1.0
	v_dot2_f32_bf16 v180, v0, v144, 0
	v_dot2_f32_bf16 v181, v1, v145, 0
	v_dot2_f32_bf16 v182, v2, v148, 0
	v_dot2_f32_bf16 v183, v3, v149, 0
	v_dot2c_f32_bf16_e32 v180, v4, v152
	v_dot2c_f32_bf16_e32 v181, v5, v153
	v_dot2c_f32_bf16_e32 v182, v6, v156
	v_dot2c_f32_bf16_e32 v183, v7, v157
	v_add_f32_e32 v192, v176, v177
	v_add_f32_e32 v206, v178, v179
	v_add_f32_e32 v192, v192, v206
	s_nop 1
	v_add_f32_dpp v192, v192, v192 quad_perm:[1,0,3,2] row_mask:0xf bank_mask:0xf
	s_nop 1
	v_add_f32_dpp v192, v192, v192 quad_perm:[2,3,0,1] row_mask:0xf bank_mask:0xf
	v_cndmask_b32_e64 v118, v118, v192, s[100:101]
	v_dot2c_f32_bf16_e32 v180, v8, v160
	v_dot2c_f32_bf16_e32 v181, v9, v161
	v_dot2c_f32_bf16_e32 v182, v10, v164
	v_dot2c_f32_bf16_e32 v183, v11, v165
	v_dot2c_f32_bf16_e32 v180, v12, v168
	v_dot2c_f32_bf16_e32 v181, v13, v169
	v_dot2c_f32_bf16_e32 v182, v14, v172
	v_dot2c_f32_bf16_e32 v183, v15, v173
	v_dot2c_f32_bf16_e32 v180, v128, v146
	v_dot2c_f32_bf16_e32 v181, v129, v147
	v_dot2c_f32_bf16_e32 v182, v130, v150
	v_dot2c_f32_bf16_e32 v183, v131, v151
	v_dot2c_f32_bf16_e32 v180, v132, v154
	v_dot2c_f32_bf16_e32 v181, v133, v155
	v_dot2c_f32_bf16_e32 v182, v134, v158
	v_dot2c_f32_bf16_e32 v183, v135, v159
	v_dot2c_f32_bf16_e32 v180, v136, v162
	v_dot2c_f32_bf16_e32 v181, v137, v163
	v_dot2c_f32_bf16_e32 v182, v138, v166
	v_dot2c_f32_bf16_e32 v183, v139, v167
	v_dot2c_f32_bf16_e32 v180, v140, v170
	v_dot2c_f32_bf16_e32 v181, v141, v171
	v_dot2c_f32_bf16_e32 v182, v142, v174
	v_dot2c_f32_bf16_e32 v183, v143, v175
	v_mad_u32_u24 v186, v186, s18, v197
	v_mad_u32_u24 v187, v187, s18, v197
	global_load_dwordx4 v[40:43], v186, s[0:1]
	global_load_dwordx4 v[44:47], v186, s[0:1] offset:64
	global_load_dwordx4 v[48:51], v186, s[0:1] offset:128
	global_load_dwordx4 v[52:55], v187, s[0:1]
	global_load_dwordx4 v[56:59], v187, s[0:1] offset:64
	global_load_dwordx4 v[60:63], v187, s[0:1] offset:128
	s_waitcnt vmcnt(22)
	v_cvt_scalef32_pk32_bf16_fp6 v[0:15], v[64:69], 1.0
	v_cvt_scalef32_pk32_bf16_fp6 v[128:143], v[70:75], 1.0
	v_dot2_f32_bf16 v176, v0, v144, 0
	v_dot2_f32_bf16 v177, v1, v145, 0
	v_dot2_f32_bf16 v178, v2, v148, 0
	v_dot2_f32_bf16 v179, v3, v149, 0
	v_dot2c_f32_bf16_e32 v176, v4, v152
	v_dot2c_f32_bf16_e32 v177, v5, v153
	v_dot2c_f32_bf16_e32 v178, v6, v156
	v_dot2c_f32_bf16_e32 v179, v7, v157
	v_add_f32_e32 v192, v180, v181
	v_add_f32_e32 v206, v182, v183
	v_add_f32_e32 v192, v192, v206
	s_nop 1
	v_add_f32_dpp v192, v192, v192 quad_perm:[1,0,3,2] row_mask:0xf bank_mask:0xf
	s_nop 1
	v_add_f32_dpp v192, v192, v192 quad_perm:[2,3,0,1] row_mask:0xf bank_mask:0xf
	v_cndmask_b32_e64 v118, v118, v192, s[98:99]
	ds_add_f32 v204, v118 offset:0
	v_dot2c_f32_bf16_e32 v176, v8, v160
	v_dot2c_f32_bf16_e32 v177, v9, v161
	v_dot2c_f32_bf16_e32 v178, v10, v164
	v_dot2c_f32_bf16_e32 v179, v11, v165
	v_dot2c_f32_bf16_e32 v176, v12, v168
	v_dot2c_f32_bf16_e32 v177, v13, v169
	v_dot2c_f32_bf16_e32 v178, v14, v172
	v_dot2c_f32_bf16_e32 v179, v15, v173
	v_dot2c_f32_bf16_e32 v176, v128, v146
	v_dot2c_f32_bf16_e32 v177, v129, v147
	v_dot2c_f32_bf16_e32 v178, v130, v150
	v_dot2c_f32_bf16_e32 v179, v131, v151
	v_dot2c_f32_bf16_e32 v176, v132, v154
	v_dot2c_f32_bf16_e32 v177, v133, v155
	v_dot2c_f32_bf16_e32 v178, v134, v158
	v_dot2c_f32_bf16_e32 v179, v135, v159
	v_dot2c_f32_bf16_e32 v176, v136, v162
	v_dot2c_f32_bf16_e32 v177, v137, v163
	v_dot2c_f32_bf16_e32 v178, v138, v166
	v_dot2c_f32_bf16_e32 v179, v139, v167
	v_dot2c_f32_bf16_e32 v176, v140, v170
	v_dot2c_f32_bf16_e32 v177, v141, v171
	v_dot2c_f32_bf16_e32 v178, v142, v174
	v_dot2c_f32_bf16_e32 v179, v143, v175
	s_waitcnt vmcnt(19)
	v_cvt_scalef32_pk32_bf16_fp6 v[0:15], v[76:81], 1.0
	v_cvt_scalef32_pk32_bf16_fp6 v[128:143], v[82:87], 1.0
	v_dot2_f32_bf16 v180, v0, v144, 0
	v_dot2_f32_bf16 v181, v1, v145, 0
	v_dot2_f32_bf16 v182, v2, v148, 0
	v_dot2_f32_bf16 v183, v3, v149, 0
	v_dot2c_f32_bf16_e32 v180, v4, v152
	v_dot2c_f32_bf16_e32 v181, v5, v153
	v_dot2c_f32_bf16_e32 v182, v6, v156
	v_dot2c_f32_bf16_e32 v183, v7, v157
	v_add_f32_e32 v192, v176, v177
	v_add_f32_e32 v206, v178, v179
	v_add_f32_e32 v192, v192, v206
	s_nop 1
	v_add_f32_dpp v192, v192, v192 quad_perm:[1,0,3,2] row_mask:0xf bank_mask:0xf
	s_nop 1
	v_add_f32_dpp v192, v192, v192 quad_perm:[2,3,0,1] row_mask:0xf bank_mask:0xf
	v_cndmask_b32_e64 v119, v119, v192, s[38:39]
	v_dot2c_f32_bf16_e32 v180, v8, v160
	v_dot2c_f32_bf16_e32 v181, v9, v161
	v_dot2c_f32_bf16_e32 v182, v10, v164
	v_dot2c_f32_bf16_e32 v183, v11, v165
	v_dot2c_f32_bf16_e32 v180, v12, v168
	v_dot2c_f32_bf16_e32 v181, v13, v169
	v_dot2c_f32_bf16_e32 v182, v14, v172
	v_dot2c_f32_bf16_e32 v183, v15, v173
	v_dot2c_f32_bf16_e32 v180, v128, v146
	v_dot2c_f32_bf16_e32 v181, v129, v147
	v_dot2c_f32_bf16_e32 v182, v130, v150
	v_dot2c_f32_bf16_e32 v183, v131, v151
	v_dot2c_f32_bf16_e32 v180, v132, v154
	v_dot2c_f32_bf16_e32 v181, v133, v155
	v_dot2c_f32_bf16_e32 v182, v134, v158
	v_dot2c_f32_bf16_e32 v183, v135, v159
	v_dot2c_f32_bf16_e32 v180, v136, v162
	v_dot2c_f32_bf16_e32 v181, v137, v163
	v_dot2c_f32_bf16_e32 v182, v138, v166
	v_dot2c_f32_bf16_e32 v183, v139, v167
	v_dot2c_f32_bf16_e32 v180, v140, v170
	v_dot2c_f32_bf16_e32 v181, v141, v171
	v_dot2c_f32_bf16_e32 v182, v142, v174
	v_dot2c_f32_bf16_e32 v183, v143, v175
	v_mad_u32_u24 v188, v188, s18, v197
	v_mad_u32_u24 v189, v189, s18, v197
	global_load_dwordx4 v[64:67], v188, s[0:1]
	global_load_dwordx4 v[68:71], v188, s[0:1] offset:64
	global_load_dwordx4 v[72:75], v188, s[0:1] offset:128
	global_load_dwordx4 v[76:79], v189, s[0:1]
	global_load_dwordx4 v[80:83], v189, s[0:1] offset:64
	global_load_dwordx4 v[84:87], v189, s[0:1] offset:128
	s_waitcnt vmcnt(22)
	v_cvt_scalef32_pk32_bf16_fp6 v[0:15], v[88:93], 1.0
	v_cvt_scalef32_pk32_bf16_fp6 v[128:143], v[94:99], 1.0
	v_dot2_f32_bf16 v176, v0, v144, 0
	v_dot2_f32_bf16 v177, v1, v145, 0
	v_dot2_f32_bf16 v178, v2, v148, 0
	v_dot2_f32_bf16 v179, v3, v149, 0
	v_dot2c_f32_bf16_e32 v176, v4, v152
	v_dot2c_f32_bf16_e32 v177, v5, v153
	v_dot2c_f32_bf16_e32 v178, v6, v156
	v_dot2c_f32_bf16_e32 v179, v7, v157
	v_add_f32_e32 v192, v180, v181
	v_add_f32_e32 v206, v182, v183
	v_add_f32_e32 v192, v192, v206
	s_nop 1
	v_add_f32_dpp v192, v192, v192 quad_perm:[1,0,3,2] row_mask:0xf bank_mask:0xf
	s_nop 1
	v_add_f32_dpp v192, v192, v192 quad_perm:[2,3,0,1] row_mask:0xf bank_mask:0xf
	v_cndmask_b32_e64 v119, v119, v192, s[10:11]
	v_dot2c_f32_bf16_e32 v176, v8, v160
	v_dot2c_f32_bf16_e32 v177, v9, v161
	v_dot2c_f32_bf16_e32 v178, v10, v164
	v_dot2c_f32_bf16_e32 v179, v11, v165
	v_dot2c_f32_bf16_e32 v176, v12, v168
	v_dot2c_f32_bf16_e32 v177, v13, v169
	v_dot2c_f32_bf16_e32 v178, v14, v172
	v_dot2c_f32_bf16_e32 v179, v15, v173
	v_dot2c_f32_bf16_e32 v176, v128, v146
	v_dot2c_f32_bf16_e32 v177, v129, v147
	v_dot2c_f32_bf16_e32 v178, v130, v150
	v_dot2c_f32_bf16_e32 v179, v131, v151
	v_dot2c_f32_bf16_e32 v176, v132, v154
	v_dot2c_f32_bf16_e32 v177, v133, v155
	v_dot2c_f32_bf16_e32 v178, v134, v158
	v_dot2c_f32_bf16_e32 v179, v135, v159
	v_dot2c_f32_bf16_e32 v176, v136, v162
	v_dot2c_f32_bf16_e32 v177, v137, v163
	v_dot2c_f32_bf16_e32 v178, v138, v166
	v_dot2c_f32_bf16_e32 v179, v139, v167
	v_dot2c_f32_bf16_e32 v176, v140, v170
	v_dot2c_f32_bf16_e32 v177, v141, v171
	v_dot2c_f32_bf16_e32 v178, v142, v174
	v_dot2c_f32_bf16_e32 v179, v143, v175
	s_waitcnt vmcnt(19)
	v_cvt_scalef32_pk32_bf16_fp6 v[0:15], v[100:105], 1.0
	v_cvt_scalef32_pk32_bf16_fp6 v[128:143], v[106:111], 1.0
	v_dot2_f32_bf16 v180, v0, v144, 0
	v_dot2_f32_bf16 v181, v1, v145, 0
	v_dot2_f32_bf16 v182, v2, v148, 0
	v_dot2_f32_bf16 v183, v3, v149, 0
	v_dot2c_f32_bf16_e32 v180, v4, v152
	v_dot2c_f32_bf16_e32 v181, v5, v153
	v_dot2c_f32_bf16_e32 v182, v6, v156
	v_dot2c_f32_bf16_e32 v183, v7, v157
	v_add_f32_e32 v192, v176, v177
	v_add_f32_e32 v206, v178, v179
	v_add_f32_e32 v192, v192, v206
	s_nop 1
	v_add_f32_dpp v192, v192, v192 quad_perm:[1,0,3,2] row_mask:0xf bank_mask:0xf
	s_nop 1
	v_add_f32_dpp v192, v192, v192 quad_perm:[2,3,0,1] row_mask:0xf bank_mask:0xf
	v_cndmask_b32_e64 v119, v119, v192, s[100:101]
	v_dot2c_f32_bf16_e32 v180, v8, v160
	v_dot2c_f32_bf16_e32 v181, v9, v161
	v_dot2c_f32_bf16_e32 v182, v10, v164
	v_dot2c_f32_bf16_e32 v183, v11, v165
	v_dot2c_f32_bf16_e32 v180, v12, v168
	v_dot2c_f32_bf16_e32 v181, v13, v169
	v_dot2c_f32_bf16_e32 v182, v14, v172
	v_dot2c_f32_bf16_e32 v183, v15, v173
	v_dot2c_f32_bf16_e32 v180, v128, v146
	v_dot2c_f32_bf16_e32 v181, v129, v147
	v_dot2c_f32_bf16_e32 v182, v130, v150
	v_dot2c_f32_bf16_e32 v183, v131, v151
	v_dot2c_f32_bf16_e32 v180, v132, v154
	v_dot2c_f32_bf16_e32 v181, v133, v155
	v_dot2c_f32_bf16_e32 v182, v134, v158
	v_dot2c_f32_bf16_e32 v183, v135, v159
	v_dot2c_f32_bf16_e32 v180, v136, v162
	v_dot2c_f32_bf16_e32 v181, v137, v163
	v_dot2c_f32_bf16_e32 v182, v138, v166
	v_dot2c_f32_bf16_e32 v183, v139, v167
	v_dot2c_f32_bf16_e32 v180, v140, v170
	v_dot2c_f32_bf16_e32 v181, v141, v171
	v_dot2c_f32_bf16_e32 v182, v142, v174
	v_dot2c_f32_bf16_e32 v183, v143, v175
	v_mad_u32_u24 v190, v190, s18, v197
	v_mad_u32_u24 v191, v191, s18, v197
	global_load_dwordx4 v[88:91], v190, s[0:1]
	global_load_dwordx4 v[92:95], v190, s[0:1] offset:64
	global_load_dwordx4 v[96:99], v190, s[0:1] offset:128
	global_load_dwordx4 v[100:103], v191, s[0:1]
	global_load_dwordx4 v[104:107], v191, s[0:1] offset:64
	global_load_dwordx4 v[108:111], v191, s[0:1] offset:128
	s_add_u32 s12, s12, 1
	s_and_b32 s12, s12, 63
	s_add_u32 s14, s12, 1
	s_and_b32 s14, s14, 63
	s_and_b32 s15, s14, 15
	s_lshr_b32 s16, s14, 4
	s_lshl_b32 s17, s15, 9
	s_mul_i32 s13, s15, s19
	s_lshl_b32 s14, s16, 6
	s_add_u32 s13, s13, s14
	s_add_u32 s8, s4, s13
	s_addc_u32 s9, s5, 0
	s_mul_i32 s13, s16, 0x300000
	s_add_u32 s0, s26, 0x2800000
	s_addc_u32 s1, s27, 0
	s_add_u32 s0, s0, s13
	s_addc_u32 s1, s1, 0
	v_add_u32_e32 v202, s17, v194
	ds_read2_b32 v[184:185], v202 offset0:0 offset1:16
	ds_read2_b32 v[186:187], v202 offset0:32 offset1:48
	ds_read2_b32 v[188:189], v202 offset0:64 offset1:80
	ds_read2_b32 v[190:191], v202 offset0:96 offset1:112
	v_add_f32_e32 v192, v180, v181
	v_add_f32_e32 v206, v182, v183
	v_add_f32_e32 v192, v192, v206
	s_nop 1
	v_add_f32_dpp v192, v192, v192 quad_perm:[1,0,3,2] row_mask:0xf bank_mask:0xf
	s_nop 1
	v_add_f32_dpp v192, v192, v192 quad_perm:[2,3,0,1] row_mask:0xf bank_mask:0xf
	v_cndmask_b32_e64 v119, v119, v192, s[98:99]
	ds_add_f32 v204, v119 offset:256
	s_cmp_lg_u32 s12, 0
	s_cbranch_scc1 .Lgu1_loop
	s_waitcnt vmcnt(0) lgkmcnt(0)
	s_add_u32 s0, s26, 0x1420000
	s_addc_u32 s1, s27, 0
	s_add_u32 s4, s26, 0x1430000
	s_addc_u32 s5, s27, 0
	s_lshl_b32 s13, s35, 9
	s_add_u32 s6, s26, 0xe800000
	s_addc_u32 s7, s27, 0
	s_add_u32 s6, s6, s13
	s_addc_u32 s7, s7, 0
	s_add_u32 s8, s26, 0xf800000
	s_addc_u32 s9, s27, 0
	s_add_u32 s8, s8, s13
	s_addc_u32 s9, s9, 0
	s_lshl_b32 s14, s92, 11
	s_mov_b32 s12, 0x378e98ab
	s_mov_b32 s15, 0x3b7cd369
	s_mov_b32 s16, 0xbcc618b2
	s_mov_b32 s17, 0x3dda74e4
	s_mov_b32 s18, 0x3f228afd
	s_mov_b32 s19, 0x3e03c728
	s_mov_b32 s98, 0xbfb8aa3b
	s_mov_b32 s38, 0x42ce8ed0
	s_mov_b32 s39, 0xc2b17218
	s_mov_b32 s10, 0x7fffffff
	v_mov_b32_e32 v176, 0x3ba10414
	v_mov_b32_e32 v177, 0xb9c68948
	v_mov_b32_e32 v178, 0x7f800000
	ds_read2st64_b32 v[16:17], v199 offset0:0 offset1:1
	ds_read2st64_b32 v[80:81], v200 offset0:0 offset1:1
	ds_read2st64_b32 v[18:19], v199 offset0:2 offset1:3
	ds_read2st64_b32 v[82:83], v200 offset0:2 offset1:3
	ds_read2st64_b32 v[20:21], v199 offset0:4 offset1:5
	ds_read2st64_b32 v[84:85], v200 offset0:4 offset1:5
	ds_read2st64_b32 v[22:23], v199 offset0:6 offset1:7
	ds_read2st64_b32 v[86:87], v200 offset0:6 offset1:7
	ds_read2st64_b32 v[24:25], v199 offset0:8 offset1:9
	ds_read2st64_b32 v[88:89], v200 offset0:8 offset1:9
	ds_read2st64_b32 v[26:27], v199 offset0:10 offset1:11
	ds_read2st64_b32 v[90:91], v200 offset0:10 offset1:11
	ds_read2st64_b32 v[28:29], v199 offset0:12 offset1:13
	ds_read2st64_b32 v[92:93], v200 offset0:12 offset1:13
	ds_read2st64_b32 v[30:31], v199 offset0:14 offset1:15
	ds_read2st64_b32 v[94:95], v200 offset0:14 offset1:15
	s_waitcnt lgkmcnt(0)
	v_lshlrev_b32_e32 v16, 2, v16
	v_lshlrev_b32_e32 v17, 2, v17
	v_lshlrev_b32_e32 v18, 2, v18
	v_lshlrev_b32_e32 v19, 2, v19
	v_lshlrev_b32_e32 v20, 2, v20
	v_lshlrev_b32_e32 v21, 2, v21
	v_lshlrev_b32_e32 v22, 2, v22
	v_lshlrev_b32_e32 v23, 2, v23
	v_lshlrev_b32_e32 v24, 2, v24
	v_lshlrev_b32_e32 v25, 2, v25
	v_lshlrev_b32_e32 v26, 2, v26
	v_lshlrev_b32_e32 v27, 2, v27
	v_lshlrev_b32_e32 v28, 2, v28
	v_lshlrev_b32_e32 v29, 2, v29
	v_lshlrev_b32_e32 v30, 2, v30
	v_lshlrev_b32_e32 v31, 2, v31
	global_load_dword v32, v193, s[6:7]
	global_load_dword v33, v193, s[6:7] offset:256
	global_load_dword v34, v16, s[0:1]
	global_load_dword v35, v17, s[0:1]
	global_load_dword v36, v16, s[4:5]
	global_load_dword v37, v17, s[4:5]
	s_add_u32 s6, s6, s14
	s_addc_u32 s7, s7, 0
	global_load_dword v38, v193, s[6:7]
	global_load_dword v39, v193, s[6:7] offset:256
	global_load_dword v40, v18, s[0:1]
	global_load_dword v41, v19, s[0:1]
	global_load_dword v42, v18, s[4:5]
	global_load_dword v43, v19, s[4:5]
	s_add_u32 s6, s6, s14
	s_addc_u32 s7, s7, 0
	global_load_dword v44, v193, s[6:7]
	global_load_dword v45, v193, s[6:7] offset:256
	global_load_dword v46, v20, s[0:1]
	global_load_dword v47, v21, s[0:1]
	global_load_dword v48, v20, s[4:5]
	global_load_dword v49, v21, s[4:5]
	s_add_u32 s6, s6, s14
	s_addc_u32 s7, s7, 0
	global_load_dword v50, v193, s[6:7]
	global_load_dword v51, v193, s[6:7] offset:256
	global_load_dword v52, v22, s[0:1]
	global_load_dword v53, v23, s[0:1]
	global_load_dword v54, v22, s[4:5]
	global_load_dword v55, v23, s[4:5]
	s_add_u32 s6, s6, s14
	s_addc_u32 s7, s7, 0
	global_load_dword v56, v193, s[6:7]
	global_load_dword v57, v193, s[6:7] offset:256
	global_load_dword v58, v24, s[0:1]
	global_load_dword v59, v25, s[0:1]
	global_load_dword v60, v24, s[4:5]
	global_load_dword v61, v25, s[4:5]
	s_add_u32 s6, s6, s14
	s_addc_u32 s7, s7, 0
	global_load_dword v62, v193, s[6:7]
	global_load_dword v63, v193, s[6:7] offset:256
	global_load_dword v64, v26, s[0:1]
	global_load_dword v65, v27, s[0:1]
	global_load_dword v66, v26, s[4:5]
	global_load_dword v67, v27, s[4:5]
	s_add_u32 s6, s6, s14
	s_addc_u32 s7, s7, 0
	global_load_dword v68, v193, s[6:7]
	global_load_dword v69, v193, s[6:7] offset:256
	global_load_dword v70, v28, s[0:1]
	global_load_dword v71, v29, s[0:1]
	global_load_dword v72, v28, s[4:5]
	global_load_dword v73, v29, s[4:5]
	s_add_u32 s6, s6, s14
	s_addc_u32 s7, s7, 0
	global_load_dword v74, v193, s[6:7]
	global_load_dword v75, v193, s[6:7] offset:256
	global_load_dword v76, v30, s[0:1]
	global_load_dword v77, v31, s[0:1]
	global_load_dword v78, v30, s[4:5]
	global_load_dword v79, v31, s[4:5]
	s_add_u32 s6, s6, s14
	s_addc_u32 s7, s7, 0
	s_waitcnt vmcnt(0)
	v_mul_f32_e32 v80, v34, v80
	v_mul_f32_e32 v180, 0x3f3504f3, v80
	v_fma_f32 v182, |v180|, s12, v177
	v_fma_f32 v182, |v180|, v182, s15
	v_fma_f32 v182, |v180|, v182, s16
	v_fma_f32 v182, |v180|, v182, s17
	v_fma_f32 v182, |v180|, v182, s18
	v_fma_f32 v182, |v180|, v182, s19
	v_fma_f32 v182, |v180|, v182, |v180|
	v_mul_f32_e32 v184, 0xbfb8aa3b, v182
	v_fma_f32 v185, v182, s98, -v184
	v_rndne_f32_e32 v186, v184
	v_fmac_f32_e32 v185, 0xb2a5705f, v182
	v_sub_f32_e32 v184, v184, v186
	v_add_f32_e32 v184, v184, v185
	v_cvt_i32_f32_e32 v185, v186
	v_exp_f32_e32 v184, v184
	v_cmp_nlt_f32_e32 vcc, s38, v182
	v_ldexp_f32 v184, v184, v185
	s_nop 0
	v_cndmask_b32_e32 v184, 0, v184, vcc
	v_cmp_ngt_f32_e32 vcc, s39, v182
	s_nop 1
	v_cndmask_b32_e32 v184, v178, v184, vcc
	v_sub_f32_e32 v184, 1.0, v184
	v_mul_f32_e32 v183, v180, v180
	v_fmamk_f32 v185, v183, 0xba1345e1, v176
	v_fmaak_f32 v185, v183, v185, 0xbcdac9b8
	v_fmaak_f32 v185, v183, v185, 0x3de703be
	v_fmaak_f32 v185, v183, v185, 0xbec09330
	v_fmaak_f32 v183, v183, v185, 0x3e0375d0
	v_fma_f32 v183, |v180|, v183, |v180|
	v_cmp_nlt_f32_e64 vcc, |v180|, 1.0
	s_nop 1
	v_cndmask_b32_e32 v184, v183, v184, vcc
	v_bfi_b32 v184, s10, v184, v180
	v_add_f32_e32 v184, 1.0, v184
	v_mul_f32_e32 v80, 0.5, v80
	v_mul_f32_e32 v32, v32, v36
	v_mul_f32_e32 v80, v80, v184
	v_mul_f32_e32 v80, v32, v80
	v_mul_f32_e32 v81, v35, v81
	v_mul_f32_e32 v180, 0x3f3504f3, v81
	v_fma_f32 v182, |v180|, s12, v177
	v_fma_f32 v182, |v180|, v182, s15
	v_fma_f32 v182, |v180|, v182, s16
	v_fma_f32 v182, |v180|, v182, s17
	v_fma_f32 v182, |v180|, v182, s18
	v_fma_f32 v182, |v180|, v182, s19
	v_fma_f32 v182, |v180|, v182, |v180|
	v_mul_f32_e32 v184, 0xbfb8aa3b, v182
	v_fma_f32 v185, v182, s98, -v184
	v_rndne_f32_e32 v186, v184
	v_fmac_f32_e32 v185, 0xb2a5705f, v182
	v_sub_f32_e32 v184, v184, v186
	v_add_f32_e32 v184, v184, v185
	v_cvt_i32_f32_e32 v185, v186
	v_exp_f32_e32 v184, v184
	v_cmp_nlt_f32_e32 vcc, s38, v182
	v_ldexp_f32 v184, v184, v185
	s_nop 0
	v_cndmask_b32_e32 v184, 0, v184, vcc
	v_cmp_ngt_f32_e32 vcc, s39, v182
	s_nop 1
	v_cndmask_b32_e32 v184, v178, v184, vcc
	v_sub_f32_e32 v184, 1.0, v184
	v_mul_f32_e32 v183, v180, v180
	v_fmamk_f32 v185, v183, 0xba1345e1, v176
	v_fmaak_f32 v185, v183, v185, 0xbcdac9b8
	v_fmaak_f32 v185, v183, v185, 0x3de703be
	v_fmaak_f32 v185, v183, v185, 0xbec09330
	v_fmaak_f32 v183, v183, v185, 0x3e0375d0
	v_fma_f32 v183, |v180|, v183, |v180|
	v_cmp_nlt_f32_e64 vcc, |v180|, 1.0
	s_nop 1
	v_cndmask_b32_e32 v184, v183, v184, vcc
	v_bfi_b32 v184, s10, v184, v180
	v_add_f32_e32 v184, 1.0, v184
	v_mul_f32_e32 v81, 0.5, v81
	v_mul_f32_e32 v33, v33, v37
	v_mul_f32_e32 v81, v81, v184
	v_mul_f32_e32 v81, v33, v81
	global_store_dword v193, v80, s[8:9]
	global_store_dword v193, v81, s[8:9] offset:256
	s_add_u32 s8, s8, s14
	s_addc_u32 s9, s9, 0
	v_mul_f32_e32 v82, v40, v82
	v_mul_f32_e32 v180, 0x3f3504f3, v82
	v_fma_f32 v182, |v180|, s12, v177
	v_fma_f32 v182, |v180|, v182, s15
	v_fma_f32 v182, |v180|, v182, s16
	v_fma_f32 v182, |v180|, v182, s17
	v_fma_f32 v182, |v180|, v182, s18
	v_fma_f32 v182, |v180|, v182, s19
	v_fma_f32 v182, |v180|, v182, |v180|
	v_mul_f32_e32 v184, 0xbfb8aa3b, v182
	v_fma_f32 v185, v182, s98, -v184
	v_rndne_f32_e32 v186, v184
	v_fmac_f32_e32 v185, 0xb2a5705f, v182
	v_sub_f32_e32 v184, v184, v186
	v_add_f32_e32 v184, v184, v185
	v_cvt_i32_f32_e32 v185, v186
	v_exp_f32_e32 v184, v184
	v_cmp_nlt_f32_e32 vcc, s38, v182
	v_ldexp_f32 v184, v184, v185
	s_nop 0
	v_cndmask_b32_e32 v184, 0, v184, vcc
	v_cmp_ngt_f32_e32 vcc, s39, v182
	s_nop 1
	v_cndmask_b32_e32 v184, v178, v184, vcc
	v_sub_f32_e32 v184, 1.0, v184
	v_mul_f32_e32 v183, v180, v180
	v_fmamk_f32 v185, v183, 0xba1345e1, v176
	v_fmaak_f32 v185, v183, v185, 0xbcdac9b8
	v_fmaak_f32 v185, v183, v185, 0x3de703be
	v_fmaak_f32 v185, v183, v185, 0xbec09330
	v_fmaak_f32 v183, v183, v185, 0x3e0375d0
	v_fma_f32 v183, |v180|, v183, |v180|
	v_cmp_nlt_f32_e64 vcc, |v180|, 1.0
	s_nop 1
	v_cndmask_b32_e32 v184, v183, v184, vcc
	v_bfi_b32 v184, s10, v184, v180
	v_add_f32_e32 v184, 1.0, v184
	v_mul_f32_e32 v82, 0.5, v82
	v_mul_f32_e32 v38, v38, v42
	v_mul_f32_e32 v82, v82, v184
	v_mul_f32_e32 v82, v38, v82
	v_mul_f32_e32 v83, v41, v83
	v_mul_f32_e32 v180, 0x3f3504f3, v83
	v_fma_f32 v182, |v180|, s12, v177
	v_fma_f32 v182, |v180|, v182, s15
	v_fma_f32 v182, |v180|, v182, s16
	v_fma_f32 v182, |v180|, v182, s17
	v_fma_f32 v182, |v180|, v182, s18
	v_fma_f32 v182, |v180|, v182, s19
	v_fma_f32 v182, |v180|, v182, |v180|
	v_mul_f32_e32 v184, 0xbfb8aa3b, v182
	v_fma_f32 v185, v182, s98, -v184
	v_rndne_f32_e32 v186, v184
	v_fmac_f32_e32 v185, 0xb2a5705f, v182
	v_sub_f32_e32 v184, v184, v186
	v_add_f32_e32 v184, v184, v185
	v_cvt_i32_f32_e32 v185, v186
	v_exp_f32_e32 v184, v184
	v_cmp_nlt_f32_e32 vcc, s38, v182
	v_ldexp_f32 v184, v184, v185
	s_nop 0
	v_cndmask_b32_e32 v184, 0, v184, vcc
	v_cmp_ngt_f32_e32 vcc, s39, v182
	s_nop 1
	v_cndmask_b32_e32 v184, v178, v184, vcc
	v_sub_f32_e32 v184, 1.0, v184
	v_mul_f32_e32 v183, v180, v180
	v_fmamk_f32 v185, v183, 0xba1345e1, v176
	v_fmaak_f32 v185, v183, v185, 0xbcdac9b8
	v_fmaak_f32 v185, v183, v185, 0x3de703be
	v_fmaak_f32 v185, v183, v185, 0xbec09330
	v_fmaak_f32 v183, v183, v185, 0x3e0375d0
	v_fma_f32 v183, |v180|, v183, |v180|
	v_cmp_nlt_f32_e64 vcc, |v180|, 1.0
	s_nop 1
	v_cndmask_b32_e32 v184, v183, v184, vcc
	v_bfi_b32 v184, s10, v184, v180
	v_add_f32_e32 v184, 1.0, v184
	v_mul_f32_e32 v83, 0.5, v83
	v_mul_f32_e32 v39, v39, v43
	v_mul_f32_e32 v83, v83, v184
	v_mul_f32_e32 v83, v39, v83
	global_store_dword v193, v82, s[8:9]
	global_store_dword v193, v83, s[8:9] offset:256
	s_add_u32 s8, s8, s14
	s_addc_u32 s9, s9, 0
	v_mul_f32_e32 v84, v46, v84
	v_mul_f32_e32 v180, 0x3f3504f3, v84
	v_fma_f32 v182, |v180|, s12, v177
	v_fma_f32 v182, |v180|, v182, s15
	v_fma_f32 v182, |v180|, v182, s16
	v_fma_f32 v182, |v180|, v182, s17
	v_fma_f32 v182, |v180|, v182, s18
	v_fma_f32 v182, |v180|, v182, s19
	v_fma_f32 v182, |v180|, v182, |v180|
	v_mul_f32_e32 v184, 0xbfb8aa3b, v182
	v_fma_f32 v185, v182, s98, -v184
	v_rndne_f32_e32 v186, v184
	v_fmac_f32_e32 v185, 0xb2a5705f, v182
	v_sub_f32_e32 v184, v184, v186
	v_add_f32_e32 v184, v184, v185
	v_cvt_i32_f32_e32 v185, v186
	v_exp_f32_e32 v184, v184
	v_cmp_nlt_f32_e32 vcc, s38, v182
	v_ldexp_f32 v184, v184, v185
	s_nop 0
	v_cndmask_b32_e32 v184, 0, v184, vcc
	v_cmp_ngt_f32_e32 vcc, s39, v182
	s_nop 1
	v_cndmask_b32_e32 v184, v178, v184, vcc
	v_sub_f32_e32 v184, 1.0, v184
	v_mul_f32_e32 v183, v180, v180
	v_fmamk_f32 v185, v183, 0xba1345e1, v176
	v_fmaak_f32 v185, v183, v185, 0xbcdac9b8
	v_fmaak_f32 v185, v183, v185, 0x3de703be
	v_fmaak_f32 v185, v183, v185, 0xbec09330
	v_fmaak_f32 v183, v183, v185, 0x3e0375d0
	v_fma_f32 v183, |v180|, v183, |v180|
	v_cmp_nlt_f32_e64 vcc, |v180|, 1.0
	s_nop 1
	v_cndmask_b32_e32 v184, v183, v184, vcc
	v_bfi_b32 v184, s10, v184, v180
	v_add_f32_e32 v184, 1.0, v184
	v_mul_f32_e32 v84, 0.5, v84
	v_mul_f32_e32 v44, v44, v48
	v_mul_f32_e32 v84, v84, v184
	v_mul_f32_e32 v84, v44, v84
	v_mul_f32_e32 v85, v47, v85
	v_mul_f32_e32 v180, 0x3f3504f3, v85
	v_fma_f32 v182, |v180|, s12, v177
	v_fma_f32 v182, |v180|, v182, s15
	v_fma_f32 v182, |v180|, v182, s16
	v_fma_f32 v182, |v180|, v182, s17
	v_fma_f32 v182, |v180|, v182, s18
	v_fma_f32 v182, |v180|, v182, s19
	v_fma_f32 v182, |v180|, v182, |v180|
	v_mul_f32_e32 v184, 0xbfb8aa3b, v182
	v_fma_f32 v185, v182, s98, -v184
	v_rndne_f32_e32 v186, v184
	v_fmac_f32_e32 v185, 0xb2a5705f, v182
	v_sub_f32_e32 v184, v184, v186
	v_add_f32_e32 v184, v184, v185
	v_cvt_i32_f32_e32 v185, v186
	v_exp_f32_e32 v184, v184
	v_cmp_nlt_f32_e32 vcc, s38, v182
	v_ldexp_f32 v184, v184, v185
	s_nop 0
	v_cndmask_b32_e32 v184, 0, v184, vcc
	v_cmp_ngt_f32_e32 vcc, s39, v182
	s_nop 1
	v_cndmask_b32_e32 v184, v178, v184, vcc
	v_sub_f32_e32 v184, 1.0, v184
	v_mul_f32_e32 v183, v180, v180
	v_fmamk_f32 v185, v183, 0xba1345e1, v176
	v_fmaak_f32 v185, v183, v185, 0xbcdac9b8
	v_fmaak_f32 v185, v183, v185, 0x3de703be
	v_fmaak_f32 v185, v183, v185, 0xbec09330
	v_fmaak_f32 v183, v183, v185, 0x3e0375d0
	v_fma_f32 v183, |v180|, v183, |v180|
	v_cmp_nlt_f32_e64 vcc, |v180|, 1.0
	s_nop 1
	v_cndmask_b32_e32 v184, v183, v184, vcc
	v_bfi_b32 v184, s10, v184, v180
	v_add_f32_e32 v184, 1.0, v184
	v_mul_f32_e32 v85, 0.5, v85
	v_mul_f32_e32 v45, v45, v49
	v_mul_f32_e32 v85, v85, v184
	v_mul_f32_e32 v85, v45, v85
	global_store_dword v193, v84, s[8:9]
	global_store_dword v193, v85, s[8:9] offset:256
	s_add_u32 s8, s8, s14
	s_addc_u32 s9, s9, 0
	v_mul_f32_e32 v86, v52, v86
	v_mul_f32_e32 v180, 0x3f3504f3, v86
	v_fma_f32 v182, |v180|, s12, v177
	v_fma_f32 v182, |v180|, v182, s15
	v_fma_f32 v182, |v180|, v182, s16
	v_fma_f32 v182, |v180|, v182, s17
	v_fma_f32 v182, |v180|, v182, s18
	v_fma_f32 v182, |v180|, v182, s19
	v_fma_f32 v182, |v180|, v182, |v180|
	v_mul_f32_e32 v184, 0xbfb8aa3b, v182
	v_fma_f32 v185, v182, s98, -v184
	v_rndne_f32_e32 v186, v184
	v_fmac_f32_e32 v185, 0xb2a5705f, v182
	v_sub_f32_e32 v184, v184, v186
	v_add_f32_e32 v184, v184, v185
	v_cvt_i32_f32_e32 v185, v186
	v_exp_f32_e32 v184, v184
	v_cmp_nlt_f32_e32 vcc, s38, v182
	v_ldexp_f32 v184, v184, v185
	s_nop 0
	v_cndmask_b32_e32 v184, 0, v184, vcc
	v_cmp_ngt_f32_e32 vcc, s39, v182
	s_nop 1
	v_cndmask_b32_e32 v184, v178, v184, vcc
	v_sub_f32_e32 v184, 1.0, v184
	v_mul_f32_e32 v183, v180, v180
	v_fmamk_f32 v185, v183, 0xba1345e1, v176
	v_fmaak_f32 v185, v183, v185, 0xbcdac9b8
	v_fmaak_f32 v185, v183, v185, 0x3de703be
	v_fmaak_f32 v185, v183, v185, 0xbec09330
	v_fmaak_f32 v183, v183, v185, 0x3e0375d0
	v_fma_f32 v183, |v180|, v183, |v180|
	v_cmp_nlt_f32_e64 vcc, |v180|, 1.0
	s_nop 1
	v_cndmask_b32_e32 v184, v183, v184, vcc
	v_bfi_b32 v184, s10, v184, v180
	v_add_f32_e32 v184, 1.0, v184
	v_mul_f32_e32 v86, 0.5, v86
	v_mul_f32_e32 v50, v50, v54
	v_mul_f32_e32 v86, v86, v184
	v_mul_f32_e32 v86, v50, v86
	v_mul_f32_e32 v87, v53, v87
	v_mul_f32_e32 v180, 0x3f3504f3, v87
	v_fma_f32 v182, |v180|, s12, v177
	v_fma_f32 v182, |v180|, v182, s15
	v_fma_f32 v182, |v180|, v182, s16
	v_fma_f32 v182, |v180|, v182, s17
	v_fma_f32 v182, |v180|, v182, s18
	v_fma_f32 v182, |v180|, v182, s19
	v_fma_f32 v182, |v180|, v182, |v180|
	v_mul_f32_e32 v184, 0xbfb8aa3b, v182
	v_fma_f32 v185, v182, s98, -v184
	v_rndne_f32_e32 v186, v184
	v_fmac_f32_e32 v185, 0xb2a5705f, v182
	v_sub_f32_e32 v184, v184, v186
	v_add_f32_e32 v184, v184, v185
	v_cvt_i32_f32_e32 v185, v186
	v_exp_f32_e32 v184, v184
	v_cmp_nlt_f32_e32 vcc, s38, v182
	v_ldexp_f32 v184, v184, v185
	s_nop 0
	v_cndmask_b32_e32 v184, 0, v184, vcc
	v_cmp_ngt_f32_e32 vcc, s39, v182
	s_nop 1
	v_cndmask_b32_e32 v184, v178, v184, vcc
	v_sub_f32_e32 v184, 1.0, v184
	v_mul_f32_e32 v183, v180, v180
	v_fmamk_f32 v185, v183, 0xba1345e1, v176
	v_fmaak_f32 v185, v183, v185, 0xbcdac9b8
	v_fmaak_f32 v185, v183, v185, 0x3de703be
	v_fmaak_f32 v185, v183, v185, 0xbec09330
	v_fmaak_f32 v183, v183, v185, 0x3e0375d0
	v_fma_f32 v183, |v180|, v183, |v180|
	v_cmp_nlt_f32_e64 vcc, |v180|, 1.0
	s_nop 1
	v_cndmask_b32_e32 v184, v183, v184, vcc
	v_bfi_b32 v184, s10, v184, v180
	v_add_f32_e32 v184, 1.0, v184
	v_mul_f32_e32 v87, 0.5, v87
	v_mul_f32_e32 v51, v51, v55
	v_mul_f32_e32 v87, v87, v184
	v_mul_f32_e32 v87, v51, v87
	global_store_dword v193, v86, s[8:9]
	global_store_dword v193, v87, s[8:9] offset:256
	s_add_u32 s8, s8, s14
	s_addc_u32 s9, s9, 0
	v_mul_f32_e32 v88, v58, v88
	v_mul_f32_e32 v180, 0x3f3504f3, v88
	v_fma_f32 v182, |v180|, s12, v177
	v_fma_f32 v182, |v180|, v182, s15
	v_fma_f32 v182, |v180|, v182, s16
	v_fma_f32 v182, |v180|, v182, s17
	v_fma_f32 v182, |v180|, v182, s18
	v_fma_f32 v182, |v180|, v182, s19
	v_fma_f32 v182, |v180|, v182, |v180|
	v_mul_f32_e32 v184, 0xbfb8aa3b, v182
	v_fma_f32 v185, v182, s98, -v184
	v_rndne_f32_e32 v186, v184
	v_fmac_f32_e32 v185, 0xb2a5705f, v182
	v_sub_f32_e32 v184, v184, v186
	v_add_f32_e32 v184, v184, v185
	v_cvt_i32_f32_e32 v185, v186
	v_exp_f32_e32 v184, v184
	v_cmp_nlt_f32_e32 vcc, s38, v182
	v_ldexp_f32 v184, v184, v185
	s_nop 0
	v_cndmask_b32_e32 v184, 0, v184, vcc
	v_cmp_ngt_f32_e32 vcc, s39, v182
	s_nop 1
	v_cndmask_b32_e32 v184, v178, v184, vcc
	v_sub_f32_e32 v184, 1.0, v184
	v_mul_f32_e32 v183, v180, v180
	v_fmamk_f32 v185, v183, 0xba1345e1, v176
	v_fmaak_f32 v185, v183, v185, 0xbcdac9b8
	v_fmaak_f32 v185, v183, v185, 0x3de703be
	v_fmaak_f32 v185, v183, v185, 0xbec09330
	v_fmaak_f32 v183, v183, v185, 0x3e0375d0
	v_fma_f32 v183, |v180|, v183, |v180|
	v_cmp_nlt_f32_e64 vcc, |v180|, 1.0
	s_nop 1
	v_cndmask_b32_e32 v184, v183, v184, vcc
	v_bfi_b32 v184, s10, v184, v180
	v_add_f32_e32 v184, 1.0, v184
	v_mul_f32_e32 v88, 0.5, v88
	v_mul_f32_e32 v56, v56, v60
	v_mul_f32_e32 v88, v88, v184
	v_mul_f32_e32 v88, v56, v88
	v_mul_f32_e32 v89, v59, v89
	v_mul_f32_e32 v180, 0x3f3504f3, v89
	v_fma_f32 v182, |v180|, s12, v177
	v_fma_f32 v182, |v180|, v182, s15
	v_fma_f32 v182, |v180|, v182, s16
	v_fma_f32 v182, |v180|, v182, s17
	v_fma_f32 v182, |v180|, v182, s18
	v_fma_f32 v182, |v180|, v182, s19
	v_fma_f32 v182, |v180|, v182, |v180|
	v_mul_f32_e32 v184, 0xbfb8aa3b, v182
	v_fma_f32 v185, v182, s98, -v184
	v_rndne_f32_e32 v186, v184
	v_fmac_f32_e32 v185, 0xb2a5705f, v182
	v_sub_f32_e32 v184, v184, v186
	v_add_f32_e32 v184, v184, v185
	v_cvt_i32_f32_e32 v185, v186
	v_exp_f32_e32 v184, v184
	v_cmp_nlt_f32_e32 vcc, s38, v182
	v_ldexp_f32 v184, v184, v185
	s_nop 0
	v_cndmask_b32_e32 v184, 0, v184, vcc
	v_cmp_ngt_f32_e32 vcc, s39, v182
	s_nop 1
	v_cndmask_b32_e32 v184, v178, v184, vcc
	v_sub_f32_e32 v184, 1.0, v184
	v_mul_f32_e32 v183, v180, v180
	v_fmamk_f32 v185, v183, 0xba1345e1, v176
	v_fmaak_f32 v185, v183, v185, 0xbcdac9b8
	v_fmaak_f32 v185, v183, v185, 0x3de703be
	v_fmaak_f32 v185, v183, v185, 0xbec09330
	v_fmaak_f32 v183, v183, v185, 0x3e0375d0
	v_fma_f32 v183, |v180|, v183, |v180|
	v_cmp_nlt_f32_e64 vcc, |v180|, 1.0
	s_nop 1
	v_cndmask_b32_e32 v184, v183, v184, vcc
	v_bfi_b32 v184, s10, v184, v180
	v_add_f32_e32 v184, 1.0, v184
	v_mul_f32_e32 v89, 0.5, v89
	v_mul_f32_e32 v57, v57, v61
	v_mul_f32_e32 v89, v89, v184
	v_mul_f32_e32 v89, v57, v89
	global_store_dword v193, v88, s[8:9]
	global_store_dword v193, v89, s[8:9] offset:256
	s_add_u32 s8, s8, s14
	s_addc_u32 s9, s9, 0
	v_mul_f32_e32 v90, v64, v90
	v_mul_f32_e32 v180, 0x3f3504f3, v90
	v_fma_f32 v182, |v180|, s12, v177
	v_fma_f32 v182, |v180|, v182, s15
	v_fma_f32 v182, |v180|, v182, s16
	v_fma_f32 v182, |v180|, v182, s17
	v_fma_f32 v182, |v180|, v182, s18
	v_fma_f32 v182, |v180|, v182, s19
	v_fma_f32 v182, |v180|, v182, |v180|
	v_mul_f32_e32 v184, 0xbfb8aa3b, v182
	v_fma_f32 v185, v182, s98, -v184
	v_rndne_f32_e32 v186, v184
	v_fmac_f32_e32 v185, 0xb2a5705f, v182
	v_sub_f32_e32 v184, v184, v186
	v_add_f32_e32 v184, v184, v185
	v_cvt_i32_f32_e32 v185, v186
	v_exp_f32_e32 v184, v184
	v_cmp_nlt_f32_e32 vcc, s38, v182
	v_ldexp_f32 v184, v184, v185
	s_nop 0
	v_cndmask_b32_e32 v184, 0, v184, vcc
	v_cmp_ngt_f32_e32 vcc, s39, v182
	s_nop 1
	v_cndmask_b32_e32 v184, v178, v184, vcc
	v_sub_f32_e32 v184, 1.0, v184
	v_mul_f32_e32 v183, v180, v180
	v_fmamk_f32 v185, v183, 0xba1345e1, v176
	v_fmaak_f32 v185, v183, v185, 0xbcdac9b8
	v_fmaak_f32 v185, v183, v185, 0x3de703be
	v_fmaak_f32 v185, v183, v185, 0xbec09330
	v_fmaak_f32 v183, v183, v185, 0x3e0375d0
	v_fma_f32 v183, |v180|, v183, |v180|
	v_cmp_nlt_f32_e64 vcc, |v180|, 1.0
	s_nop 1
	v_cndmask_b32_e32 v184, v183, v184, vcc
	v_bfi_b32 v184, s10, v184, v180
	v_add_f32_e32 v184, 1.0, v184
	v_mul_f32_e32 v90, 0.5, v90
	v_mul_f32_e32 v62, v62, v66
	v_mul_f32_e32 v90, v90, v184
	v_mul_f32_e32 v90, v62, v90
	v_mul_f32_e32 v91, v65, v91
	v_mul_f32_e32 v180, 0x3f3504f3, v91
	v_fma_f32 v182, |v180|, s12, v177
	v_fma_f32 v182, |v180|, v182, s15
	v_fma_f32 v182, |v180|, v182, s16
	v_fma_f32 v182, |v180|, v182, s17
	v_fma_f32 v182, |v180|, v182, s18
	v_fma_f32 v182, |v180|, v182, s19
	v_fma_f32 v182, |v180|, v182, |v180|
	v_mul_f32_e32 v184, 0xbfb8aa3b, v182
	v_fma_f32 v185, v182, s98, -v184
	v_rndne_f32_e32 v186, v184
	v_fmac_f32_e32 v185, 0xb2a5705f, v182
	v_sub_f32_e32 v184, v184, v186
	v_add_f32_e32 v184, v184, v185
	v_cvt_i32_f32_e32 v185, v186
	v_exp_f32_e32 v184, v184
	v_cmp_nlt_f32_e32 vcc, s38, v182
	v_ldexp_f32 v184, v184, v185
	s_nop 0
	v_cndmask_b32_e32 v184, 0, v184, vcc
	v_cmp_ngt_f32_e32 vcc, s39, v182
	s_nop 1
	v_cndmask_b32_e32 v184, v178, v184, vcc
	v_sub_f32_e32 v184, 1.0, v184
	v_mul_f32_e32 v183, v180, v180
	v_fmamk_f32 v185, v183, 0xba1345e1, v176
	v_fmaak_f32 v185, v183, v185, 0xbcdac9b8
	v_fmaak_f32 v185, v183, v185, 0x3de703be
	v_fmaak_f32 v185, v183, v185, 0xbec09330
	v_fmaak_f32 v183, v183, v185, 0x3e0375d0
	v_fma_f32 v183, |v180|, v183, |v180|
	v_cmp_nlt_f32_e64 vcc, |v180|, 1.0
	s_nop 1
	v_cndmask_b32_e32 v184, v183, v184, vcc
	v_bfi_b32 v184, s10, v184, v180
	v_add_f32_e32 v184, 1.0, v184
	v_mul_f32_e32 v91, 0.5, v91
	v_mul_f32_e32 v63, v63, v67
	v_mul_f32_e32 v91, v91, v184
	v_mul_f32_e32 v91, v63, v91
	global_store_dword v193, v90, s[8:9]
	global_store_dword v193, v91, s[8:9] offset:256
	s_add_u32 s8, s8, s14
	s_addc_u32 s9, s9, 0
	v_mul_f32_e32 v92, v70, v92
	v_mul_f32_e32 v180, 0x3f3504f3, v92
	v_fma_f32 v182, |v180|, s12, v177
	v_fma_f32 v182, |v180|, v182, s15
	v_fma_f32 v182, |v180|, v182, s16
	v_fma_f32 v182, |v180|, v182, s17
	v_fma_f32 v182, |v180|, v182, s18
	v_fma_f32 v182, |v180|, v182, s19
	v_fma_f32 v182, |v180|, v182, |v180|
	v_mul_f32_e32 v184, 0xbfb8aa3b, v182
	v_fma_f32 v185, v182, s98, -v184
	v_rndne_f32_e32 v186, v184
	v_fmac_f32_e32 v185, 0xb2a5705f, v182
	v_sub_f32_e32 v184, v184, v186
	v_add_f32_e32 v184, v184, v185
	v_cvt_i32_f32_e32 v185, v186
	v_exp_f32_e32 v184, v184
	v_cmp_nlt_f32_e32 vcc, s38, v182
	v_ldexp_f32 v184, v184, v185
	s_nop 0
	v_cndmask_b32_e32 v184, 0, v184, vcc
	v_cmp_ngt_f32_e32 vcc, s39, v182
	s_nop 1
	v_cndmask_b32_e32 v184, v178, v184, vcc
	v_sub_f32_e32 v184, 1.0, v184
	v_mul_f32_e32 v183, v180, v180
	v_fmamk_f32 v185, v183, 0xba1345e1, v176
	v_fmaak_f32 v185, v183, v185, 0xbcdac9b8
	v_fmaak_f32 v185, v183, v185, 0x3de703be
	v_fmaak_f32 v185, v183, v185, 0xbec09330
	v_fmaak_f32 v183, v183, v185, 0x3e0375d0
	v_fma_f32 v183, |v180|, v183, |v180|
	v_cmp_nlt_f32_e64 vcc, |v180|, 1.0
	s_nop 1
	v_cndmask_b32_e32 v184, v183, v184, vcc
	v_bfi_b32 v184, s10, v184, v180
	v_add_f32_e32 v184, 1.0, v184
	v_mul_f32_e32 v92, 0.5, v92
	v_mul_f32_e32 v68, v68, v72
	v_mul_f32_e32 v92, v92, v184
	v_mul_f32_e32 v92, v68, v92
	v_mul_f32_e32 v93, v71, v93
	v_mul_f32_e32 v180, 0x3f3504f3, v93
	v_fma_f32 v182, |v180|, s12, v177
	v_fma_f32 v182, |v180|, v182, s15
	v_fma_f32 v182, |v180|, v182, s16
	v_fma_f32 v182, |v180|, v182, s17
	v_fma_f32 v182, |v180|, v182, s18
	v_fma_f32 v182, |v180|, v182, s19
	v_fma_f32 v182, |v180|, v182, |v180|
	v_mul_f32_e32 v184, 0xbfb8aa3b, v182
	v_fma_f32 v185, v182, s98, -v184
	v_rndne_f32_e32 v186, v184
	v_fmac_f32_e32 v185, 0xb2a5705f, v182
	v_sub_f32_e32 v184, v184, v186
	v_add_f32_e32 v184, v184, v185
	v_cvt_i32_f32_e32 v185, v186
	v_exp_f32_e32 v184, v184
	v_cmp_nlt_f32_e32 vcc, s38, v182
	v_ldexp_f32 v184, v184, v185
	s_nop 0
	v_cndmask_b32_e32 v184, 0, v184, vcc
	v_cmp_ngt_f32_e32 vcc, s39, v182
	s_nop 1
	v_cndmask_b32_e32 v184, v178, v184, vcc
	v_sub_f32_e32 v184, 1.0, v184
	v_mul_f32_e32 v183, v180, v180
	v_fmamk_f32 v185, v183, 0xba1345e1, v176
	v_fmaak_f32 v185, v183, v185, 0xbcdac9b8
	v_fmaak_f32 v185, v183, v185, 0x3de703be
	v_fmaak_f32 v185, v183, v185, 0xbec09330
	v_fmaak_f32 v183, v183, v185, 0x3e0375d0
	v_fma_f32 v183, |v180|, v183, |v180|
	v_cmp_nlt_f32_e64 vcc, |v180|, 1.0
	s_nop 1
	v_cndmask_b32_e32 v184, v183, v184, vcc
	v_bfi_b32 v184, s10, v184, v180
	v_add_f32_e32 v184, 1.0, v184
	v_mul_f32_e32 v93, 0.5, v93
	v_mul_f32_e32 v69, v69, v73
	v_mul_f32_e32 v93, v93, v184
	v_mul_f32_e32 v93, v69, v93
	global_store_dword v193, v92, s[8:9]
	global_store_dword v193, v93, s[8:9] offset:256
	s_add_u32 s8, s8, s14
	s_addc_u32 s9, s9, 0
	v_mul_f32_e32 v94, v76, v94
	v_mul_f32_e32 v180, 0x3f3504f3, v94
	v_fma_f32 v182, |v180|, s12, v177
	v_fma_f32 v182, |v180|, v182, s15
	v_fma_f32 v182, |v180|, v182, s16
	v_fma_f32 v182, |v180|, v182, s17
	v_fma_f32 v182, |v180|, v182, s18
	v_fma_f32 v182, |v180|, v182, s19
	v_fma_f32 v182, |v180|, v182, |v180|
	v_mul_f32_e32 v184, 0xbfb8aa3b, v182
	v_fma_f32 v185, v182, s98, -v184
	v_rndne_f32_e32 v186, v184
	v_fmac_f32_e32 v185, 0xb2a5705f, v182
	v_sub_f32_e32 v184, v184, v186
	v_add_f32_e32 v184, v184, v185
	v_cvt_i32_f32_e32 v185, v186
	v_exp_f32_e32 v184, v184
	v_cmp_nlt_f32_e32 vcc, s38, v182
	v_ldexp_f32 v184, v184, v185
	s_nop 0
	v_cndmask_b32_e32 v184, 0, v184, vcc
	v_cmp_ngt_f32_e32 vcc, s39, v182
	s_nop 1
	v_cndmask_b32_e32 v184, v178, v184, vcc
	v_sub_f32_e32 v184, 1.0, v184
	v_mul_f32_e32 v183, v180, v180
	v_fmamk_f32 v185, v183, 0xba1345e1, v176
	v_fmaak_f32 v185, v183, v185, 0xbcdac9b8
	v_fmaak_f32 v185, v183, v185, 0x3de703be
	v_fmaak_f32 v185, v183, v185, 0xbec09330
	v_fmaak_f32 v183, v183, v185, 0x3e0375d0
	v_fma_f32 v183, |v180|, v183, |v180|
	v_cmp_nlt_f32_e64 vcc, |v180|, 1.0
	s_nop 1
	v_cndmask_b32_e32 v184, v183, v184, vcc
	v_bfi_b32 v184, s10, v184, v180
	v_add_f32_e32 v184, 1.0, v184
	v_mul_f32_e32 v94, 0.5, v94
	v_mul_f32_e32 v74, v74, v78
	v_mul_f32_e32 v94, v94, v184
	v_mul_f32_e32 v94, v74, v94
	v_mul_f32_e32 v95, v77, v95
	v_mul_f32_e32 v180, 0x3f3504f3, v95
	v_fma_f32 v182, |v180|, s12, v177
	v_fma_f32 v182, |v180|, v182, s15
	v_fma_f32 v182, |v180|, v182, s16
	v_fma_f32 v182, |v180|, v182, s17
	v_fma_f32 v182, |v180|, v182, s18
	v_fma_f32 v182, |v180|, v182, s19
	v_fma_f32 v182, |v180|, v182, |v180|
	v_mul_f32_e32 v184, 0xbfb8aa3b, v182
	v_fma_f32 v185, v182, s98, -v184
	v_rndne_f32_e32 v186, v184
	v_fmac_f32_e32 v185, 0xb2a5705f, v182
	v_sub_f32_e32 v184, v184, v186
	v_add_f32_e32 v184, v184, v185
	v_cvt_i32_f32_e32 v185, v186
	v_exp_f32_e32 v184, v184
	v_cmp_nlt_f32_e32 vcc, s38, v182
	v_ldexp_f32 v184, v184, v185
	s_nop 0
	v_cndmask_b32_e32 v184, 0, v184, vcc
	v_cmp_ngt_f32_e32 vcc, s39, v182
	s_nop 1
	v_cndmask_b32_e32 v184, v178, v184, vcc
	v_sub_f32_e32 v184, 1.0, v184
	v_mul_f32_e32 v183, v180, v180
	v_fmamk_f32 v185, v183, 0xba1345e1, v176
	v_fmaak_f32 v185, v183, v185, 0xbcdac9b8
	v_fmaak_f32 v185, v183, v185, 0x3de703be
	v_fmaak_f32 v185, v183, v185, 0xbec09330
	v_fmaak_f32 v183, v183, v185, 0x3e0375d0
	v_fma_f32 v183, |v180|, v183, |v180|
	v_cmp_nlt_f32_e64 vcc, |v180|, 1.0
	s_nop 1
	v_cndmask_b32_e32 v184, v183, v184, vcc
	v_bfi_b32 v184, s10, v184, v180
	v_add_f32_e32 v184, 1.0, v184
	v_mul_f32_e32 v95, 0.5, v95
	v_mul_f32_e32 v75, v75, v79
	v_mul_f32_e32 v95, v95, v184
	v_mul_f32_e32 v95, v75, v95
	global_store_dword v193, v94, s[8:9]
	global_store_dword v193, v95, s[8:9] offset:256
	s_add_u32 s8, s8, s14
	s_addc_u32 s9, s9, 0
	ds_read2st64_b32 v[16:17], v199 offset0:16 offset1:17
	ds_read2st64_b32 v[80:81], v200 offset0:16 offset1:17
	ds_read2st64_b32 v[18:19], v199 offset0:18 offset1:19
	ds_read2st64_b32 v[82:83], v200 offset0:18 offset1:19
	ds_read2st64_b32 v[20:21], v199 offset0:20 offset1:21
	ds_read2st64_b32 v[84:85], v200 offset0:20 offset1:21
	ds_read2st64_b32 v[22:23], v199 offset0:22 offset1:23
	ds_read2st64_b32 v[86:87], v200 offset0:22 offset1:23
	ds_read2st64_b32 v[24:25], v199 offset0:24 offset1:25
	ds_read2st64_b32 v[88:89], v200 offset0:24 offset1:25
	ds_read2st64_b32 v[26:27], v199 offset0:26 offset1:27
	ds_read2st64_b32 v[90:91], v200 offset0:26 offset1:27
	ds_read2st64_b32 v[28:29], v199 offset0:28 offset1:29
	ds_read2st64_b32 v[92:93], v200 offset0:28 offset1:29
	ds_read2st64_b32 v[30:31], v199 offset0:30 offset1:31
	ds_read2st64_b32 v[94:95], v200 offset0:30 offset1:31
	s_waitcnt lgkmcnt(0)
	v_lshlrev_b32_e32 v16, 2, v16
	v_lshlrev_b32_e32 v17, 2, v17
	v_lshlrev_b32_e32 v18, 2, v18
	v_lshlrev_b32_e32 v19, 2, v19
	v_lshlrev_b32_e32 v20, 2, v20
	v_lshlrev_b32_e32 v21, 2, v21
	v_lshlrev_b32_e32 v22, 2, v22
	v_lshlrev_b32_e32 v23, 2, v23
	v_lshlrev_b32_e32 v24, 2, v24
	v_lshlrev_b32_e32 v25, 2, v25
	v_lshlrev_b32_e32 v26, 2, v26
	v_lshlrev_b32_e32 v27, 2, v27
	v_lshlrev_b32_e32 v28, 2, v28
	v_lshlrev_b32_e32 v29, 2, v29
	v_lshlrev_b32_e32 v30, 2, v30
	v_lshlrev_b32_e32 v31, 2, v31
	global_load_dword v32, v193, s[6:7]
	global_load_dword v33, v193, s[6:7] offset:256
	global_load_dword v34, v16, s[0:1]
	global_load_dword v35, v17, s[0:1]
	global_load_dword v36, v16, s[4:5]
	global_load_dword v37, v17, s[4:5]
	s_add_u32 s6, s6, s14
	s_addc_u32 s7, s7, 0
	global_load_dword v38, v193, s[6:7]
	global_load_dword v39, v193, s[6:7] offset:256
	global_load_dword v40, v18, s[0:1]
	global_load_dword v41, v19, s[0:1]
	global_load_dword v42, v18, s[4:5]
	global_load_dword v43, v19, s[4:5]
	s_add_u32 s6, s6, s14
	s_addc_u32 s7, s7, 0
	global_load_dword v44, v193, s[6:7]
	global_load_dword v45, v193, s[6:7] offset:256
	global_load_dword v46, v20, s[0:1]
	global_load_dword v47, v21, s[0:1]
	global_load_dword v48, v20, s[4:5]
	global_load_dword v49, v21, s[4:5]
	s_add_u32 s6, s6, s14
	s_addc_u32 s7, s7, 0
	global_load_dword v50, v193, s[6:7]
	global_load_dword v51, v193, s[6:7] offset:256
	global_load_dword v52, v22, s[0:1]
	global_load_dword v53, v23, s[0:1]
	global_load_dword v54, v22, s[4:5]
	global_load_dword v55, v23, s[4:5]
	s_add_u32 s6, s6, s14
	s_addc_u32 s7, s7, 0
	global_load_dword v56, v193, s[6:7]
	global_load_dword v57, v193, s[6:7] offset:256
	global_load_dword v58, v24, s[0:1]
	global_load_dword v59, v25, s[0:1]
	global_load_dword v60, v24, s[4:5]
	global_load_dword v61, v25, s[4:5]
	s_add_u32 s6, s6, s14
	s_addc_u32 s7, s7, 0
	global_load_dword v62, v193, s[6:7]
	global_load_dword v63, v193, s[6:7] offset:256
	global_load_dword v64, v26, s[0:1]
	global_load_dword v65, v27, s[0:1]
	global_load_dword v66, v26, s[4:5]
	global_load_dword v67, v27, s[4:5]
	s_add_u32 s6, s6, s14
	s_addc_u32 s7, s7, 0
	global_load_dword v68, v193, s[6:7]
	global_load_dword v69, v193, s[6:7] offset:256
	global_load_dword v70, v28, s[0:1]
	global_load_dword v71, v29, s[0:1]
	global_load_dword v72, v28, s[4:5]
	global_load_dword v73, v29, s[4:5]
	s_add_u32 s6, s6, s14
	s_addc_u32 s7, s7, 0
	global_load_dword v74, v193, s[6:7]
	global_load_dword v75, v193, s[6:7] offset:256
	global_load_dword v76, v30, s[0:1]
	global_load_dword v77, v31, s[0:1]
	global_load_dword v78, v30, s[4:5]
	global_load_dword v79, v31, s[4:5]
	s_add_u32 s6, s6, s14
	s_addc_u32 s7, s7, 0
	s_waitcnt vmcnt(0)
	v_mul_f32_e32 v80, v34, v80
	v_mul_f32_e32 v180, 0x3f3504f3, v80
	v_fma_f32 v182, |v180|, s12, v177
	v_fma_f32 v182, |v180|, v182, s15
	v_fma_f32 v182, |v180|, v182, s16
	v_fma_f32 v182, |v180|, v182, s17
	v_fma_f32 v182, |v180|, v182, s18
	v_fma_f32 v182, |v180|, v182, s19
	v_fma_f32 v182, |v180|, v182, |v180|
	v_mul_f32_e32 v184, 0xbfb8aa3b, v182
	v_fma_f32 v185, v182, s98, -v184
	v_rndne_f32_e32 v186, v184
	v_fmac_f32_e32 v185, 0xb2a5705f, v182
	v_sub_f32_e32 v184, v184, v186
	v_add_f32_e32 v184, v184, v185
	v_cvt_i32_f32_e32 v185, v186
	v_exp_f32_e32 v184, v184
	v_cmp_nlt_f32_e32 vcc, s38, v182
	v_ldexp_f32 v184, v184, v185
	s_nop 0
	v_cndmask_b32_e32 v184, 0, v184, vcc
	v_cmp_ngt_f32_e32 vcc, s39, v182
	s_nop 1
	v_cndmask_b32_e32 v184, v178, v184, vcc
	v_sub_f32_e32 v184, 1.0, v184
	v_mul_f32_e32 v183, v180, v180
	v_fmamk_f32 v185, v183, 0xba1345e1, v176
	v_fmaak_f32 v185, v183, v185, 0xbcdac9b8
	v_fmaak_f32 v185, v183, v185, 0x3de703be
	v_fmaak_f32 v185, v183, v185, 0xbec09330
	v_fmaak_f32 v183, v183, v185, 0x3e0375d0
	v_fma_f32 v183, |v180|, v183, |v180|
	v_cmp_nlt_f32_e64 vcc, |v180|, 1.0
	s_nop 1
	v_cndmask_b32_e32 v184, v183, v184, vcc
	v_bfi_b32 v184, s10, v184, v180
	v_add_f32_e32 v184, 1.0, v184
	v_mul_f32_e32 v80, 0.5, v80
	v_mul_f32_e32 v32, v32, v36
	v_mul_f32_e32 v80, v80, v184
	v_mul_f32_e32 v80, v32, v80
	v_mul_f32_e32 v81, v35, v81
	v_mul_f32_e32 v180, 0x3f3504f3, v81
	v_fma_f32 v182, |v180|, s12, v177
	v_fma_f32 v182, |v180|, v182, s15
	v_fma_f32 v182, |v180|, v182, s16
	v_fma_f32 v182, |v180|, v182, s17
	v_fma_f32 v182, |v180|, v182, s18
	v_fma_f32 v182, |v180|, v182, s19
	v_fma_f32 v182, |v180|, v182, |v180|
	v_mul_f32_e32 v184, 0xbfb8aa3b, v182
	v_fma_f32 v185, v182, s98, -v184
	v_rndne_f32_e32 v186, v184
	v_fmac_f32_e32 v185, 0xb2a5705f, v182
	v_sub_f32_e32 v184, v184, v186
	v_add_f32_e32 v184, v184, v185
	v_cvt_i32_f32_e32 v185, v186
	v_exp_f32_e32 v184, v184
	v_cmp_nlt_f32_e32 vcc, s38, v182
	v_ldexp_f32 v184, v184, v185
	s_nop 0
	v_cndmask_b32_e32 v184, 0, v184, vcc
	v_cmp_ngt_f32_e32 vcc, s39, v182
	s_nop 1
	v_cndmask_b32_e32 v184, v178, v184, vcc
	v_sub_f32_e32 v184, 1.0, v184
	v_mul_f32_e32 v183, v180, v180
	v_fmamk_f32 v185, v183, 0xba1345e1, v176
	v_fmaak_f32 v185, v183, v185, 0xbcdac9b8
	v_fmaak_f32 v185, v183, v185, 0x3de703be
	v_fmaak_f32 v185, v183, v185, 0xbec09330
	v_fmaak_f32 v183, v183, v185, 0x3e0375d0
	v_fma_f32 v183, |v180|, v183, |v180|
	v_cmp_nlt_f32_e64 vcc, |v180|, 1.0
	s_nop 1
	v_cndmask_b32_e32 v184, v183, v184, vcc
	v_bfi_b32 v184, s10, v184, v180
	v_add_f32_e32 v184, 1.0, v184
	v_mul_f32_e32 v81, 0.5, v81
	v_mul_f32_e32 v33, v33, v37
	v_mul_f32_e32 v81, v81, v184
	v_mul_f32_e32 v81, v33, v81
	global_store_dword v193, v80, s[8:9]
	global_store_dword v193, v81, s[8:9] offset:256
	s_add_u32 s8, s8, s14
	s_addc_u32 s9, s9, 0
	v_mul_f32_e32 v82, v40, v82
	v_mul_f32_e32 v180, 0x3f3504f3, v82
	v_fma_f32 v182, |v180|, s12, v177
	v_fma_f32 v182, |v180|, v182, s15
	v_fma_f32 v182, |v180|, v182, s16
	v_fma_f32 v182, |v180|, v182, s17
	v_fma_f32 v182, |v180|, v182, s18
	v_fma_f32 v182, |v180|, v182, s19
	v_fma_f32 v182, |v180|, v182, |v180|
	v_mul_f32_e32 v184, 0xbfb8aa3b, v182
	v_fma_f32 v185, v182, s98, -v184
	v_rndne_f32_e32 v186, v184
	v_fmac_f32_e32 v185, 0xb2a5705f, v182
	v_sub_f32_e32 v184, v184, v186
	v_add_f32_e32 v184, v184, v185
	v_cvt_i32_f32_e32 v185, v186
	v_exp_f32_e32 v184, v184
	v_cmp_nlt_f32_e32 vcc, s38, v182
	v_ldexp_f32 v184, v184, v185
	s_nop 0
	v_cndmask_b32_e32 v184, 0, v184, vcc
	v_cmp_ngt_f32_e32 vcc, s39, v182
	s_nop 1
	v_cndmask_b32_e32 v184, v178, v184, vcc
	v_sub_f32_e32 v184, 1.0, v184
	v_mul_f32_e32 v183, v180, v180
	v_fmamk_f32 v185, v183, 0xba1345e1, v176
	v_fmaak_f32 v185, v183, v185, 0xbcdac9b8
	v_fmaak_f32 v185, v183, v185, 0x3de703be
	v_fmaak_f32 v185, v183, v185, 0xbec09330
	v_fmaak_f32 v183, v183, v185, 0x3e0375d0
	v_fma_f32 v183, |v180|, v183, |v180|
	v_cmp_nlt_f32_e64 vcc, |v180|, 1.0
	s_nop 1
	v_cndmask_b32_e32 v184, v183, v184, vcc
	v_bfi_b32 v184, s10, v184, v180
	v_add_f32_e32 v184, 1.0, v184
	v_mul_f32_e32 v82, 0.5, v82
	v_mul_f32_e32 v38, v38, v42
	v_mul_f32_e32 v82, v82, v184
	v_mul_f32_e32 v82, v38, v82
	v_mul_f32_e32 v83, v41, v83
	v_mul_f32_e32 v180, 0x3f3504f3, v83
	v_fma_f32 v182, |v180|, s12, v177
	v_fma_f32 v182, |v180|, v182, s15
	v_fma_f32 v182, |v180|, v182, s16
	v_fma_f32 v182, |v180|, v182, s17
	v_fma_f32 v182, |v180|, v182, s18
	v_fma_f32 v182, |v180|, v182, s19
	v_fma_f32 v182, |v180|, v182, |v180|
	v_mul_f32_e32 v184, 0xbfb8aa3b, v182
	v_fma_f32 v185, v182, s98, -v184
	v_rndne_f32_e32 v186, v184
	v_fmac_f32_e32 v185, 0xb2a5705f, v182
	v_sub_f32_e32 v184, v184, v186
	v_add_f32_e32 v184, v184, v185
	v_cvt_i32_f32_e32 v185, v186
	v_exp_f32_e32 v184, v184
	v_cmp_nlt_f32_e32 vcc, s38, v182
	v_ldexp_f32 v184, v184, v185
	s_nop 0
	v_cndmask_b32_e32 v184, 0, v184, vcc
	v_cmp_ngt_f32_e32 vcc, s39, v182
	s_nop 1
	v_cndmask_b32_e32 v184, v178, v184, vcc
	v_sub_f32_e32 v184, 1.0, v184
	v_mul_f32_e32 v183, v180, v180
	v_fmamk_f32 v185, v183, 0xba1345e1, v176
	v_fmaak_f32 v185, v183, v185, 0xbcdac9b8
	v_fmaak_f32 v185, v183, v185, 0x3de703be
	v_fmaak_f32 v185, v183, v185, 0xbec09330
	v_fmaak_f32 v183, v183, v185, 0x3e0375d0
	v_fma_f32 v183, |v180|, v183, |v180|
	v_cmp_nlt_f32_e64 vcc, |v180|, 1.0
	s_nop 1
	v_cndmask_b32_e32 v184, v183, v184, vcc
	v_bfi_b32 v184, s10, v184, v180
	v_add_f32_e32 v184, 1.0, v184
	v_mul_f32_e32 v83, 0.5, v83
	v_mul_f32_e32 v39, v39, v43
	v_mul_f32_e32 v83, v83, v184
	v_mul_f32_e32 v83, v39, v83
	global_store_dword v193, v82, s[8:9]
	global_store_dword v193, v83, s[8:9] offset:256
	s_add_u32 s8, s8, s14
	s_addc_u32 s9, s9, 0
	v_mul_f32_e32 v84, v46, v84
	v_mul_f32_e32 v180, 0x3f3504f3, v84
	v_fma_f32 v182, |v180|, s12, v177
	v_fma_f32 v182, |v180|, v182, s15
	v_fma_f32 v182, |v180|, v182, s16
	v_fma_f32 v182, |v180|, v182, s17
	v_fma_f32 v182, |v180|, v182, s18
	v_fma_f32 v182, |v180|, v182, s19
	v_fma_f32 v182, |v180|, v182, |v180|
	v_mul_f32_e32 v184, 0xbfb8aa3b, v182
	v_fma_f32 v185, v182, s98, -v184
	v_rndne_f32_e32 v186, v184
	v_fmac_f32_e32 v185, 0xb2a5705f, v182
	v_sub_f32_e32 v184, v184, v186
	v_add_f32_e32 v184, v184, v185
	v_cvt_i32_f32_e32 v185, v186
	v_exp_f32_e32 v184, v184
	v_cmp_nlt_f32_e32 vcc, s38, v182
	v_ldexp_f32 v184, v184, v185
	s_nop 0
	v_cndmask_b32_e32 v184, 0, v184, vcc
	v_cmp_ngt_f32_e32 vcc, s39, v182
	s_nop 1
	v_cndmask_b32_e32 v184, v178, v184, vcc
	v_sub_f32_e32 v184, 1.0, v184
	v_mul_f32_e32 v183, v180, v180
	v_fmamk_f32 v185, v183, 0xba1345e1, v176
	v_fmaak_f32 v185, v183, v185, 0xbcdac9b8
	v_fmaak_f32 v185, v183, v185, 0x3de703be
	v_fmaak_f32 v185, v183, v185, 0xbec09330
	v_fmaak_f32 v183, v183, v185, 0x3e0375d0
	v_fma_f32 v183, |v180|, v183, |v180|
	v_cmp_nlt_f32_e64 vcc, |v180|, 1.0
	s_nop 1
	v_cndmask_b32_e32 v184, v183, v184, vcc
	v_bfi_b32 v184, s10, v184, v180
	v_add_f32_e32 v184, 1.0, v184
	v_mul_f32_e32 v84, 0.5, v84
	v_mul_f32_e32 v44, v44, v48
	v_mul_f32_e32 v84, v84, v184
	v_mul_f32_e32 v84, v44, v84
	v_mul_f32_e32 v85, v47, v85
	v_mul_f32_e32 v180, 0x3f3504f3, v85
	v_fma_f32 v182, |v180|, s12, v177
	v_fma_f32 v182, |v180|, v182, s15
	v_fma_f32 v182, |v180|, v182, s16
	v_fma_f32 v182, |v180|, v182, s17
	v_fma_f32 v182, |v180|, v182, s18
	v_fma_f32 v182, |v180|, v182, s19
	v_fma_f32 v182, |v180|, v182, |v180|
	v_mul_f32_e32 v184, 0xbfb8aa3b, v182
	v_fma_f32 v185, v182, s98, -v184
	v_rndne_f32_e32 v186, v184
	v_fmac_f32_e32 v185, 0xb2a5705f, v182
	v_sub_f32_e32 v184, v184, v186
	v_add_f32_e32 v184, v184, v185
	v_cvt_i32_f32_e32 v185, v186
	v_exp_f32_e32 v184, v184
	v_cmp_nlt_f32_e32 vcc, s38, v182
	v_ldexp_f32 v184, v184, v185
	s_nop 0
	v_cndmask_b32_e32 v184, 0, v184, vcc
	v_cmp_ngt_f32_e32 vcc, s39, v182
	s_nop 1
	v_cndmask_b32_e32 v184, v178, v184, vcc
	v_sub_f32_e32 v184, 1.0, v184
	v_mul_f32_e32 v183, v180, v180
	v_fmamk_f32 v185, v183, 0xba1345e1, v176
	v_fmaak_f32 v185, v183, v185, 0xbcdac9b8
	v_fmaak_f32 v185, v183, v185, 0x3de703be
	v_fmaak_f32 v185, v183, v185, 0xbec09330
	v_fmaak_f32 v183, v183, v185, 0x3e0375d0
	v_fma_f32 v183, |v180|, v183, |v180|
	v_cmp_nlt_f32_e64 vcc, |v180|, 1.0
	s_nop 1
	v_cndmask_b32_e32 v184, v183, v184, vcc
	v_bfi_b32 v184, s10, v184, v180
	v_add_f32_e32 v184, 1.0, v184
	v_mul_f32_e32 v85, 0.5, v85
	v_mul_f32_e32 v45, v45, v49
	v_mul_f32_e32 v85, v85, v184
	v_mul_f32_e32 v85, v45, v85
	global_store_dword v193, v84, s[8:9]
	global_store_dword v193, v85, s[8:9] offset:256
	s_add_u32 s8, s8, s14
	s_addc_u32 s9, s9, 0
	v_mul_f32_e32 v86, v52, v86
	v_mul_f32_e32 v180, 0x3f3504f3, v86
	v_fma_f32 v182, |v180|, s12, v177
	v_fma_f32 v182, |v180|, v182, s15
	v_fma_f32 v182, |v180|, v182, s16
	v_fma_f32 v182, |v180|, v182, s17
	v_fma_f32 v182, |v180|, v182, s18
	v_fma_f32 v182, |v180|, v182, s19
	v_fma_f32 v182, |v180|, v182, |v180|
	v_mul_f32_e32 v184, 0xbfb8aa3b, v182
	v_fma_f32 v185, v182, s98, -v184
	v_rndne_f32_e32 v186, v184
	v_fmac_f32_e32 v185, 0xb2a5705f, v182
	v_sub_f32_e32 v184, v184, v186
	v_add_f32_e32 v184, v184, v185
	v_cvt_i32_f32_e32 v185, v186
	v_exp_f32_e32 v184, v184
	v_cmp_nlt_f32_e32 vcc, s38, v182
	v_ldexp_f32 v184, v184, v185
	s_nop 0
	v_cndmask_b32_e32 v184, 0, v184, vcc
	v_cmp_ngt_f32_e32 vcc, s39, v182
	s_nop 1
	v_cndmask_b32_e32 v184, v178, v184, vcc
	v_sub_f32_e32 v184, 1.0, v184
	v_mul_f32_e32 v183, v180, v180
	v_fmamk_f32 v185, v183, 0xba1345e1, v176
	v_fmaak_f32 v185, v183, v185, 0xbcdac9b8
	v_fmaak_f32 v185, v183, v185, 0x3de703be
	v_fmaak_f32 v185, v183, v185, 0xbec09330
	v_fmaak_f32 v183, v183, v185, 0x3e0375d0
	v_fma_f32 v183, |v180|, v183, |v180|
	v_cmp_nlt_f32_e64 vcc, |v180|, 1.0
	s_nop 1
	v_cndmask_b32_e32 v184, v183, v184, vcc
	v_bfi_b32 v184, s10, v184, v180
	v_add_f32_e32 v184, 1.0, v184
	v_mul_f32_e32 v86, 0.5, v86
	v_mul_f32_e32 v50, v50, v54
	v_mul_f32_e32 v86, v86, v184
	v_mul_f32_e32 v86, v50, v86
	v_mul_f32_e32 v87, v53, v87
	v_mul_f32_e32 v180, 0x3f3504f3, v87
	v_fma_f32 v182, |v180|, s12, v177
	v_fma_f32 v182, |v180|, v182, s15
	v_fma_f32 v182, |v180|, v182, s16
	v_fma_f32 v182, |v180|, v182, s17
	v_fma_f32 v182, |v180|, v182, s18
	v_fma_f32 v182, |v180|, v182, s19
	v_fma_f32 v182, |v180|, v182, |v180|
	v_mul_f32_e32 v184, 0xbfb8aa3b, v182
	v_fma_f32 v185, v182, s98, -v184
	v_rndne_f32_e32 v186, v184
	v_fmac_f32_e32 v185, 0xb2a5705f, v182
	v_sub_f32_e32 v184, v184, v186
	v_add_f32_e32 v184, v184, v185
	v_cvt_i32_f32_e32 v185, v186
	v_exp_f32_e32 v184, v184
	v_cmp_nlt_f32_e32 vcc, s38, v182
	v_ldexp_f32 v184, v184, v185
	s_nop 0
	v_cndmask_b32_e32 v184, 0, v184, vcc
	v_cmp_ngt_f32_e32 vcc, s39, v182
	s_nop 1
	v_cndmask_b32_e32 v184, v178, v184, vcc
	v_sub_f32_e32 v184, 1.0, v184
	v_mul_f32_e32 v183, v180, v180
	v_fmamk_f32 v185, v183, 0xba1345e1, v176
	v_fmaak_f32 v185, v183, v185, 0xbcdac9b8
	v_fmaak_f32 v185, v183, v185, 0x3de703be
	v_fmaak_f32 v185, v183, v185, 0xbec09330
	v_fmaak_f32 v183, v183, v185, 0x3e0375d0
	v_fma_f32 v183, |v180|, v183, |v180|
	v_cmp_nlt_f32_e64 vcc, |v180|, 1.0
	s_nop 1
	v_cndmask_b32_e32 v184, v183, v184, vcc
	v_bfi_b32 v184, s10, v184, v180
	v_add_f32_e32 v184, 1.0, v184
	v_mul_f32_e32 v87, 0.5, v87
	v_mul_f32_e32 v51, v51, v55
	v_mul_f32_e32 v87, v87, v184
	v_mul_f32_e32 v87, v51, v87
	global_store_dword v193, v86, s[8:9]
	global_store_dword v193, v87, s[8:9] offset:256
	s_add_u32 s8, s8, s14
	s_addc_u32 s9, s9, 0
	v_mul_f32_e32 v88, v58, v88
	v_mul_f32_e32 v180, 0x3f3504f3, v88
	v_fma_f32 v182, |v180|, s12, v177
	v_fma_f32 v182, |v180|, v182, s15
	v_fma_f32 v182, |v180|, v182, s16
	v_fma_f32 v182, |v180|, v182, s17
	v_fma_f32 v182, |v180|, v182, s18
	v_fma_f32 v182, |v180|, v182, s19
	v_fma_f32 v182, |v180|, v182, |v180|
	v_mul_f32_e32 v184, 0xbfb8aa3b, v182
	v_fma_f32 v185, v182, s98, -v184
	v_rndne_f32_e32 v186, v184
	v_fmac_f32_e32 v185, 0xb2a5705f, v182
	v_sub_f32_e32 v184, v184, v186
	v_add_f32_e32 v184, v184, v185
	v_cvt_i32_f32_e32 v185, v186
	v_exp_f32_e32 v184, v184
	v_cmp_nlt_f32_e32 vcc, s38, v182
	v_ldexp_f32 v184, v184, v185
	s_nop 0
	v_cndmask_b32_e32 v184, 0, v184, vcc
	v_cmp_ngt_f32_e32 vcc, s39, v182
	s_nop 1
	v_cndmask_b32_e32 v184, v178, v184, vcc
	v_sub_f32_e32 v184, 1.0, v184
	v_mul_f32_e32 v183, v180, v180
	v_fmamk_f32 v185, v183, 0xba1345e1, v176
	v_fmaak_f32 v185, v183, v185, 0xbcdac9b8
	v_fmaak_f32 v185, v183, v185, 0x3de703be
	v_fmaak_f32 v185, v183, v185, 0xbec09330
	v_fmaak_f32 v183, v183, v185, 0x3e0375d0
	v_fma_f32 v183, |v180|, v183, |v180|
	v_cmp_nlt_f32_e64 vcc, |v180|, 1.0
	s_nop 1
	v_cndmask_b32_e32 v184, v183, v184, vcc
	v_bfi_b32 v184, s10, v184, v180
	v_add_f32_e32 v184, 1.0, v184
	v_mul_f32_e32 v88, 0.5, v88
	v_mul_f32_e32 v56, v56, v60
	v_mul_f32_e32 v88, v88, v184
	v_mul_f32_e32 v88, v56, v88
	v_mul_f32_e32 v89, v59, v89
	v_mul_f32_e32 v180, 0x3f3504f3, v89
	v_fma_f32 v182, |v180|, s12, v177
	v_fma_f32 v182, |v180|, v182, s15
	v_fma_f32 v182, |v180|, v182, s16
	v_fma_f32 v182, |v180|, v182, s17
	v_fma_f32 v182, |v180|, v182, s18
	v_fma_f32 v182, |v180|, v182, s19
	v_fma_f32 v182, |v180|, v182, |v180|
	v_mul_f32_e32 v184, 0xbfb8aa3b, v182
	v_fma_f32 v185, v182, s98, -v184
	v_rndne_f32_e32 v186, v184
	v_fmac_f32_e32 v185, 0xb2a5705f, v182
	v_sub_f32_e32 v184, v184, v186
	v_add_f32_e32 v184, v184, v185
	v_cvt_i32_f32_e32 v185, v186
	v_exp_f32_e32 v184, v184
	v_cmp_nlt_f32_e32 vcc, s38, v182
	v_ldexp_f32 v184, v184, v185
	s_nop 0
	v_cndmask_b32_e32 v184, 0, v184, vcc
	v_cmp_ngt_f32_e32 vcc, s39, v182
	s_nop 1
	v_cndmask_b32_e32 v184, v178, v184, vcc
	v_sub_f32_e32 v184, 1.0, v184
	v_mul_f32_e32 v183, v180, v180
	v_fmamk_f32 v185, v183, 0xba1345e1, v176
	v_fmaak_f32 v185, v183, v185, 0xbcdac9b8
	v_fmaak_f32 v185, v183, v185, 0x3de703be
	v_fmaak_f32 v185, v183, v185, 0xbec09330
	v_fmaak_f32 v183, v183, v185, 0x3e0375d0
	v_fma_f32 v183, |v180|, v183, |v180|
	v_cmp_nlt_f32_e64 vcc, |v180|, 1.0
	s_nop 1
	v_cndmask_b32_e32 v184, v183, v184, vcc
	v_bfi_b32 v184, s10, v184, v180
	v_add_f32_e32 v184, 1.0, v184
	v_mul_f32_e32 v89, 0.5, v89
	v_mul_f32_e32 v57, v57, v61
	v_mul_f32_e32 v89, v89, v184
	v_mul_f32_e32 v89, v57, v89
	global_store_dword v193, v88, s[8:9]
	global_store_dword v193, v89, s[8:9] offset:256
	s_add_u32 s8, s8, s14
	s_addc_u32 s9, s9, 0
	v_mul_f32_e32 v90, v64, v90
	v_mul_f32_e32 v180, 0x3f3504f3, v90
	v_fma_f32 v182, |v180|, s12, v177
	v_fma_f32 v182, |v180|, v182, s15
	v_fma_f32 v182, |v180|, v182, s16
	v_fma_f32 v182, |v180|, v182, s17
	v_fma_f32 v182, |v180|, v182, s18
	v_fma_f32 v182, |v180|, v182, s19
	v_fma_f32 v182, |v180|, v182, |v180|
	v_mul_f32_e32 v184, 0xbfb8aa3b, v182
	v_fma_f32 v185, v182, s98, -v184
	v_rndne_f32_e32 v186, v184
	v_fmac_f32_e32 v185, 0xb2a5705f, v182
	v_sub_f32_e32 v184, v184, v186
	v_add_f32_e32 v184, v184, v185
	v_cvt_i32_f32_e32 v185, v186
	v_exp_f32_e32 v184, v184
	v_cmp_nlt_f32_e32 vcc, s38, v182
	v_ldexp_f32 v184, v184, v185
	s_nop 0
	v_cndmask_b32_e32 v184, 0, v184, vcc
	v_cmp_ngt_f32_e32 vcc, s39, v182
	s_nop 1
	v_cndmask_b32_e32 v184, v178, v184, vcc
	v_sub_f32_e32 v184, 1.0, v184
	v_mul_f32_e32 v183, v180, v180
	v_fmamk_f32 v185, v183, 0xba1345e1, v176
	v_fmaak_f32 v185, v183, v185, 0xbcdac9b8
	v_fmaak_f32 v185, v183, v185, 0x3de703be
	v_fmaak_f32 v185, v183, v185, 0xbec09330
	v_fmaak_f32 v183, v183, v185, 0x3e0375d0
	v_fma_f32 v183, |v180|, v183, |v180|
	v_cmp_nlt_f32_e64 vcc, |v180|, 1.0
	s_nop 1
	v_cndmask_b32_e32 v184, v183, v184, vcc
	v_bfi_b32 v184, s10, v184, v180
	v_add_f32_e32 v184, 1.0, v184
	v_mul_f32_e32 v90, 0.5, v90
	v_mul_f32_e32 v62, v62, v66
	v_mul_f32_e32 v90, v90, v184
	v_mul_f32_e32 v90, v62, v90
	v_mul_f32_e32 v91, v65, v91
	v_mul_f32_e32 v180, 0x3f3504f3, v91
	v_fma_f32 v182, |v180|, s12, v177
	v_fma_f32 v182, |v180|, v182, s15
	v_fma_f32 v182, |v180|, v182, s16
	v_fma_f32 v182, |v180|, v182, s17
	v_fma_f32 v182, |v180|, v182, s18
	v_fma_f32 v182, |v180|, v182, s19
	v_fma_f32 v182, |v180|, v182, |v180|
	v_mul_f32_e32 v184, 0xbfb8aa3b, v182
	v_fma_f32 v185, v182, s98, -v184
	v_rndne_f32_e32 v186, v184
	v_fmac_f32_e32 v185, 0xb2a5705f, v182
	v_sub_f32_e32 v184, v184, v186
	v_add_f32_e32 v184, v184, v185
	v_cvt_i32_f32_e32 v185, v186
	v_exp_f32_e32 v184, v184
	v_cmp_nlt_f32_e32 vcc, s38, v182
	v_ldexp_f32 v184, v184, v185
	s_nop 0
	v_cndmask_b32_e32 v184, 0, v184, vcc
	v_cmp_ngt_f32_e32 vcc, s39, v182
	s_nop 1
	v_cndmask_b32_e32 v184, v178, v184, vcc
	v_sub_f32_e32 v184, 1.0, v184
	v_mul_f32_e32 v183, v180, v180
	v_fmamk_f32 v185, v183, 0xba1345e1, v176
	v_fmaak_f32 v185, v183, v185, 0xbcdac9b8
	v_fmaak_f32 v185, v183, v185, 0x3de703be
	v_fmaak_f32 v185, v183, v185, 0xbec09330
	v_fmaak_f32 v183, v183, v185, 0x3e0375d0
	v_fma_f32 v183, |v180|, v183, |v180|
	v_cmp_nlt_f32_e64 vcc, |v180|, 1.0
	s_nop 1
	v_cndmask_b32_e32 v184, v183, v184, vcc
	v_bfi_b32 v184, s10, v184, v180
	v_add_f32_e32 v184, 1.0, v184
	v_mul_f32_e32 v91, 0.5, v91
	v_mul_f32_e32 v63, v63, v67
	v_mul_f32_e32 v91, v91, v184
	v_mul_f32_e32 v91, v63, v91
	global_store_dword v193, v90, s[8:9]
	global_store_dword v193, v91, s[8:9] offset:256
	s_add_u32 s8, s8, s14
	s_addc_u32 s9, s9, 0
	v_mul_f32_e32 v92, v70, v92
	v_mul_f32_e32 v180, 0x3f3504f3, v92
	v_fma_f32 v182, |v180|, s12, v177
	v_fma_f32 v182, |v180|, v182, s15
	v_fma_f32 v182, |v180|, v182, s16
	v_fma_f32 v182, |v180|, v182, s17
	v_fma_f32 v182, |v180|, v182, s18
	v_fma_f32 v182, |v180|, v182, s19
	v_fma_f32 v182, |v180|, v182, |v180|
	v_mul_f32_e32 v184, 0xbfb8aa3b, v182
	v_fma_f32 v185, v182, s98, -v184
	v_rndne_f32_e32 v186, v184
	v_fmac_f32_e32 v185, 0xb2a5705f, v182
	v_sub_f32_e32 v184, v184, v186
	v_add_f32_e32 v184, v184, v185
	v_cvt_i32_f32_e32 v185, v186
	v_exp_f32_e32 v184, v184
	v_cmp_nlt_f32_e32 vcc, s38, v182
	v_ldexp_f32 v184, v184, v185
	s_nop 0
	v_cndmask_b32_e32 v184, 0, v184, vcc
	v_cmp_ngt_f32_e32 vcc, s39, v182
	s_nop 1
	v_cndmask_b32_e32 v184, v178, v184, vcc
	v_sub_f32_e32 v184, 1.0, v184
	v_mul_f32_e32 v183, v180, v180
	v_fmamk_f32 v185, v183, 0xba1345e1, v176
	v_fmaak_f32 v185, v183, v185, 0xbcdac9b8
	v_fmaak_f32 v185, v183, v185, 0x3de703be
	v_fmaak_f32 v185, v183, v185, 0xbec09330
	v_fmaak_f32 v183, v183, v185, 0x3e0375d0
	v_fma_f32 v183, |v180|, v183, |v180|
	v_cmp_nlt_f32_e64 vcc, |v180|, 1.0
	s_nop 1
	v_cndmask_b32_e32 v184, v183, v184, vcc
	v_bfi_b32 v184, s10, v184, v180
	v_add_f32_e32 v184, 1.0, v184
	v_mul_f32_e32 v92, 0.5, v92
	v_mul_f32_e32 v68, v68, v72
	v_mul_f32_e32 v92, v92, v184
	v_mul_f32_e32 v92, v68, v92
	v_mul_f32_e32 v93, v71, v93
	v_mul_f32_e32 v180, 0x3f3504f3, v93
	v_fma_f32 v182, |v180|, s12, v177
	v_fma_f32 v182, |v180|, v182, s15
	v_fma_f32 v182, |v180|, v182, s16
	v_fma_f32 v182, |v180|, v182, s17
	v_fma_f32 v182, |v180|, v182, s18
	v_fma_f32 v182, |v180|, v182, s19
	v_fma_f32 v182, |v180|, v182, |v180|
	v_mul_f32_e32 v184, 0xbfb8aa3b, v182
	v_fma_f32 v185, v182, s98, -v184
	v_rndne_f32_e32 v186, v184
	v_fmac_f32_e32 v185, 0xb2a5705f, v182
	v_sub_f32_e32 v184, v184, v186
	v_add_f32_e32 v184, v184, v185
	v_cvt_i32_f32_e32 v185, v186
	v_exp_f32_e32 v184, v184
	v_cmp_nlt_f32_e32 vcc, s38, v182
	v_ldexp_f32 v184, v184, v185
	s_nop 0
	v_cndmask_b32_e32 v184, 0, v184, vcc
	v_cmp_ngt_f32_e32 vcc, s39, v182
	s_nop 1
	v_cndmask_b32_e32 v184, v178, v184, vcc
	v_sub_f32_e32 v184, 1.0, v184
	v_mul_f32_e32 v183, v180, v180
	v_fmamk_f32 v185, v183, 0xba1345e1, v176
	v_fmaak_f32 v185, v183, v185, 0xbcdac9b8
	v_fmaak_f32 v185, v183, v185, 0x3de703be
	v_fmaak_f32 v185, v183, v185, 0xbec09330
	v_fmaak_f32 v183, v183, v185, 0x3e0375d0
	v_fma_f32 v183, |v180|, v183, |v180|
	v_cmp_nlt_f32_e64 vcc, |v180|, 1.0
	s_nop 1
	v_cndmask_b32_e32 v184, v183, v184, vcc
	v_bfi_b32 v184, s10, v184, v180
	v_add_f32_e32 v184, 1.0, v184
	v_mul_f32_e32 v93, 0.5, v93
	v_mul_f32_e32 v69, v69, v73
	v_mul_f32_e32 v93, v93, v184
	v_mul_f32_e32 v93, v69, v93
	global_store_dword v193, v92, s[8:9]
	global_store_dword v193, v93, s[8:9] offset:256
	s_add_u32 s8, s8, s14
	s_addc_u32 s9, s9, 0
	v_mul_f32_e32 v94, v76, v94
	v_mul_f32_e32 v180, 0x3f3504f3, v94
	v_fma_f32 v182, |v180|, s12, v177
	v_fma_f32 v182, |v180|, v182, s15
	v_fma_f32 v182, |v180|, v182, s16
	v_fma_f32 v182, |v180|, v182, s17
	v_fma_f32 v182, |v180|, v182, s18
	v_fma_f32 v182, |v180|, v182, s19
	v_fma_f32 v182, |v180|, v182, |v180|
	v_mul_f32_e32 v184, 0xbfb8aa3b, v182
	v_fma_f32 v185, v182, s98, -v184
	v_rndne_f32_e32 v186, v184
	v_fmac_f32_e32 v185, 0xb2a5705f, v182
	v_sub_f32_e32 v184, v184, v186
	v_add_f32_e32 v184, v184, v185
	v_cvt_i32_f32_e32 v185, v186
	v_exp_f32_e32 v184, v184
	v_cmp_nlt_f32_e32 vcc, s38, v182
	v_ldexp_f32 v184, v184, v185
	s_nop 0
	v_cndmask_b32_e32 v184, 0, v184, vcc
	v_cmp_ngt_f32_e32 vcc, s39, v182
	s_nop 1
	v_cndmask_b32_e32 v184, v178, v184, vcc
	v_sub_f32_e32 v184, 1.0, v184
	v_mul_f32_e32 v183, v180, v180
	v_fmamk_f32 v185, v183, 0xba1345e1, v176
	v_fmaak_f32 v185, v183, v185, 0xbcdac9b8
	v_fmaak_f32 v185, v183, v185, 0x3de703be
	v_fmaak_f32 v185, v183, v185, 0xbec09330
	v_fmaak_f32 v183, v183, v185, 0x3e0375d0
	v_fma_f32 v183, |v180|, v183, |v180|
	v_cmp_nlt_f32_e64 vcc, |v180|, 1.0
	s_nop 1
	v_cndmask_b32_e32 v184, v183, v184, vcc
	v_bfi_b32 v184, s10, v184, v180
	v_add_f32_e32 v184, 1.0, v184
	v_mul_f32_e32 v94, 0.5, v94
	v_mul_f32_e32 v74, v74, v78
	v_mul_f32_e32 v94, v94, v184
	v_mul_f32_e32 v94, v74, v94
	v_mul_f32_e32 v95, v77, v95
	v_mul_f32_e32 v180, 0x3f3504f3, v95
	v_fma_f32 v182, |v180|, s12, v177
	v_fma_f32 v182, |v180|, v182, s15
	v_fma_f32 v182, |v180|, v182, s16
	v_fma_f32 v182, |v180|, v182, s17
	v_fma_f32 v182, |v180|, v182, s18
	v_fma_f32 v182, |v180|, v182, s19
	v_fma_f32 v182, |v180|, v182, |v180|
	v_mul_f32_e32 v184, 0xbfb8aa3b, v182
	v_fma_f32 v185, v182, s98, -v184
	v_rndne_f32_e32 v186, v184
	v_fmac_f32_e32 v185, 0xb2a5705f, v182
	v_sub_f32_e32 v184, v184, v186
	v_add_f32_e32 v184, v184, v185
	v_cvt_i32_f32_e32 v185, v186
	v_exp_f32_e32 v184, v184
	v_cmp_nlt_f32_e32 vcc, s38, v182
	v_ldexp_f32 v184, v184, v185
	s_nop 0
	v_cndmask_b32_e32 v184, 0, v184, vcc
	v_cmp_ngt_f32_e32 vcc, s39, v182
	s_nop 1
	v_cndmask_b32_e32 v184, v178, v184, vcc
	v_sub_f32_e32 v184, 1.0, v184
	v_mul_f32_e32 v183, v180, v180
	v_fmamk_f32 v185, v183, 0xba1345e1, v176
	v_fmaak_f32 v185, v183, v185, 0xbcdac9b8
	v_fmaak_f32 v185, v183, v185, 0x3de703be
	v_fmaak_f32 v185, v183, v185, 0xbec09330
	v_fmaak_f32 v183, v183, v185, 0x3e0375d0
	v_fma_f32 v183, |v180|, v183, |v180|
	v_cmp_nlt_f32_e64 vcc, |v180|, 1.0
	s_nop 1
	v_cndmask_b32_e32 v184, v183, v184, vcc
	v_bfi_b32 v184, s10, v184, v180
	v_add_f32_e32 v184, 1.0, v184
	v_mul_f32_e32 v95, 0.5, v95
	v_mul_f32_e32 v75, v75, v79
	v_mul_f32_e32 v95, v95, v184
	v_mul_f32_e32 v95, v75, v95
	global_store_dword v193, v94, s[8:9]
	global_store_dword v193, v95, s[8:9] offset:256
	s_add_u32 s8, s8, s14
	s_addc_u32 s9, s9, 0
	s_lshl_b32 s13, s92, 6
	s_add_u32 s35, s35, s13
	s_cmpk_lt_u32 s35, 0x8000
	s_cbranch_scc1 .Lgu1_chunk
	s_branch .LBB0_1045
